# MFMA order variant: SrcB held for 4 consecutive MFMAs, accumulator reuse at k turn (all 12 loops)
# baseline (speedup 1.0000x reference)
.LBB0_272:
	s_add_u32 s58, s22, 0xfff00000
	s_addc_u32 s59, s23, -1
	s_mov_b32 m0, s36
	ds_read_b128 v[154:157], v148
	global_load_lds_dwordx4 v130, s[58:59]
	s_mov_b32 m0, s37
	ds_read_b128 v[158:161], v148 offset:1024
	global_load_lds_dwordx4 v134, s[58:59]
	s_mov_b32 m0, s40
	ds_read_b128 v[164:167], v148 offset:2048
	global_load_lds_dwordx4 v142, s[22:23]
	s_mov_b32 m0, s41
	ds_read_b128 v[168:171], v148 offset:3072
	global_load_lds_dwordx4 v144, s[22:23]
	ds_read_b128 v[172:175], v149
	ds_read_b128 v[176:179], v149 offset:1024
	ds_read_b128 v[180:183], v149 offset:2048
	ds_read_b128 v[184:187], v149 offset:3072
	s_add_u32 s24, s22, 0xfff00080
	s_addc_u32 s25, s23, -1
	s_cmp_eq_u32 s56, 60
	s_cselect_b32 s27, s51, s25
	s_cselect_b32 s26, s52, s24
	s_cselect_b32 s25, s7, s55
	s_cselect_b32 s24, s53, s54
	ds_read_b128 v[188:191], v150
	ds_read_b128 v[192:195], v150 offset:1024
	ds_read_b128 v[196:199], v150 offset:2048
	ds_read_b128 v[200:203], v150 offset:3072
	ds_read_b128 v[204:207], v150 offset:4096
	ds_read_b128 v[208:211], v150 offset:5120
	ds_read_b128 v[212:215], v150 offset:6144
	ds_read_b128 v[216:219], v150 offset:7168
	s_waitcnt vmcnt(8)
	s_waitcnt lgkmcnt(0)
	s_barrier
	s_setprio 1
	s_waitcnt lgkmcnt(0)
	v_mfma_f32_16x16x32_bf16 v[126:129], v[154:157], v[188:191], v[126:129]
	v_mfma_f32_16x16x32_bf16 v[122:125], v[164:167], v[188:191], v[122:125]
	v_mfma_f32_16x16x32_bf16 v[110:113], v[172:175], v[188:191], v[110:113]
	v_mfma_f32_16x16x32_bf16 v[106:109], v[180:183], v[188:191], v[106:109]
	v_mfma_f32_16x16x32_bf16 v[106:109], v[184:187], v[192:195], v[106:109]
	v_mfma_f32_16x16x32_bf16 v[110:113], v[176:179], v[192:195], v[110:113]
	v_mfma_f32_16x16x32_bf16 v[122:125], v[168:171], v[192:195], v[122:125]
	v_mfma_f32_16x16x32_bf16 v[126:129], v[158:161], v[192:195], v[126:129]
	v_mfma_f32_16x16x32_bf16 v[118:121], v[158:161], v[200:203], v[118:121]
	v_mfma_f32_16x16x32_bf16 v[114:117], v[168:171], v[200:203], v[114:117]
	v_mfma_f32_16x16x32_bf16 v[94:97], v[176:179], v[200:203], v[94:97]
	v_mfma_f32_16x16x32_bf16 v[90:93], v[184:187], v[200:203], v[90:93]
	v_mfma_f32_16x16x32_bf16 v[90:93], v[180:183], v[196:199], v[90:93]
	v_mfma_f32_16x16x32_bf16 v[94:97], v[172:175], v[196:199], v[94:97]
	v_mfma_f32_16x16x32_bf16 v[114:117], v[164:167], v[196:199], v[114:117]
	v_mfma_f32_16x16x32_bf16 v[118:121], v[154:157], v[196:199], v[118:121]
	v_mfma_f32_16x16x32_bf16 v[102:105], v[154:157], v[204:207], v[102:105]
	v_mfma_f32_16x16x32_bf16 v[98:101], v[164:167], v[204:207], v[98:101]
	v_mfma_f32_16x16x32_bf16 v[78:81], v[172:175], v[204:207], v[78:81]
	v_mfma_f32_16x16x32_bf16 v[74:77], v[180:183], v[204:207], v[74:77]
	v_mfma_f32_16x16x32_bf16 v[74:77], v[184:187], v[208:211], v[74:77]
	v_mfma_f32_16x16x32_bf16 v[78:81], v[176:179], v[208:211], v[78:81]
	v_mfma_f32_16x16x32_bf16 v[98:101], v[168:171], v[208:211], v[98:101]
	v_mfma_f32_16x16x32_bf16 v[102:105], v[158:161], v[208:211], v[102:105]
	v_mfma_f32_16x16x32_bf16 v[86:89], v[158:161], v[216:219], v[86:89]
	v_mfma_f32_16x16x32_bf16 v[82:85], v[168:171], v[216:219], v[82:85]
	v_mfma_f32_16x16x32_bf16 v[70:73], v[176:179], v[216:219], v[70:73]
	v_mfma_f32_16x16x32_bf16 v[66:69], v[184:187], v[216:219], v[66:69]
	v_mfma_f32_16x16x32_bf16 v[66:69], v[180:183], v[212:215], v[66:69]
	v_mfma_f32_16x16x32_bf16 v[70:73], v[172:175], v[212:215], v[70:73]
	v_mfma_f32_16x16x32_bf16 v[82:85], v[164:167], v[212:215], v[82:85]
	v_mfma_f32_16x16x32_bf16 v[86:89], v[154:157], v[212:215], v[86:89]
	s_setprio 0
	s_barrier
	s_mov_b32 m0, s42
	s_add_u32 s58, s24, 0x100000
	global_load_lds_dwordx4 v132, s[24:25]
	s_mov_b32 m0, s43
	s_addc_u32 s59, s25, 0
	global_load_lds_dwordx4 v136, s[24:25]
	s_mov_b32 m0, s44
	ds_read_b128 v[188:191], v150 offset:16384
	global_load_lds_dwordx4 v132, s[58:59]
	s_mov_b32 m0, s45
	ds_read_b128 v[192:195], v150 offset:17408
	global_load_lds_dwordx4 v136, s[58:59]
	ds_read_b128 v[196:199], v150 offset:18432
	ds_read_b128 v[200:203], v150 offset:19456
	ds_read_b128 v[204:207], v150 offset:20480
	ds_read_b128 v[208:211], v150 offset:21504
	ds_read_b128 v[212:215], v150 offset:22528
	ds_read_b128 v[216:219], v150 offset:23552
	s_waitcnt vmcnt(6)
	s_waitcnt lgkmcnt(0)
	s_barrier
	s_setprio 1
	s_waitcnt lgkmcnt(0)
	v_mfma_f32_16x16x32_bf16 v[62:65], v[154:157], v[188:191], v[62:65]
	v_mfma_f32_16x16x32_bf16 v[58:61], v[164:167], v[188:191], v[58:61]
	v_mfma_f32_16x16x32_bf16 v[46:49], v[172:175], v[188:191], v[46:49]
	v_mfma_f32_16x16x32_bf16 v[42:45], v[180:183], v[188:191], v[42:45]
	v_mfma_f32_16x16x32_bf16 v[42:45], v[184:187], v[192:195], v[42:45]
	v_mfma_f32_16x16x32_bf16 v[46:49], v[176:179], v[192:195], v[46:49]
	v_mfma_f32_16x16x32_bf16 v[58:61], v[168:171], v[192:195], v[58:61]
	v_mfma_f32_16x16x32_bf16 v[62:65], v[158:161], v[192:195], v[62:65]
	v_mfma_f32_16x16x32_bf16 v[54:57], v[158:161], v[200:203], v[54:57]
	v_mfma_f32_16x16x32_bf16 v[50:53], v[168:171], v[200:203], v[50:53]
	v_mfma_f32_16x16x32_bf16 v[30:33], v[176:179], v[200:203], v[30:33]
	v_mfma_f32_16x16x32_bf16 v[26:29], v[184:187], v[200:203], v[26:29]
	v_mfma_f32_16x16x32_bf16 v[26:29], v[180:183], v[196:199], v[26:29]
	v_mfma_f32_16x16x32_bf16 v[30:33], v[172:175], v[196:199], v[30:33]
	v_mfma_f32_16x16x32_bf16 v[50:53], v[164:167], v[196:199], v[50:53]
	v_mfma_f32_16x16x32_bf16 v[54:57], v[154:157], v[196:199], v[54:57]
	v_mfma_f32_16x16x32_bf16 v[38:41], v[154:157], v[204:207], v[38:41]
	v_mfma_f32_16x16x32_bf16 v[34:37], v[164:167], v[204:207], v[34:37]
	v_mfma_f32_16x16x32_bf16 v[14:17], v[172:175], v[204:207], v[14:17]
	v_mfma_f32_16x16x32_bf16 v[10:13], v[180:183], v[204:207], v[10:13]
	v_mfma_f32_16x16x32_bf16 v[10:13], v[184:187], v[208:211], v[10:13]
	v_mfma_f32_16x16x32_bf16 v[14:17], v[176:179], v[208:211], v[14:17]
	v_mfma_f32_16x16x32_bf16 v[34:37], v[168:171], v[208:211], v[34:37]
	v_mfma_f32_16x16x32_bf16 v[38:41], v[158:161], v[208:211], v[38:41]
	v_mfma_f32_16x16x32_bf16 v[22:25], v[158:161], v[216:219], v[22:25]
	v_mfma_f32_16x16x32_bf16 v[18:21], v[168:171], v[216:219], v[18:21]
	v_mfma_f32_16x16x32_bf16 v[6:9], v[176:179], v[216:219], v[6:9]
	v_mfma_f32_16x16x32_bf16 v[2:5], v[184:187], v[216:219], v[2:5]
	v_mfma_f32_16x16x32_bf16 v[2:5], v[180:183], v[212:215], v[2:5]
	v_mfma_f32_16x16x32_bf16 v[6:9], v[172:175], v[212:215], v[6:9]
	v_mfma_f32_16x16x32_bf16 v[18:21], v[164:167], v[212:215], v[18:21]
	v_mfma_f32_16x16x32_bf16 v[22:25], v[154:157], v[212:215], v[22:25]
	s_setprio 0
	s_barrier
	s_mov_b32 m0, s30
	ds_read_b128 v[154:157], v151
	global_load_lds_dwordx4 v130, s[26:27]
	s_mov_b32 m0, s31
	ds_read_b128 v[158:161], v151 offset:1024
	global_load_lds_dwordx4 v134, s[26:27]
	s_add_u32 s26, s26, 0x100000
	s_addc_u32 s27, s27, 0
	s_mov_b32 m0, s33
	ds_read_b128 v[164:167], v151 offset:2048
	global_load_lds_dwordx4 v130, s[26:27]
	s_mov_b32 m0, s34
	ds_read_b128 v[168:171], v151 offset:3072
	global_load_lds_dwordx4 v134, s[26:27]
	ds_read_b128 v[172:175], v152
	ds_read_b128 v[176:179], v152 offset:1024
	ds_read_b128 v[180:183], v152 offset:2048
	ds_read_b128 v[184:187], v152 offset:3072
	ds_read_b128 v[188:191], v150 offset:32768
	ds_read_b128 v[192:195], v150 offset:33792
	ds_read_b128 v[196:199], v150 offset:34816
	ds_read_b128 v[200:203], v150 offset:35840
	ds_read_b128 v[204:207], v150 offset:36864
	ds_read_b128 v[208:211], v150 offset:37888
	ds_read_b128 v[212:215], v150 offset:38912
	ds_read_b128 v[216:219], v150 offset:39936
	s_waitcnt vmcnt(8)
	s_waitcnt lgkmcnt(0)
	s_barrier
	s_setprio 1
	s_waitcnt lgkmcnt(0)
	v_mfma_f32_16x16x32_bf16 v[126:129], v[154:157], v[188:191], v[126:129]
	v_mfma_f32_16x16x32_bf16 v[122:125], v[164:167], v[188:191], v[122:125]
	v_mfma_f32_16x16x32_bf16 v[110:113], v[172:175], v[188:191], v[110:113]
	v_mfma_f32_16x16x32_bf16 v[106:109], v[180:183], v[188:191], v[106:109]
	v_mfma_f32_16x16x32_bf16 v[106:109], v[184:187], v[192:195], v[106:109]
	v_mfma_f32_16x16x32_bf16 v[110:113], v[176:179], v[192:195], v[110:113]
	v_mfma_f32_16x16x32_bf16 v[122:125], v[168:171], v[192:195], v[122:125]
	v_mfma_f32_16x16x32_bf16 v[126:129], v[158:161], v[192:195], v[126:129]
	v_mfma_f32_16x16x32_bf16 v[118:121], v[158:161], v[200:203], v[118:121]
	v_mfma_f32_16x16x32_bf16 v[114:117], v[168:171], v[200:203], v[114:117]
	v_mfma_f32_16x16x32_bf16 v[94:97], v[176:179], v[200:203], v[94:97]
	v_mfma_f32_16x16x32_bf16 v[90:93], v[184:187], v[200:203], v[90:93]
	v_mfma_f32_16x16x32_bf16 v[90:93], v[180:183], v[196:199], v[90:93]
	v_mfma_f32_16x16x32_bf16 v[94:97], v[172:175], v[196:199], v[94:97]
	v_mfma_f32_16x16x32_bf16 v[114:117], v[164:167], v[196:199], v[114:117]
	v_mfma_f32_16x16x32_bf16 v[118:121], v[154:157], v[196:199], v[118:121]
	v_mfma_f32_16x16x32_bf16 v[102:105], v[154:157], v[204:207], v[102:105]
	v_mfma_f32_16x16x32_bf16 v[98:101], v[164:167], v[204:207], v[98:101]
	v_mfma_f32_16x16x32_bf16 v[78:81], v[172:175], v[204:207], v[78:81]
	v_mfma_f32_16x16x32_bf16 v[74:77], v[180:183], v[204:207], v[74:77]
	v_mfma_f32_16x16x32_bf16 v[74:77], v[184:187], v[208:211], v[74:77]
	v_mfma_f32_16x16x32_bf16 v[78:81], v[176:179], v[208:211], v[78:81]
	v_mfma_f32_16x16x32_bf16 v[98:101], v[168:171], v[208:211], v[98:101]
	v_mfma_f32_16x16x32_bf16 v[102:105], v[158:161], v[208:211], v[102:105]
	v_mfma_f32_16x16x32_bf16 v[86:89], v[158:161], v[216:219], v[86:89]
	v_mfma_f32_16x16x32_bf16 v[82:85], v[168:171], v[216:219], v[82:85]
	v_mfma_f32_16x16x32_bf16 v[70:73], v[176:179], v[216:219], v[70:73]
	v_mfma_f32_16x16x32_bf16 v[66:69], v[184:187], v[216:219], v[66:69]
	v_mfma_f32_16x16x32_bf16 v[66:69], v[180:183], v[212:215], v[66:69]
	v_mfma_f32_16x16x32_bf16 v[70:73], v[172:175], v[212:215], v[70:73]
	v_mfma_f32_16x16x32_bf16 v[82:85], v[164:167], v[212:215], v[82:85]
	v_mfma_f32_16x16x32_bf16 v[86:89], v[154:157], v[212:215], v[86:89]
	s_setprio 0
	s_barrier
	s_mov_b32 m0, s47
	s_add_u32 s24, s24, 0x80
	s_addc_u32 s25, s25, 0
	global_load_lds_dwordx4 v132, s[24:25]
	s_mov_b32 m0, s48
	ds_read_b128 v[188:191], v150 offset:49152
	global_load_lds_dwordx4 v136, s[24:25]
	s_add_i32 s26, s46, s29
	s_mov_b32 m0, s26
	s_add_u32 s24, s24, 0x100000
	s_addc_u32 s25, s25, 0
	global_load_lds_dwordx4 v132, s[24:25]
	s_add_i32 m0, s26, 0x2000
	ds_read_b128 v[192:195], v150 offset:50176
	global_load_lds_dwordx4 v136, s[24:25]
	ds_read_b128 v[196:199], v150 offset:51200
	ds_read_b128 v[200:203], v150 offset:52224
	ds_read_b128 v[204:207], v150 offset:53248
	ds_read_b128 v[208:211], v150 offset:54272
	ds_read_b128 v[212:215], v150 offset:55296
	ds_read_b128 v[216:219], v150 offset:56320
	s_waitcnt vmcnt(6)
	s_waitcnt lgkmcnt(0)
	s_barrier
	s_setprio 1
	s_waitcnt lgkmcnt(0)
	v_mfma_f32_16x16x32_bf16 v[62:65], v[154:157], v[188:191], v[62:65]
	v_mfma_f32_16x16x32_bf16 v[58:61], v[164:167], v[188:191], v[58:61]
	v_mfma_f32_16x16x32_bf16 v[46:49], v[172:175], v[188:191], v[46:49]
	v_mfma_f32_16x16x32_bf16 v[42:45], v[180:183], v[188:191], v[42:45]
	v_mfma_f32_16x16x32_bf16 v[42:45], v[184:187], v[192:195], v[42:45]
	v_mfma_f32_16x16x32_bf16 v[46:49], v[176:179], v[192:195], v[46:49]
	v_mfma_f32_16x16x32_bf16 v[58:61], v[168:171], v[192:195], v[58:61]
	v_mfma_f32_16x16x32_bf16 v[62:65], v[158:161], v[192:195], v[62:65]
	v_mfma_f32_16x16x32_bf16 v[54:57], v[158:161], v[200:203], v[54:57]
	v_mfma_f32_16x16x32_bf16 v[50:53], v[168:171], v[200:203], v[50:53]
	v_mfma_f32_16x16x32_bf16 v[30:33], v[176:179], v[200:203], v[30:33]
	v_mfma_f32_16x16x32_bf16 v[26:29], v[184:187], v[200:203], v[26:29]
	v_mfma_f32_16x16x32_bf16 v[26:29], v[180:183], v[196:199], v[26:29]
	v_mfma_f32_16x16x32_bf16 v[30:33], v[172:175], v[196:199], v[30:33]
	v_mfma_f32_16x16x32_bf16 v[50:53], v[164:167], v[196:199], v[50:53]
	v_mfma_f32_16x16x32_bf16 v[54:57], v[154:157], v[196:199], v[54:57]
	v_mfma_f32_16x16x32_bf16 v[38:41], v[154:157], v[204:207], v[38:41]
	v_mfma_f32_16x16x32_bf16 v[34:37], v[164:167], v[204:207], v[34:37]
	v_mfma_f32_16x16x32_bf16 v[14:17], v[172:175], v[204:207], v[14:17]
	v_mfma_f32_16x16x32_bf16 v[10:13], v[180:183], v[204:207], v[10:13]
	v_mfma_f32_16x16x32_bf16 v[10:13], v[184:187], v[208:211], v[10:13]
	v_mfma_f32_16x16x32_bf16 v[14:17], v[176:179], v[208:211], v[14:17]
	v_mfma_f32_16x16x32_bf16 v[34:37], v[168:171], v[208:211], v[34:37]
	v_mfma_f32_16x16x32_bf16 v[38:41], v[158:161], v[208:211], v[38:41]
	v_mfma_f32_16x16x32_bf16 v[22:25], v[158:161], v[216:219], v[22:25]
	v_mfma_f32_16x16x32_bf16 v[18:21], v[168:171], v[216:219], v[18:21]
	v_mfma_f32_16x16x32_bf16 v[6:9], v[176:179], v[216:219], v[6:9]
	v_mfma_f32_16x16x32_bf16 v[2:5], v[184:187], v[216:219], v[2:5]
	v_mfma_f32_16x16x32_bf16 v[2:5], v[180:183], v[212:215], v[2:5]
	v_mfma_f32_16x16x32_bf16 v[6:9], v[172:175], v[212:215], v[6:9]
	v_mfma_f32_16x16x32_bf16 v[18:21], v[164:167], v[212:215], v[18:21]
	v_mfma_f32_16x16x32_bf16 v[22:25], v[154:157], v[212:215], v[22:25]
	s_setprio 0
	s_barrier
	s_add_i32 s56, s56, 2
	s_add_u32 s22, s22, 0x100
	s_addc_u32 s23, s23, 0
	s_add_u32 s54, s54, 0x100
	s_addc_u32 s55, s55, 0
	s_cmp_gt_u32 s56, 61
	s_cbranch_scc0 .LBB0_272
	s_and_b64 vcc, exec, s[16:17]
	s_cbranch_vccz .LBB0_277
	s_barrier
	v_lshl_add_u32 v138, s50, 8, v1
	s_cmp_gt_i32 s49, 63
	s_mov_b64 s[22:23], -1
	s_cbranch_scc1 .LBB0_278

.LBB0_1009:
	ds_read_b128 v[142:145], v155
	ds_read_b128 v[158:161], v155 offset:1024
	ds_read_b128 v[168:171], v155 offset:2048
	ds_read_b128 v[176:179], v155 offset:3072
	ds_read_b128 v[180:183], v156
	ds_read_b128 v[184:187], v156 offset:1024
	ds_read_b128 v[188:191], v156 offset:2048
	ds_read_b128 v[192:195], v156 offset:3072
	s_add_u32 s24, s22, 0xfff00080
	s_addc_u32 s25, s23, -1
	s_cmp_eq_u32 s51, 60
	s_cselect_b32 s27, s19, s25
	s_cselect_b32 s26, s47, s24
	s_cselect_b32 s25, s7, s50
	s_cselect_b32 s24, s48, s49
	s_mov_b32 m0, s40
	v_lshl_add_u64 v[146:147], s[22:23], 0, v[138:139]
	ds_read_b128 v[202:205], v157
	ds_read_b128 v[206:209], v157 offset:1024
	ds_read_b128 v[210:213], v157 offset:2048
	ds_read_b128 v[214:217], v157 offset:3072
	ds_read_b128 v[218:221], v157 offset:4096
	ds_read_b128 v[222:225], v157 offset:5120
	ds_read_b128 v[226:229], v157 offset:6144
	ds_read_b128 v[230:233], v157 offset:7168
	global_load_lds_dwordx4 v[146:147], off
	v_lshl_add_u64 v[146:147], s[22:23], 0, v[140:141]
	s_mov_b32 m0, s41
	s_nop 0
	global_load_lds_dwordx4 v[146:147], off
	s_waitcnt vmcnt(8)
	s_waitcnt lgkmcnt(0)
	s_barrier
	s_setprio 1
	s_waitcnt lgkmcnt(0)
	v_mfma_f32_16x16x32_bf16 v[126:129], v[142:145], v[202:205], v[126:129]
	v_mfma_f32_16x16x32_bf16 v[122:125], v[168:171], v[202:205], v[122:125]
	v_mfma_f32_16x16x32_bf16 v[118:121], v[180:183], v[202:205], v[118:121]
	v_mfma_f32_16x16x32_bf16 v[114:117], v[188:191], v[202:205], v[114:117]
	v_mfma_f32_16x16x32_bf16 v[114:117], v[192:195], v[206:209], v[114:117]
	v_mfma_f32_16x16x32_bf16 v[118:121], v[184:187], v[206:209], v[118:121]
	v_mfma_f32_16x16x32_bf16 v[122:125], v[176:179], v[206:209], v[122:125]
	v_mfma_f32_16x16x32_bf16 v[126:129], v[158:161], v[206:209], v[126:129]
	v_mfma_f32_16x16x32_bf16 v[110:113], v[158:161], v[214:217], v[110:113]
	v_mfma_f32_16x16x32_bf16 v[106:109], v[176:179], v[214:217], v[106:109]
	v_mfma_f32_16x16x32_bf16 v[102:105], v[184:187], v[214:217], v[102:105]
	v_mfma_f32_16x16x32_bf16 v[98:101], v[192:195], v[214:217], v[98:101]
	v_mfma_f32_16x16x32_bf16 v[98:101], v[188:191], v[210:213], v[98:101]
	v_mfma_f32_16x16x32_bf16 v[102:105], v[180:183], v[210:213], v[102:105]
	v_mfma_f32_16x16x32_bf16 v[106:109], v[168:171], v[210:213], v[106:109]
	v_mfma_f32_16x16x32_bf16 v[110:113], v[142:145], v[210:213], v[110:113]
	v_mfma_f32_16x16x32_bf16 v[94:97], v[142:145], v[218:221], v[94:97]
	v_mfma_f32_16x16x32_bf16 v[90:93], v[168:171], v[218:221], v[90:93]
	v_mfma_f32_16x16x32_bf16 v[86:89], v[180:183], v[218:221], v[86:89]
	v_mfma_f32_16x16x32_bf16 v[82:85], v[188:191], v[218:221], v[82:85]
	v_mfma_f32_16x16x32_bf16 v[82:85], v[192:195], v[222:225], v[82:85]
	v_mfma_f32_16x16x32_bf16 v[86:89], v[184:187], v[222:225], v[86:89]
	v_mfma_f32_16x16x32_bf16 v[90:93], v[176:179], v[222:225], v[90:93]
	v_mfma_f32_16x16x32_bf16 v[94:97], v[158:161], v[222:225], v[94:97]
	v_mfma_f32_16x16x32_bf16 v[78:81], v[158:161], v[230:233], v[78:81]
	v_mfma_f32_16x16x32_bf16 v[74:77], v[176:179], v[230:233], v[74:77]
	v_mfma_f32_16x16x32_bf16 v[70:73], v[184:187], v[230:233], v[70:73]
	v_mfma_f32_16x16x32_bf16 v[66:69], v[192:195], v[230:233], v[66:69]
	v_mfma_f32_16x16x32_bf16 v[66:69], v[188:191], v[226:229], v[66:69]
	v_mfma_f32_16x16x32_bf16 v[70:73], v[180:183], v[226:229], v[70:73]
	v_mfma_f32_16x16x32_bf16 v[74:77], v[168:171], v[226:229], v[74:77]
	v_mfma_f32_16x16x32_bf16 v[78:81], v[142:145], v[226:229], v[78:81]
	s_setprio 0
	s_barrier
	s_mov_b32 m0, s42
	v_lshl_add_u64 v[146:147], s[24:25], 0, v[132:133]
	s_add_u32 s52, s24, 0x100000
	ds_read_b128 v[202:205], v157 offset:16384
	ds_read_b128 v[206:209], v157 offset:17408
	ds_read_b128 v[210:213], v157 offset:18432
	ds_read_b128 v[214:217], v157 offset:19456
	ds_read_b128 v[218:221], v157 offset:20480
	ds_read_b128 v[222:225], v157 offset:21504
	ds_read_b128 v[226:229], v157 offset:22528
	ds_read_b128 v[230:233], v157 offset:23552
	global_load_lds_dwordx4 v[146:147], off
	v_lshl_add_u64 v[172:173], s[24:25], 0, v[136:137]
	s_mov_b32 m0, s43
	s_addc_u32 s53, s25, 0
	global_load_lds_dwordx4 v[172:173], off
	v_lshl_add_u64 v[196:197], s[52:53], 0, v[132:133]
	s_mov_b32 m0, s44
	v_lshl_add_u64 v[234:235], s[26:27], 0, v[134:135]
	global_load_lds_dwordx4 v[196:197], off
	v_lshl_add_u64 v[196:197], s[52:53], 0, v[136:137]
	s_add_i32 m0, s44, 0x2000
	s_nop 0
	global_load_lds_dwordx4 v[196:197], off
	v_lshl_add_u64 v[196:197], s[26:27], 0, v[130:131]
	s_mov_b32 m0, s33
	s_nop 0
	global_load_lds_dwordx4 v[196:197], off
	s_mov_b32 m0, s34
	s_nop 0
	global_load_lds_dwordx4 v[234:235], off
	s_waitcnt vmcnt(8)
	s_waitcnt lgkmcnt(0)
	s_barrier
	s_setprio 1
	s_waitcnt lgkmcnt(0)
	v_mfma_f32_16x16x32_bf16 v[62:65], v[142:145], v[202:205], v[62:65]
	v_mfma_f32_16x16x32_bf16 v[58:61], v[168:171], v[202:205], v[58:61]
	v_mfma_f32_16x16x32_bf16 v[54:57], v[180:183], v[202:205], v[54:57]
	v_mfma_f32_16x16x32_bf16 v[50:53], v[188:191], v[202:205], v[50:53]
	v_mfma_f32_16x16x32_bf16 v[50:53], v[192:195], v[206:209], v[50:53]
	v_mfma_f32_16x16x32_bf16 v[54:57], v[184:187], v[206:209], v[54:57]
	v_mfma_f32_16x16x32_bf16 v[58:61], v[176:179], v[206:209], v[58:61]
	v_mfma_f32_16x16x32_bf16 v[62:65], v[158:161], v[206:209], v[62:65]
	v_mfma_f32_16x16x32_bf16 v[46:49], v[158:161], v[214:217], v[46:49]
	v_mfma_f32_16x16x32_bf16 v[42:45], v[176:179], v[214:217], v[42:45]
	v_mfma_f32_16x16x32_bf16 v[38:41], v[184:187], v[214:217], v[38:41]
	v_mfma_f32_16x16x32_bf16 v[34:37], v[192:195], v[214:217], v[34:37]
	v_mfma_f32_16x16x32_bf16 v[34:37], v[188:191], v[210:213], v[34:37]
	v_mfma_f32_16x16x32_bf16 v[38:41], v[180:183], v[210:213], v[38:41]
	v_mfma_f32_16x16x32_bf16 v[42:45], v[168:171], v[210:213], v[42:45]
	v_mfma_f32_16x16x32_bf16 v[46:49], v[142:145], v[210:213], v[46:49]
	v_mfma_f32_16x16x32_bf16 v[30:33], v[142:145], v[218:221], v[30:33]
	v_mfma_f32_16x16x32_bf16 v[26:29], v[168:171], v[218:221], v[26:29]
	v_mfma_f32_16x16x32_bf16 v[22:25], v[180:183], v[218:221], v[22:25]
	v_mfma_f32_16x16x32_bf16 v[18:21], v[188:191], v[218:221], v[18:21]
	v_mfma_f32_16x16x32_bf16 v[18:21], v[192:195], v[222:225], v[18:21]
	v_mfma_f32_16x16x32_bf16 v[22:25], v[184:187], v[222:225], v[22:25]
	v_mfma_f32_16x16x32_bf16 v[26:29], v[176:179], v[222:225], v[26:29]
	v_mfma_f32_16x16x32_bf16 v[30:33], v[158:161], v[222:225], v[30:33]
	v_mfma_f32_16x16x32_bf16 v[14:17], v[158:161], v[230:233], v[14:17]
	v_mfma_f32_16x16x32_bf16 v[10:13], v[176:179], v[230:233], v[10:13]
	v_mfma_f32_16x16x32_bf16 v[6:9], v[184:187], v[230:233], v[6:9]
	v_mfma_f32_16x16x32_bf16 v[2:5], v[192:195], v[230:233], v[2:5]
	v_mfma_f32_16x16x32_bf16 v[2:5], v[188:191], v[226:229], v[2:5]
	v_mfma_f32_16x16x32_bf16 v[6:9], v[180:183], v[226:229], v[6:9]
	v_mfma_f32_16x16x32_bf16 v[10:13], v[168:171], v[226:229], v[10:13]
	v_mfma_f32_16x16x32_bf16 v[14:17], v[142:145], v[226:229], v[14:17]
	s_setprio 0
	s_barrier
	s_add_i32 s52, 0, 0x18000
	v_add_u32_e32 v166, s52, v153
	s_add_i32 s53, 0, 0x1c000
	ds_read_b128 v[142:145], v166
	ds_read_b128 v[158:161], v166 offset:1024
	ds_read_b128 v[168:171], v166 offset:2048
	ds_read_b128 v[176:179], v166 offset:3072
	v_add_u32_e32 v166, s53, v153
	ds_read_b128 v[180:183], v166
	ds_read_b128 v[184:187], v166 offset:1024
	ds_read_b128 v[188:191], v166 offset:2048
	ds_read_b128 v[192:195], v166 offset:3072
	s_add_u32 s26, s26, 0x100000
	s_addc_u32 s27, s27, 0
	s_mov_b32 m0, s35
	v_lshl_add_u64 v[236:237], s[26:27], 0, v[130:131]
	ds_read_b128 v[202:205], v157 offset:32768
	ds_read_b128 v[206:209], v157 offset:33792
	ds_read_b128 v[210:213], v157 offset:34816
	ds_read_b128 v[214:217], v157 offset:35840
	ds_read_b128 v[218:221], v157 offset:36864
	ds_read_b128 v[222:225], v157 offset:37888
	ds_read_b128 v[226:229], v157 offset:38912
	ds_read_b128 v[230:233], v157 offset:39936
	global_load_lds_dwordx4 v[236:237], off
	v_lshl_add_u64 v[236:237], s[26:27], 0, v[134:135]
	s_mov_b32 m0, s36
	s_nop 0
	global_load_lds_dwordx4 v[236:237], off
	s_waitcnt vmcnt(8)
	s_waitcnt lgkmcnt(0)
	s_barrier
	s_setprio 1
	s_waitcnt lgkmcnt(0)
	v_mfma_f32_16x16x32_bf16 v[126:129], v[142:145], v[202:205], v[126:129]
	v_mfma_f32_16x16x32_bf16 v[122:125], v[168:171], v[202:205], v[122:125]
	v_mfma_f32_16x16x32_bf16 v[118:121], v[180:183], v[202:205], v[118:121]
	v_mfma_f32_16x16x32_bf16 v[114:117], v[188:191], v[202:205], v[114:117]
	v_mfma_f32_16x16x32_bf16 v[114:117], v[192:195], v[206:209], v[114:117]
	v_mfma_f32_16x16x32_bf16 v[118:121], v[184:187], v[206:209], v[118:121]
	v_mfma_f32_16x16x32_bf16 v[122:125], v[176:179], v[206:209], v[122:125]
	v_mfma_f32_16x16x32_bf16 v[126:129], v[158:161], v[206:209], v[126:129]
	v_mfma_f32_16x16x32_bf16 v[110:113], v[158:161], v[214:217], v[110:113]
	v_mfma_f32_16x16x32_bf16 v[106:109], v[176:179], v[214:217], v[106:109]
	v_mfma_f32_16x16x32_bf16 v[102:105], v[184:187], v[214:217], v[102:105]
	v_mfma_f32_16x16x32_bf16 v[98:101], v[192:195], v[214:217], v[98:101]
	v_mfma_f32_16x16x32_bf16 v[98:101], v[188:191], v[210:213], v[98:101]
	v_mfma_f32_16x16x32_bf16 v[102:105], v[180:183], v[210:213], v[102:105]
	v_mfma_f32_16x16x32_bf16 v[106:109], v[168:171], v[210:213], v[106:109]
	v_mfma_f32_16x16x32_bf16 v[110:113], v[142:145], v[210:213], v[110:113]
	v_mfma_f32_16x16x32_bf16 v[94:97], v[142:145], v[218:221], v[94:97]
	v_mfma_f32_16x16x32_bf16 v[90:93], v[168:171], v[218:221], v[90:93]
	v_mfma_f32_16x16x32_bf16 v[86:89], v[180:183], v[218:221], v[86:89]
	v_mfma_f32_16x16x32_bf16 v[82:85], v[188:191], v[218:221], v[82:85]
	v_mfma_f32_16x16x32_bf16 v[82:85], v[192:195], v[222:225], v[82:85]
	v_mfma_f32_16x16x32_bf16 v[86:89], v[184:187], v[222:225], v[86:89]
	v_mfma_f32_16x16x32_bf16 v[90:93], v[176:179], v[222:225], v[90:93]
	v_mfma_f32_16x16x32_bf16 v[94:97], v[158:161], v[222:225], v[94:97]
	v_mfma_f32_16x16x32_bf16 v[78:81], v[158:161], v[230:233], v[78:81]
	v_mfma_f32_16x16x32_bf16 v[74:77], v[176:179], v[230:233], v[74:77]
	v_mfma_f32_16x16x32_bf16 v[70:73], v[184:187], v[230:233], v[70:73]
	v_mfma_f32_16x16x32_bf16 v[66:69], v[192:195], v[230:233], v[66:69]
	v_mfma_f32_16x16x32_bf16 v[66:69], v[188:191], v[226:229], v[66:69]
	v_mfma_f32_16x16x32_bf16 v[70:73], v[180:183], v[226:229], v[70:73]
	v_mfma_f32_16x16x32_bf16 v[74:77], v[168:171], v[226:229], v[74:77]
	v_mfma_f32_16x16x32_bf16 v[78:81], v[142:145], v[226:229], v[78:81]
	s_setprio 0
	s_barrier
	s_add_i32 s26, s52, s30
	v_lshl_add_u64 v[146:147], v[146:147], 0, s[14:15]
	s_mov_b32 m0, s26
	ds_read_b128 v[202:205], v157 offset:49152
	ds_read_b128 v[206:209], v157 offset:50176
	ds_read_b128 v[210:213], v157 offset:51200
	ds_read_b128 v[214:217], v157 offset:52224
	ds_read_b128 v[218:221], v157 offset:53248
	ds_read_b128 v[222:225], v157 offset:54272
	ds_read_b128 v[226:229], v157 offset:55296
	ds_read_b128 v[230:233], v157 offset:56320
	global_load_lds_dwordx4 v[146:147], off
	s_add_i32 m0, s26, 0x2000
	s_add_u32 s24, s24, 0x100080
	v_lshl_add_u64 v[146:147], v[172:173], 0, s[14:15]
	s_addc_u32 s25, s25, 0
	s_add_i32 s26, s53, s30
	global_load_lds_dwordx4 v[146:147], off
	v_lshl_add_u64 v[146:147], s[24:25], 0, v[132:133]
	s_mov_b32 m0, s26
	s_nop 0
	global_load_lds_dwordx4 v[146:147], off
	v_lshl_add_u64 v[146:147], s[24:25], 0, v[136:137]
	s_add_i32 m0, s26, 0x2000
	s_nop 0
	global_load_lds_dwordx4 v[146:147], off
	v_lshl_add_u64 v[146:147], v[196:197], 0, s[14:15]
	s_mov_b32 m0, s38
	s_nop 0
	global_load_lds_dwordx4 v[146:147], off
	v_lshl_add_u64 v[146:147], v[234:235], 0, s[14:15]
	s_mov_b32 m0, s39
	s_nop 0
	global_load_lds_dwordx4 v[146:147], off
	s_waitcnt vmcnt(8)
	s_waitcnt lgkmcnt(0)
	s_barrier
	s_setprio 1
	s_waitcnt lgkmcnt(0)
	v_mfma_f32_16x16x32_bf16 v[62:65], v[142:145], v[202:205], v[62:65]
	v_mfma_f32_16x16x32_bf16 v[58:61], v[168:171], v[202:205], v[58:61]
	v_mfma_f32_16x16x32_bf16 v[54:57], v[180:183], v[202:205], v[54:57]
	v_mfma_f32_16x16x32_bf16 v[50:53], v[188:191], v[202:205], v[50:53]
	v_mfma_f32_16x16x32_bf16 v[50:53], v[192:195], v[206:209], v[50:53]
	v_mfma_f32_16x16x32_bf16 v[54:57], v[184:187], v[206:209], v[54:57]
	v_mfma_f32_16x16x32_bf16 v[58:61], v[176:179], v[206:209], v[58:61]
	v_mfma_f32_16x16x32_bf16 v[62:65], v[158:161], v[206:209], v[62:65]
	v_mfma_f32_16x16x32_bf16 v[46:49], v[158:161], v[214:217], v[46:49]
	v_mfma_f32_16x16x32_bf16 v[42:45], v[176:179], v[214:217], v[42:45]
	v_mfma_f32_16x16x32_bf16 v[38:41], v[184:187], v[214:217], v[38:41]
	v_mfma_f32_16x16x32_bf16 v[34:37], v[192:195], v[214:217], v[34:37]
	v_mfma_f32_16x16x32_bf16 v[34:37], v[188:191], v[210:213], v[34:37]
	v_mfma_f32_16x16x32_bf16 v[38:41], v[180:183], v[210:213], v[38:41]
	v_mfma_f32_16x16x32_bf16 v[42:45], v[168:171], v[210:213], v[42:45]
	v_mfma_f32_16x16x32_bf16 v[46:49], v[142:145], v[210:213], v[46:49]
	v_mfma_f32_16x16x32_bf16 v[30:33], v[142:145], v[218:221], v[30:33]
	v_mfma_f32_16x16x32_bf16 v[26:29], v[168:171], v[218:221], v[26:29]
	v_mfma_f32_16x16x32_bf16 v[22:25], v[180:183], v[218:221], v[22:25]
	v_mfma_f32_16x16x32_bf16 v[18:21], v[188:191], v[218:221], v[18:21]
	v_mfma_f32_16x16x32_bf16 v[18:21], v[192:195], v[222:225], v[18:21]
	v_mfma_f32_16x16x32_bf16 v[22:25], v[184:187], v[222:225], v[22:25]
	v_mfma_f32_16x16x32_bf16 v[26:29], v[176:179], v[222:225], v[26:29]
	v_mfma_f32_16x16x32_bf16 v[30:33], v[158:161], v[222:225], v[30:33]
	v_mfma_f32_16x16x32_bf16 v[14:17], v[158:161], v[230:233], v[14:17]
	v_mfma_f32_16x16x32_bf16 v[10:13], v[176:179], v[230:233], v[10:13]
	v_mfma_f32_16x16x32_bf16 v[6:9], v[184:187], v[230:233], v[6:9]
	v_mfma_f32_16x16x32_bf16 v[2:5], v[192:195], v[230:233], v[2:5]
	v_mfma_f32_16x16x32_bf16 v[2:5], v[188:191], v[226:229], v[2:5]
	v_mfma_f32_16x16x32_bf16 v[6:9], v[180:183], v[226:229], v[6:9]
	v_mfma_f32_16x16x32_bf16 v[10:13], v[168:171], v[226:229], v[10:13]
	v_mfma_f32_16x16x32_bf16 v[14:17], v[142:145], v[226:229], v[14:17]
	s_setprio 0
	s_barrier
	s_add_i32 s51, s51, 2
	s_add_u32 s22, s22, 0x100
	s_addc_u32 s23, s23, 0
	s_add_u32 s49, s49, 0x100
	s_addc_u32 s50, s50, 0
	s_cmp_gt_u32 s51, 61
	s_cbranch_scc0 .LBB0_1009
	s_and_b64 vcc, exec, s[16:17]
	s_cbranch_vccz .LBB0_1012
	s_barrier

.LBB0_1019:
	s_add_i32 s21, s20, 0x100
	s_and_b64 s[18:19], s[18:19], exec
	s_cselect_b32 s19, 0, s21
	s_cselect_b32 s18, 0, 0
	s_add_u32 s22, s8, s19
	s_addc_u32 s23, s9, s18
	ds_read_b128 v[144:147], v139
	ds_read_b128 v[150:153], v139 offset:1024
	ds_read_b128 v[154:157], v139 offset:2048
	ds_read_b128 v[158:161], v139 offset:3072
	ds_read_b128 v[168:171], v140
	ds_read_b128 v[176:179], v140 offset:1024
	ds_read_b128 v[180:183], v140 offset:2048
	ds_read_b128 v[184:187], v140 offset:3072
	s_add_u32 s24, s10, s19
	s_addc_u32 s25, s11, s18
	s_add_u32 s30, s12, s20
	s_addc_u32 s31, s13, 0
	s_add_u32 s26, s24, 0x100000
	s_addc_u32 s27, s25, 0
	s_add_u32 s20, s22, 0x100000
	s_addc_u32 s21, s23, 0
	s_add_u32 s18, s24, 0x100080
	s_addc_u32 s19, s25, 0
	v_lshl_add_u64 v[172:173], s[30:31], 0, v[130:131]
	s_mov_b32 m0, s40
	v_lshl_add_u64 v[172:173], v[172:173], 0, s[14:15]
	ds_read_b128 v[188:191], v141
	ds_read_b128 v[192:195], v141 offset:1024
	ds_read_b128 v[202:205], v141 offset:2048
	ds_read_b128 v[206:209], v141 offset:3072
	ds_read_b128 v[210:213], v141 offset:4096
	ds_read_b128 v[214:217], v141 offset:5120
	ds_read_b128 v[218:221], v141 offset:6144
	ds_read_b128 v[222:225], v141 offset:7168
	global_load_lds_dwordx4 v[172:173], off
	v_lshl_add_u64 v[172:173], s[30:31], 0, v[134:135]
	v_lshl_add_u64 v[172:173], v[172:173], 0, s[14:15]
	s_mov_b32 m0, s41
	s_nop 0
	global_load_lds_dwordx4 v[172:173], off
	s_waitcnt vmcnt(8)
	s_waitcnt lgkmcnt(0)
	s_barrier
	s_setprio 1
	s_waitcnt lgkmcnt(0)
	v_mfma_f32_16x16x32_bf16 v[126:129], v[144:147], v[188:191], v[126:129]
	v_mfma_f32_16x16x32_bf16 v[122:125], v[154:157], v[188:191], v[122:125]
	v_mfma_f32_16x16x32_bf16 v[110:113], v[168:171], v[188:191], v[110:113]
	v_mfma_f32_16x16x32_bf16 v[106:109], v[180:183], v[188:191], v[106:109]
	v_mfma_f32_16x16x32_bf16 v[106:109], v[184:187], v[192:195], v[106:109]
	v_mfma_f32_16x16x32_bf16 v[110:113], v[176:179], v[192:195], v[110:113]
	v_mfma_f32_16x16x32_bf16 v[122:125], v[158:161], v[192:195], v[122:125]
	v_mfma_f32_16x16x32_bf16 v[126:129], v[150:153], v[192:195], v[126:129]
	v_mfma_f32_16x16x32_bf16 v[118:121], v[150:153], v[206:209], v[118:121]
	v_mfma_f32_16x16x32_bf16 v[114:117], v[158:161], v[206:209], v[114:117]
	v_mfma_f32_16x16x32_bf16 v[94:97], v[176:179], v[206:209], v[94:97]
	v_mfma_f32_16x16x32_bf16 v[90:93], v[184:187], v[206:209], v[90:93]
	v_mfma_f32_16x16x32_bf16 v[90:93], v[180:183], v[202:205], v[90:93]
	v_mfma_f32_16x16x32_bf16 v[94:97], v[168:171], v[202:205], v[94:97]
	v_mfma_f32_16x16x32_bf16 v[114:117], v[154:157], v[202:205], v[114:117]
	v_mfma_f32_16x16x32_bf16 v[118:121], v[144:147], v[202:205], v[118:121]
	v_mfma_f32_16x16x32_bf16 v[102:105], v[144:147], v[210:213], v[102:105]
	v_mfma_f32_16x16x32_bf16 v[98:101], v[154:157], v[210:213], v[98:101]
	v_mfma_f32_16x16x32_bf16 v[78:81], v[168:171], v[210:213], v[78:81]
	v_mfma_f32_16x16x32_bf16 v[74:77], v[180:183], v[210:213], v[74:77]
	v_mfma_f32_16x16x32_bf16 v[74:77], v[184:187], v[214:217], v[74:77]
	v_mfma_f32_16x16x32_bf16 v[78:81], v[176:179], v[214:217], v[78:81]
	v_mfma_f32_16x16x32_bf16 v[98:101], v[158:161], v[214:217], v[98:101]
	v_mfma_f32_16x16x32_bf16 v[102:105], v[150:153], v[214:217], v[102:105]
	v_mfma_f32_16x16x32_bf16 v[86:89], v[150:153], v[222:225], v[86:89]
	v_mfma_f32_16x16x32_bf16 v[82:85], v[158:161], v[222:225], v[82:85]
	v_mfma_f32_16x16x32_bf16 v[70:73], v[176:179], v[222:225], v[70:73]
	v_mfma_f32_16x16x32_bf16 v[66:69], v[184:187], v[222:225], v[66:69]
	v_mfma_f32_16x16x32_bf16 v[66:69], v[180:183], v[218:221], v[66:69]
	v_mfma_f32_16x16x32_bf16 v[70:73], v[168:171], v[218:221], v[70:73]
	v_mfma_f32_16x16x32_bf16 v[82:85], v[154:157], v[218:221], v[82:85]
	v_mfma_f32_16x16x32_bf16 v[86:89], v[144:147], v[218:221], v[86:89]
	s_setprio 0
	s_barrier
	s_mov_b32 m0, s42
	v_lshl_add_u64 v[172:173], s[24:25], 0, v[132:133]
	ds_read_b128 v[188:191], v141 offset:16384
	ds_read_b128 v[192:195], v141 offset:17408
	ds_read_b128 v[202:205], v141 offset:18432
	ds_read_b128 v[206:209], v141 offset:19456
	ds_read_b128 v[210:213], v141 offset:20480
	ds_read_b128 v[214:217], v141 offset:21504
	ds_read_b128 v[218:221], v141 offset:22528
	ds_read_b128 v[222:225], v141 offset:23552
	global_load_lds_dwordx4 v[172:173], off
	v_lshl_add_u64 v[196:197], s[24:25], 0, v[136:137]
	s_mov_b32 m0, s43
	v_lshl_add_u64 v[226:227], s[26:27], 0, v[132:133]
	global_load_lds_dwordx4 v[196:197], off
	s_mov_b32 m0, s44
	v_lshl_add_u64 v[228:229], s[22:23], 0, v[134:135]
	global_load_lds_dwordx4 v[226:227], off
	v_lshl_add_u64 v[226:227], s[26:27], 0, v[136:137]
	s_mov_b32 m0, s45
	s_nop 0
	global_load_lds_dwordx4 v[226:227], off
	v_lshl_add_u64 v[226:227], s[22:23], 0, v[130:131]
	s_mov_b32 m0, s7
	s_nop 0
	global_load_lds_dwordx4 v[226:227], off
	s_mov_b32 m0, s34
	s_nop 0
	global_load_lds_dwordx4 v[228:229], off
	s_waitcnt vmcnt(8)
	s_waitcnt lgkmcnt(0)
	s_barrier
	s_setprio 1
	s_waitcnt lgkmcnt(0)
	v_mfma_f32_16x16x32_bf16 v[62:65], v[144:147], v[188:191], v[62:65]
	v_mfma_f32_16x16x32_bf16 v[58:61], v[154:157], v[188:191], v[58:61]
	v_mfma_f32_16x16x32_bf16 v[46:49], v[168:171], v[188:191], v[46:49]
	v_mfma_f32_16x16x32_bf16 v[42:45], v[180:183], v[188:191], v[42:45]
	v_mfma_f32_16x16x32_bf16 v[42:45], v[184:187], v[192:195], v[42:45]
	v_mfma_f32_16x16x32_bf16 v[46:49], v[176:179], v[192:195], v[46:49]
	v_mfma_f32_16x16x32_bf16 v[58:61], v[158:161], v[192:195], v[58:61]
	v_mfma_f32_16x16x32_bf16 v[62:65], v[150:153], v[192:195], v[62:65]
	v_mfma_f32_16x16x32_bf16 v[54:57], v[150:153], v[206:209], v[54:57]
	v_mfma_f32_16x16x32_bf16 v[50:53], v[158:161], v[206:209], v[50:53]
	v_mfma_f32_16x16x32_bf16 v[30:33], v[176:179], v[206:209], v[30:33]
	v_mfma_f32_16x16x32_bf16 v[26:29], v[184:187], v[206:209], v[26:29]
	v_mfma_f32_16x16x32_bf16 v[26:29], v[180:183], v[202:205], v[26:29]
	v_mfma_f32_16x16x32_bf16 v[30:33], v[168:171], v[202:205], v[30:33]
	v_mfma_f32_16x16x32_bf16 v[50:53], v[154:157], v[202:205], v[50:53]
	v_mfma_f32_16x16x32_bf16 v[54:57], v[144:147], v[202:205], v[54:57]
	v_mfma_f32_16x16x32_bf16 v[38:41], v[144:147], v[210:213], v[38:41]
	v_mfma_f32_16x16x32_bf16 v[34:37], v[154:157], v[210:213], v[34:37]
	v_mfma_f32_16x16x32_bf16 v[14:17], v[168:171], v[210:213], v[14:17]
	v_mfma_f32_16x16x32_bf16 v[10:13], v[180:183], v[210:213], v[10:13]
	v_mfma_f32_16x16x32_bf16 v[10:13], v[184:187], v[214:217], v[10:13]
	v_mfma_f32_16x16x32_bf16 v[14:17], v[176:179], v[214:217], v[14:17]
	v_mfma_f32_16x16x32_bf16 v[34:37], v[158:161], v[214:217], v[34:37]
	v_mfma_f32_16x16x32_bf16 v[38:41], v[150:153], v[214:217], v[38:41]
	v_mfma_f32_16x16x32_bf16 v[22:25], v[150:153], v[222:225], v[22:25]
	v_mfma_f32_16x16x32_bf16 v[18:21], v[158:161], v[222:225], v[18:21]
	v_mfma_f32_16x16x32_bf16 v[6:9], v[176:179], v[222:225], v[6:9]
	v_mfma_f32_16x16x32_bf16 v[2:5], v[184:187], v[222:225], v[2:5]
	v_mfma_f32_16x16x32_bf16 v[2:5], v[180:183], v[218:221], v[2:5]
	v_mfma_f32_16x16x32_bf16 v[6:9], v[168:171], v[218:221], v[6:9]
	v_mfma_f32_16x16x32_bf16 v[18:21], v[154:157], v[218:221], v[18:21]
	v_mfma_f32_16x16x32_bf16 v[22:25], v[144:147], v[218:221], v[22:25]
	s_setprio 0
	s_barrier
	ds_read_b128 v[144:147], v142
	ds_read_b128 v[150:153], v142 offset:1024
	ds_read_b128 v[154:157], v142 offset:2048
	ds_read_b128 v[158:161], v142 offset:3072
	ds_read_b128 v[168:171], v143
	ds_read_b128 v[176:179], v143 offset:1024
	ds_read_b128 v[180:183], v143 offset:2048
	ds_read_b128 v[184:187], v143 offset:3072
	s_mov_b32 m0, s35
	v_lshl_add_u64 v[230:231], s[20:21], 0, v[130:131]
	ds_read_b128 v[188:191], v141 offset:32768
	ds_read_b128 v[192:195], v141 offset:33792
	ds_read_b128 v[202:205], v141 offset:34816
	ds_read_b128 v[206:209], v141 offset:35840
	ds_read_b128 v[210:213], v141 offset:36864
	ds_read_b128 v[214:217], v141 offset:37888
	ds_read_b128 v[218:221], v141 offset:38912
	ds_read_b128 v[222:225], v141 offset:39936
	global_load_lds_dwordx4 v[230:231], off
	v_lshl_add_u64 v[230:231], s[20:21], 0, v[134:135]
	s_mov_b32 m0, s36
	s_nop 0
	global_load_lds_dwordx4 v[230:231], off
	s_waitcnt vmcnt(8)
	s_waitcnt lgkmcnt(0)
	s_barrier
	s_setprio 1
	s_waitcnt lgkmcnt(0)
	v_mfma_f32_16x16x32_bf16 v[126:129], v[144:147], v[188:191], v[126:129]
	v_mfma_f32_16x16x32_bf16 v[122:125], v[154:157], v[188:191], v[122:125]
	v_mfma_f32_16x16x32_bf16 v[110:113], v[168:171], v[188:191], v[110:113]
	v_mfma_f32_16x16x32_bf16 v[106:109], v[180:183], v[188:191], v[106:109]
	v_mfma_f32_16x16x32_bf16 v[106:109], v[184:187], v[192:195], v[106:109]
	v_mfma_f32_16x16x32_bf16 v[110:113], v[176:179], v[192:195], v[110:113]
	v_mfma_f32_16x16x32_bf16 v[122:125], v[158:161], v[192:195], v[122:125]
	v_mfma_f32_16x16x32_bf16 v[126:129], v[150:153], v[192:195], v[126:129]
	v_mfma_f32_16x16x32_bf16 v[118:121], v[150:153], v[206:209], v[118:121]
	v_mfma_f32_16x16x32_bf16 v[114:117], v[158:161], v[206:209], v[114:117]
	v_mfma_f32_16x16x32_bf16 v[94:97], v[176:179], v[206:209], v[94:97]
	v_mfma_f32_16x16x32_bf16 v[90:93], v[184:187], v[206:209], v[90:93]
	v_mfma_f32_16x16x32_bf16 v[90:93], v[180:183], v[202:205], v[90:93]
	v_mfma_f32_16x16x32_bf16 v[94:97], v[168:171], v[202:205], v[94:97]
	v_mfma_f32_16x16x32_bf16 v[114:117], v[154:157], v[202:205], v[114:117]
	v_mfma_f32_16x16x32_bf16 v[118:121], v[144:147], v[202:205], v[118:121]
	v_mfma_f32_16x16x32_bf16 v[102:105], v[144:147], v[210:213], v[102:105]
	v_mfma_f32_16x16x32_bf16 v[98:101], v[154:157], v[210:213], v[98:101]
	v_mfma_f32_16x16x32_bf16 v[78:81], v[168:171], v[210:213], v[78:81]
	v_mfma_f32_16x16x32_bf16 v[74:77], v[180:183], v[210:213], v[74:77]
	v_mfma_f32_16x16x32_bf16 v[74:77], v[184:187], v[214:217], v[74:77]
	v_mfma_f32_16x16x32_bf16 v[78:81], v[176:179], v[214:217], v[78:81]
	v_mfma_f32_16x16x32_bf16 v[98:101], v[158:161], v[214:217], v[98:101]
	v_mfma_f32_16x16x32_bf16 v[102:105], v[150:153], v[214:217], v[102:105]
	v_mfma_f32_16x16x32_bf16 v[86:89], v[150:153], v[222:225], v[86:89]
	v_mfma_f32_16x16x32_bf16 v[82:85], v[158:161], v[222:225], v[82:85]
	v_mfma_f32_16x16x32_bf16 v[70:73], v[176:179], v[222:225], v[70:73]
	v_mfma_f32_16x16x32_bf16 v[66:69], v[184:187], v[222:225], v[66:69]
	v_mfma_f32_16x16x32_bf16 v[66:69], v[180:183], v[218:221], v[66:69]
	v_mfma_f32_16x16x32_bf16 v[70:73], v[168:171], v[218:221], v[70:73]
	v_mfma_f32_16x16x32_bf16 v[82:85], v[154:157], v[218:221], v[82:85]
	v_mfma_f32_16x16x32_bf16 v[86:89], v[144:147], v[218:221], v[86:89]
	s_setprio 0
	s_barrier
	s_mov_b32 m0, s46
	v_lshl_add_u64 v[172:173], v[172:173], 0, s[14:15]
	ds_read_b128 v[188:191], v141 offset:49152
	ds_read_b128 v[192:195], v141 offset:50176
	ds_read_b128 v[202:205], v141 offset:51200
	ds_read_b128 v[206:209], v141 offset:52224
	ds_read_b128 v[210:213], v141 offset:53248
	ds_read_b128 v[214:217], v141 offset:54272
	ds_read_b128 v[218:221], v141 offset:55296
	ds_read_b128 v[222:225], v141 offset:56320
	global_load_lds_dwordx4 v[172:173], off
	v_lshl_add_u64 v[172:173], v[196:197], 0, s[14:15]
	s_mov_b32 m0, s47
	s_nop 0
	global_load_lds_dwordx4 v[172:173], off
	v_lshl_add_u64 v[172:173], s[18:19], 0, v[132:133]
	s_mov_b32 m0, s48
	s_nop 0
	global_load_lds_dwordx4 v[172:173], off
	v_lshl_add_u64 v[172:173], s[18:19], 0, v[136:137]
	s_mov_b32 m0, s49
	s_nop 0
	global_load_lds_dwordx4 v[172:173], off
	v_lshl_add_u64 v[172:173], v[226:227], 0, s[14:15]
	s_mov_b32 m0, s38
	s_nop 0
	global_load_lds_dwordx4 v[172:173], off
	v_lshl_add_u64 v[172:173], v[228:229], 0, s[14:15]
	s_mov_b32 m0, s39
	s_nop 0
	global_load_lds_dwordx4 v[172:173], off
	s_waitcnt vmcnt(8)
	s_waitcnt lgkmcnt(0)
	s_barrier
	s_setprio 1
	s_waitcnt lgkmcnt(0)
	v_mfma_f32_16x16x32_bf16 v[62:65], v[144:147], v[188:191], v[62:65]
	v_mfma_f32_16x16x32_bf16 v[58:61], v[154:157], v[188:191], v[58:61]
	v_mfma_f32_16x16x32_bf16 v[46:49], v[168:171], v[188:191], v[46:49]
	v_mfma_f32_16x16x32_bf16 v[42:45], v[180:183], v[188:191], v[42:45]
	v_mfma_f32_16x16x32_bf16 v[42:45], v[184:187], v[192:195], v[42:45]
	v_mfma_f32_16x16x32_bf16 v[46:49], v[176:179], v[192:195], v[46:49]
	v_mfma_f32_16x16x32_bf16 v[58:61], v[158:161], v[192:195], v[58:61]
	v_mfma_f32_16x16x32_bf16 v[62:65], v[150:153], v[192:195], v[62:65]
	v_mfma_f32_16x16x32_bf16 v[54:57], v[150:153], v[206:209], v[54:57]
	v_mfma_f32_16x16x32_bf16 v[50:53], v[158:161], v[206:209], v[50:53]
	v_mfma_f32_16x16x32_bf16 v[30:33], v[176:179], v[206:209], v[30:33]
	v_mfma_f32_16x16x32_bf16 v[26:29], v[184:187], v[206:209], v[26:29]
	v_mfma_f32_16x16x32_bf16 v[26:29], v[180:183], v[202:205], v[26:29]
	v_mfma_f32_16x16x32_bf16 v[30:33], v[168:171], v[202:205], v[30:33]
	v_mfma_f32_16x16x32_bf16 v[50:53], v[154:157], v[202:205], v[50:53]
	v_mfma_f32_16x16x32_bf16 v[54:57], v[144:147], v[202:205], v[54:57]
	v_mfma_f32_16x16x32_bf16 v[38:41], v[144:147], v[210:213], v[38:41]
	v_mfma_f32_16x16x32_bf16 v[34:37], v[154:157], v[210:213], v[34:37]
	v_mfma_f32_16x16x32_bf16 v[14:17], v[168:171], v[210:213], v[14:17]
	v_mfma_f32_16x16x32_bf16 v[10:13], v[180:183], v[210:213], v[10:13]
	v_mfma_f32_16x16x32_bf16 v[10:13], v[184:187], v[214:217], v[10:13]
	v_mfma_f32_16x16x32_bf16 v[14:17], v[176:179], v[214:217], v[14:17]
	v_mfma_f32_16x16x32_bf16 v[34:37], v[158:161], v[214:217], v[34:37]
	v_mfma_f32_16x16x32_bf16 v[38:41], v[150:153], v[214:217], v[38:41]
	v_mfma_f32_16x16x32_bf16 v[22:25], v[150:153], v[222:225], v[22:25]
	v_mfma_f32_16x16x32_bf16 v[18:21], v[158:161], v[222:225], v[18:21]
	v_mfma_f32_16x16x32_bf16 v[6:9], v[176:179], v[222:225], v[6:9]
	v_mfma_f32_16x16x32_bf16 v[2:5], v[184:187], v[222:225], v[2:5]
	v_mfma_f32_16x16x32_bf16 v[2:5], v[180:183], v[218:221], v[2:5]
	v_mfma_f32_16x16x32_bf16 v[6:9], v[168:171], v[218:221], v[6:9]
	v_mfma_f32_16x16x32_bf16 v[18:21], v[154:157], v[218:221], v[18:21]
	v_mfma_f32_16x16x32_bf16 v[22:25], v[144:147], v[218:221], v[22:25]
	s_setprio 0
	s_barrier
	s_andn2_b64 vcc, exec, s[16:17]
	s_mov_b64 s[18:19], -1
	s_mov_b64 s[16:17], 0
	s_movk_i32 s20, 0x100
	s_cbranch_vccz .LBB0_1019
	s_lshl_b32 s7, s33, 21
	v_readlane_b32 s0, v249, 29
	v_lshl_or_b32 v130, s6, 8, v148
	v_mov_b32_e32 v139, 0
	s_add_u32 s8, s0, s7
	v_readlane_b32 s0, v249, 31
	v_or_b32_e32 v130, s37, v130
	v_cvt_pk_bf16_f32 v70, v70, v71
	v_cvt_pk_bf16_f32 v71, v72, v73
	v_cvt_pk_bf16_f32 v72, v66, v67
	v_add_u32_e32 v66, 0x80, v138
	v_mov_b32_e32 v67, v139
	s_addc_u32 s9, s0, 0
	v_ashrrev_i32_e32 v131, 31, v130
	v_lshlrev_b64 v[132:133], 13, v[138:139]
	v_cvt_pk_bf16_f32 v110, v110, v111
	v_cvt_pk_bf16_f32 v111, v112, v113
	v_cvt_pk_bf16_f32 v112, v106, v107
	v_or_b32_e32 v106, 16, v138
	v_mov_b32_e32 v107, v139
	v_lshlrev_b64 v[66:67], 13, v[66:67]
	v_cvt_pk_bf16_f32 v46, v46, v47
	v_cvt_pk_bf16_f32 v47, v48, v49
	v_cvt_pk_bf16_f32 v48, v42, v43
	v_add_u32_e32 v42, 0x90, v138
	v_mov_b32_e32 v43, v139
	v_lshl_add_u64 v[132:133], s[8:9], 0, v[132:133]
	v_lshlrev_b64 v[130:131], 1, v[130:131]
	v_lshlrev_b64 v[106:107], 13, v[106:107]
	v_cvt_pk_bf16_f32 v94, v94, v95
	v_cvt_pk_bf16_f32 v95, v96, v97
	v_cvt_pk_bf16_f32 v96, v90, v91
	v_or_b32_e32 v90, 32, v138
	v_mov_b32_e32 v91, v139
	v_lshl_add_u64 v[66:67], s[8:9], 0, v[66:67]
	v_lshlrev_b64 v[42:43], 13, v[42:43]
	v_cvt_pk_bf16_f32 v30, v30, v31
	v_cvt_pk_bf16_f32 v31, v32, v33
	v_cvt_pk_bf16_f32 v32, v26, v27
	v_add_u32_e32 v26, 0xa0, v138
	v_mov_b32_e32 v27, v139
	v_lshl_add_u64 v[132:133], v[132:133], 0, v[130:131]
	v_cvt_pk_bf16_f32 v113, v108, v109
	v_lshl_add_u64 v[106:107], s[8:9], 0, v[106:107]
	v_lshlrev_b64 v[90:91], 13, v[90:91]
	v_cvt_pk_bf16_f32 v78, v78, v79
	v_cvt_pk_bf16_f32 v79, v80, v81
	v_cvt_pk_bf16_f32 v80, v74, v75
	v_or_b32_e32 v74, 48, v138
	v_mov_b32_e32 v75, v139
	v_lshl_add_u64 v[66:67], v[66:67], 0, v[130:131]
	v_cvt_pk_bf16_f32 v49, v44, v45
	v_lshl_add_u64 v[42:43], s[8:9], 0, v[42:43]
	v_lshlrev_b64 v[26:27], 13, v[26:27]
	v_add_u32_e32 v138, 0xb0, v138
	global_store_dwordx4 v[132:133], v[110:113], off offset:256
	v_cvt_pk_bf16_f32 v97, v92, v93
	v_lshl_add_u64 v[90:91], s[8:9], 0, v[90:91]
	v_lshl_add_u64 v[110:111], v[106:107], 0, v[130:131]
	v_lshlrev_b64 v[74:75], 13, v[74:75]
	global_store_dwordx4 v[66:67], v[46:49], off offset:256
	v_cvt_pk_bf16_f32 v33, v28, v29
	v_lshl_add_u64 v[26:27], s[8:9], 0, v[26:27]
	v_lshl_add_u64 v[46:47], v[42:43], 0, v[130:131]
	v_cvt_pk_bf16_f32 v14, v14, v15
	v_cvt_pk_bf16_f32 v15, v16, v17
	v_cvt_pk_bf16_f32 v16, v10, v11
	v_lshlrev_b64 v[10:11], 13, v[138:139]
	global_store_dwordx4 v[110:111], v[94:97], off offset:256
	v_cvt_pk_bf16_f32 v81, v76, v77
	v_lshl_add_u64 v[74:75], s[8:9], 0, v[74:75]
	v_lshl_add_u64 v[94:95], v[90:91], 0, v[130:131]
	global_store_dwordx4 v[46:47], v[30:33], off offset:256
	v_cvt_pk_bf16_f32 v17, v12, v13
	v_lshl_add_u64 v[10:11], s[8:9], 0, v[10:11]
	v_lshl_add_u64 v[30:31], v[26:27], 0, v[130:131]
	v_cvt_pk_bf16_f32 v126, v126, v127
	v_cvt_pk_bf16_f32 v127, v128, v129
	v_cvt_pk_bf16_f32 v128, v122, v123
	v_cvt_pk_bf16_f32 v129, v124, v125
	v_cvt_pk_bf16_f32 v106, v118, v119
	v_cvt_pk_bf16_f32 v107, v120, v121
	v_cvt_pk_bf16_f32 v108, v114, v115
	v_cvt_pk_bf16_f32 v109, v116, v117
	v_cvt_pk_bf16_f32 v90, v102, v103
	v_cvt_pk_bf16_f32 v91, v104, v105
	v_cvt_pk_bf16_f32 v92, v98, v99
	v_cvt_pk_bf16_f32 v93, v100, v101
	global_store_dwordx4 v[94:95], v[78:81], off offset:256
	v_cvt_pk_bf16_f32 v76, v82, v83
	v_cvt_pk_bf16_f32 v77, v84, v85
	v_lshl_add_u64 v[78:79], v[74:75], 0, v[130:131]
	v_cvt_pk_bf16_f32 v74, v86, v87
	v_cvt_pk_bf16_f32 v75, v88, v89
	v_cvt_pk_bf16_f32 v73, v68, v69
	v_cvt_pk_bf16_f32 v62, v62, v63
	v_cvt_pk_bf16_f32 v63, v64, v65
	v_cvt_pk_bf16_f32 v64, v58, v59
	v_cvt_pk_bf16_f32 v65, v60, v61
	v_cvt_pk_bf16_f32 v42, v54, v55
	v_cvt_pk_bf16_f32 v43, v56, v57
	v_cvt_pk_bf16_f32 v44, v50, v51
	v_cvt_pk_bf16_f32 v45, v52, v53
	v_cvt_pk_bf16_f32 v26, v38, v39
	v_cvt_pk_bf16_f32 v27, v40, v41
	v_cvt_pk_bf16_f32 v28, v34, v35
	v_cvt_pk_bf16_f32 v29, v36, v37
	global_store_dwordx4 v[30:31], v[14:17], off offset:256
	v_cvt_pk_bf16_f32 v12, v18, v19
	v_cvt_pk_bf16_f32 v13, v20, v21
	v_lshl_add_u64 v[14:15], v[10:11], 0, v[130:131]
	v_cvt_pk_bf16_f32 v10, v22, v23
	v_cvt_pk_bf16_f32 v11, v24, v25
	v_cvt_pk_bf16_f32 v6, v6, v7
	v_cvt_pk_bf16_f32 v7, v8, v9
	v_cvt_pk_bf16_f32 v8, v2, v3
	v_cvt_pk_bf16_f32 v9, v4, v5
	global_store_dwordx4 v[132:133], v[126:129], off
	global_store_dwordx4 v[110:111], v[106:109], off
	global_store_dwordx4 v[94:95], v[90:93], off
	global_store_dwordx4 v[78:79], v[74:77], off
	global_store_dwordx4 v[78:79], v[70:73], off offset:256
	global_store_dwordx4 v[66:67], v[62:65], off
	global_store_dwordx4 v[46:47], v[42:45], off
	global_store_dwordx4 v[30:31], v[26:29], off
	global_store_dwordx4 v[14:15], v[10:13], off
	global_store_dwordx4 v[14:15], v[6:9], off offset:256
	s_waitcnt vmcnt(0)
	s_cmpk_lt_u32 s3, 0x100
	s_cbranch_scc0 .LBB0_1022
	s_barrier

.LBB0_1172:
	s_add_u32 s62, s20, 0xfff00000
	s_addc_u32 s63, s21, -1
	s_mov_b32 m0, s37
	ds_read_b128 v[142:145], v148
	global_load_lds_dwordx4 v130, s[62:63]
	s_mov_b32 m0, s38
	ds_read_b128 v[154:157], v148 offset:1024
	global_load_lds_dwordx4 v134, s[62:63]
	s_mov_b32 m0, s42
	ds_read_b128 v[158:161], v148 offset:2048
	global_load_lds_dwordx4 v138, s[20:21]
	s_mov_b32 m0, s43
	ds_read_b128 v[168:171], v148 offset:3072
	global_load_lds_dwordx4 v140, s[20:21]
	ds_read_b128 v[176:179], v149
	ds_read_b128 v[180:183], v149 offset:1024
	ds_read_b128 v[184:187], v149 offset:2048
	ds_read_b128 v[188:191], v149 offset:3072
	s_add_u32 s22, s20, 0xfff00080
	s_addc_u32 s23, s21, -1
	s_cmp_eq_u32 s61, 60
	s_cselect_b32 s25, s54, s23
	s_cselect_b32 s24, s55, s22
	s_cselect_b32 s23, s7, s60
	s_cselect_b32 s22, s56, s57
	ds_read_b128 v[192:195], v150
	ds_read_b128 v[202:205], v150 offset:1024
	ds_read_b128 v[206:209], v150 offset:2048
	ds_read_b128 v[210:213], v150 offset:3072
	ds_read_b128 v[214:217], v150 offset:4096
	ds_read_b128 v[218:221], v150 offset:5120
	ds_read_b128 v[222:225], v150 offset:6144
	ds_read_b128 v[226:229], v150 offset:7168
	s_waitcnt vmcnt(8)
	s_waitcnt lgkmcnt(0)
	s_barrier
	s_setprio 1
	s_waitcnt lgkmcnt(0)
	v_mfma_f32_16x16x32_bf16 v[126:129], v[142:145], v[192:195], v[126:129]
	v_mfma_f32_16x16x32_bf16 v[118:121], v[158:161], v[192:195], v[118:121]
	v_mfma_f32_16x16x32_bf16 v[122:125], v[176:179], v[192:195], v[122:125]
	v_mfma_f32_16x16x32_bf16 v[114:117], v[184:187], v[192:195], v[114:117]
	v_mfma_f32_16x16x32_bf16 v[114:117], v[188:191], v[202:205], v[114:117]
	v_mfma_f32_16x16x32_bf16 v[122:125], v[180:183], v[202:205], v[122:125]
	v_mfma_f32_16x16x32_bf16 v[118:121], v[168:171], v[202:205], v[118:121]
	v_mfma_f32_16x16x32_bf16 v[126:129], v[154:157], v[202:205], v[126:129]
	v_mfma_f32_16x16x32_bf16 v[110:113], v[154:157], v[210:213], v[110:113]
	v_mfma_f32_16x16x32_bf16 v[102:105], v[168:171], v[210:213], v[102:105]
	v_mfma_f32_16x16x32_bf16 v[106:109], v[180:183], v[210:213], v[106:109]
	v_mfma_f32_16x16x32_bf16 v[98:101], v[188:191], v[210:213], v[98:101]
	v_mfma_f32_16x16x32_bf16 v[98:101], v[184:187], v[206:209], v[98:101]
	v_mfma_f32_16x16x32_bf16 v[106:109], v[176:179], v[206:209], v[106:109]
	v_mfma_f32_16x16x32_bf16 v[102:105], v[158:161], v[206:209], v[102:105]
	v_mfma_f32_16x16x32_bf16 v[110:113], v[142:145], v[206:209], v[110:113]
	v_mfma_f32_16x16x32_bf16 v[94:97], v[142:145], v[214:217], v[94:97]
	v_mfma_f32_16x16x32_bf16 v[86:89], v[158:161], v[214:217], v[86:89]
	v_mfma_f32_16x16x32_bf16 v[90:93], v[176:179], v[214:217], v[90:93]
	v_mfma_f32_16x16x32_bf16 v[82:85], v[184:187], v[214:217], v[82:85]
	v_mfma_f32_16x16x32_bf16 v[82:85], v[188:191], v[218:221], v[82:85]
	v_mfma_f32_16x16x32_bf16 v[90:93], v[180:183], v[218:221], v[90:93]
	v_mfma_f32_16x16x32_bf16 v[86:89], v[168:171], v[218:221], v[86:89]
	v_mfma_f32_16x16x32_bf16 v[94:97], v[154:157], v[218:221], v[94:97]
	v_mfma_f32_16x16x32_bf16 v[78:81], v[154:157], v[226:229], v[78:81]
	v_mfma_f32_16x16x32_bf16 v[70:73], v[168:171], v[226:229], v[70:73]
	v_mfma_f32_16x16x32_bf16 v[74:77], v[180:183], v[226:229], v[74:77]
	v_mfma_f32_16x16x32_bf16 v[66:69], v[188:191], v[226:229], v[66:69]
	v_mfma_f32_16x16x32_bf16 v[66:69], v[184:187], v[222:225], v[66:69]
	v_mfma_f32_16x16x32_bf16 v[74:77], v[176:179], v[222:225], v[74:77]
	v_mfma_f32_16x16x32_bf16 v[70:73], v[158:161], v[222:225], v[70:73]
	v_mfma_f32_16x16x32_bf16 v[78:81], v[142:145], v[222:225], v[78:81]
	s_setprio 0
	s_barrier
	s_mov_b32 m0, s44
	s_add_u32 s62, s22, 0x100000
	global_load_lds_dwordx4 v132, s[22:23]
	s_mov_b32 m0, s45
	s_addc_u32 s63, s23, 0
	global_load_lds_dwordx4 v136, s[22:23]
	s_mov_b32 m0, s46
	ds_read_b128 v[192:195], v150 offset:16384
	global_load_lds_dwordx4 v132, s[62:63]
	s_mov_b32 m0, s47
	ds_read_b128 v[202:205], v150 offset:17408
	global_load_lds_dwordx4 v136, s[62:63]
	ds_read_b128 v[206:209], v150 offset:18432
	ds_read_b128 v[210:213], v150 offset:19456
	ds_read_b128 v[214:217], v150 offset:20480
	ds_read_b128 v[218:221], v150 offset:21504
	ds_read_b128 v[222:225], v150 offset:22528
	ds_read_b128 v[226:229], v150 offset:23552
	s_waitcnt vmcnt(6)
	s_waitcnt lgkmcnt(0)
	s_barrier
	s_setprio 1
	s_waitcnt lgkmcnt(0)
	v_mfma_f32_16x16x32_bf16 v[62:65], v[142:145], v[192:195], v[62:65]
	v_mfma_f32_16x16x32_bf16 v[54:57], v[158:161], v[192:195], v[54:57]
	v_mfma_f32_16x16x32_bf16 v[58:61], v[176:179], v[192:195], v[58:61]
	v_mfma_f32_16x16x32_bf16 v[50:53], v[184:187], v[192:195], v[50:53]
	v_mfma_f32_16x16x32_bf16 v[50:53], v[188:191], v[202:205], v[50:53]
	v_mfma_f32_16x16x32_bf16 v[58:61], v[180:183], v[202:205], v[58:61]
	v_mfma_f32_16x16x32_bf16 v[54:57], v[168:171], v[202:205], v[54:57]
	v_mfma_f32_16x16x32_bf16 v[62:65], v[154:157], v[202:205], v[62:65]
	v_mfma_f32_16x16x32_bf16 v[46:49], v[154:157], v[210:213], v[46:49]
	v_mfma_f32_16x16x32_bf16 v[38:41], v[168:171], v[210:213], v[38:41]
	v_mfma_f32_16x16x32_bf16 v[42:45], v[180:183], v[210:213], v[42:45]
	v_mfma_f32_16x16x32_bf16 v[34:37], v[188:191], v[210:213], v[34:37]
	v_mfma_f32_16x16x32_bf16 v[34:37], v[184:187], v[206:209], v[34:37]
	v_mfma_f32_16x16x32_bf16 v[42:45], v[176:179], v[206:209], v[42:45]
	v_mfma_f32_16x16x32_bf16 v[38:41], v[158:161], v[206:209], v[38:41]
	v_mfma_f32_16x16x32_bf16 v[46:49], v[142:145], v[206:209], v[46:49]
	v_mfma_f32_16x16x32_bf16 v[30:33], v[142:145], v[214:217], v[30:33]
	v_mfma_f32_16x16x32_bf16 v[22:25], v[158:161], v[214:217], v[22:25]
	v_mfma_f32_16x16x32_bf16 v[26:29], v[176:179], v[214:217], v[26:29]
	v_mfma_f32_16x16x32_bf16 v[18:21], v[184:187], v[214:217], v[18:21]
	v_mfma_f32_16x16x32_bf16 v[18:21], v[188:191], v[218:221], v[18:21]
	v_mfma_f32_16x16x32_bf16 v[26:29], v[180:183], v[218:221], v[26:29]
	v_mfma_f32_16x16x32_bf16 v[22:25], v[168:171], v[218:221], v[22:25]
	v_mfma_f32_16x16x32_bf16 v[30:33], v[154:157], v[218:221], v[30:33]
	v_mfma_f32_16x16x32_bf16 v[14:17], v[154:157], v[226:229], v[14:17]
	v_mfma_f32_16x16x32_bf16 v[6:9], v[168:171], v[226:229], v[6:9]
	v_mfma_f32_16x16x32_bf16 v[10:13], v[180:183], v[226:229], v[10:13]
	v_mfma_f32_16x16x32_bf16 v[2:5], v[188:191], v[226:229], v[2:5]
	v_mfma_f32_16x16x32_bf16 v[2:5], v[184:187], v[222:225], v[2:5]
	v_mfma_f32_16x16x32_bf16 v[10:13], v[176:179], v[222:225], v[10:13]
	v_mfma_f32_16x16x32_bf16 v[6:9], v[158:161], v[222:225], v[6:9]
	v_mfma_f32_16x16x32_bf16 v[14:17], v[142:145], v[222:225], v[14:17]
	s_setprio 0
	s_barrier
	s_mov_b32 m0, s31
	ds_read_b128 v[142:145], v151
	global_load_lds_dwordx4 v130, s[24:25]
	s_mov_b32 m0, s33
	ds_read_b128 v[154:157], v151 offset:1024
	global_load_lds_dwordx4 v134, s[24:25]
	s_add_u32 s24, s24, 0x100000
	s_addc_u32 s25, s25, 0
	s_mov_b32 m0, s34
	ds_read_b128 v[158:161], v151 offset:2048
	global_load_lds_dwordx4 v130, s[24:25]
	s_mov_b32 m0, s35
	ds_read_b128 v[168:171], v151 offset:3072
	global_load_lds_dwordx4 v134, s[24:25]
	ds_read_b128 v[176:179], v152
	ds_read_b128 v[180:183], v152 offset:1024
	ds_read_b128 v[184:187], v152 offset:2048
	ds_read_b128 v[188:191], v152 offset:3072
	ds_read_b128 v[192:195], v150 offset:32768
	ds_read_b128 v[202:205], v150 offset:33792
	ds_read_b128 v[206:209], v150 offset:34816
	ds_read_b128 v[210:213], v150 offset:35840
	ds_read_b128 v[214:217], v150 offset:36864
	ds_read_b128 v[218:221], v150 offset:37888
	ds_read_b128 v[222:225], v150 offset:38912
	ds_read_b128 v[226:229], v150 offset:39936
	s_waitcnt vmcnt(8)
	s_waitcnt lgkmcnt(0)
	s_barrier
	s_setprio 1
	s_waitcnt lgkmcnt(0)
	v_mfma_f32_16x16x32_bf16 v[126:129], v[142:145], v[192:195], v[126:129]
	v_mfma_f32_16x16x32_bf16 v[118:121], v[158:161], v[192:195], v[118:121]
	v_mfma_f32_16x16x32_bf16 v[122:125], v[176:179], v[192:195], v[122:125]
	v_mfma_f32_16x16x32_bf16 v[114:117], v[184:187], v[192:195], v[114:117]
	v_mfma_f32_16x16x32_bf16 v[114:117], v[188:191], v[202:205], v[114:117]
	v_mfma_f32_16x16x32_bf16 v[122:125], v[180:183], v[202:205], v[122:125]
	v_mfma_f32_16x16x32_bf16 v[118:121], v[168:171], v[202:205], v[118:121]
	v_mfma_f32_16x16x32_bf16 v[126:129], v[154:157], v[202:205], v[126:129]
	v_mfma_f32_16x16x32_bf16 v[110:113], v[154:157], v[210:213], v[110:113]
	v_mfma_f32_16x16x32_bf16 v[102:105], v[168:171], v[210:213], v[102:105]
	v_mfma_f32_16x16x32_bf16 v[106:109], v[180:183], v[210:213], v[106:109]
	v_mfma_f32_16x16x32_bf16 v[98:101], v[188:191], v[210:213], v[98:101]
	v_mfma_f32_16x16x32_bf16 v[98:101], v[184:187], v[206:209], v[98:101]
	v_mfma_f32_16x16x32_bf16 v[106:109], v[176:179], v[206:209], v[106:109]
	v_mfma_f32_16x16x32_bf16 v[102:105], v[158:161], v[206:209], v[102:105]
	v_mfma_f32_16x16x32_bf16 v[110:113], v[142:145], v[206:209], v[110:113]
	v_mfma_f32_16x16x32_bf16 v[94:97], v[142:145], v[214:217], v[94:97]
	v_mfma_f32_16x16x32_bf16 v[86:89], v[158:161], v[214:217], v[86:89]
	v_mfma_f32_16x16x32_bf16 v[90:93], v[176:179], v[214:217], v[90:93]
	v_mfma_f32_16x16x32_bf16 v[82:85], v[184:187], v[214:217], v[82:85]
	v_mfma_f32_16x16x32_bf16 v[82:85], v[188:191], v[218:221], v[82:85]
	v_mfma_f32_16x16x32_bf16 v[90:93], v[180:183], v[218:221], v[90:93]
	v_mfma_f32_16x16x32_bf16 v[86:89], v[168:171], v[218:221], v[86:89]
	v_mfma_f32_16x16x32_bf16 v[94:97], v[154:157], v[218:221], v[94:97]
	v_mfma_f32_16x16x32_bf16 v[78:81], v[154:157], v[226:229], v[78:81]
	v_mfma_f32_16x16x32_bf16 v[70:73], v[168:171], v[226:229], v[70:73]
	v_mfma_f32_16x16x32_bf16 v[74:77], v[180:183], v[226:229], v[74:77]
	v_mfma_f32_16x16x32_bf16 v[66:69], v[188:191], v[226:229], v[66:69]
	v_mfma_f32_16x16x32_bf16 v[66:69], v[184:187], v[222:225], v[66:69]
	v_mfma_f32_16x16x32_bf16 v[74:77], v[176:179], v[222:225], v[74:77]
	v_mfma_f32_16x16x32_bf16 v[70:73], v[158:161], v[222:225], v[70:73]
	v_mfma_f32_16x16x32_bf16 v[78:81], v[142:145], v[222:225], v[78:81]
	s_setprio 0
	s_barrier
	s_mov_b32 m0, s48
	s_add_u32 s22, s22, 0x80
	s_addc_u32 s23, s23, 0
	global_load_lds_dwordx4 v132, s[22:23]
	s_mov_b32 m0, s49
	ds_read_b128 v[192:195], v150 offset:49152
	global_load_lds_dwordx4 v136, s[22:23]
	s_mov_b32 m0, s50
	s_add_u32 s22, s22, 0x100000
	s_addc_u32 s23, s23, 0
	global_load_lds_dwordx4 v132, s[22:23]
	s_mov_b32 m0, s51
	ds_read_b128 v[202:205], v150 offset:50176
	global_load_lds_dwordx4 v136, s[22:23]
	ds_read_b128 v[206:209], v150 offset:51200
	ds_read_b128 v[210:213], v150 offset:52224
	ds_read_b128 v[214:217], v150 offset:53248
	ds_read_b128 v[218:221], v150 offset:54272
	ds_read_b128 v[222:225], v150 offset:55296
	ds_read_b128 v[226:229], v150 offset:56320
	s_waitcnt vmcnt(6)
	s_waitcnt lgkmcnt(0)
	s_barrier
	s_setprio 1
	s_waitcnt lgkmcnt(0)
	v_mfma_f32_16x16x32_bf16 v[62:65], v[142:145], v[192:195], v[62:65]
	v_mfma_f32_16x16x32_bf16 v[54:57], v[158:161], v[192:195], v[54:57]
	v_mfma_f32_16x16x32_bf16 v[58:61], v[176:179], v[192:195], v[58:61]
	v_mfma_f32_16x16x32_bf16 v[50:53], v[184:187], v[192:195], v[50:53]
	v_mfma_f32_16x16x32_bf16 v[50:53], v[188:191], v[202:205], v[50:53]
	v_mfma_f32_16x16x32_bf16 v[58:61], v[180:183], v[202:205], v[58:61]
	v_mfma_f32_16x16x32_bf16 v[54:57], v[168:171], v[202:205], v[54:57]
	v_mfma_f32_16x16x32_bf16 v[62:65], v[154:157], v[202:205], v[62:65]
	v_mfma_f32_16x16x32_bf16 v[46:49], v[154:157], v[210:213], v[46:49]
	v_mfma_f32_16x16x32_bf16 v[38:41], v[168:171], v[210:213], v[38:41]
	v_mfma_f32_16x16x32_bf16 v[42:45], v[180:183], v[210:213], v[42:45]
	v_mfma_f32_16x16x32_bf16 v[34:37], v[188:191], v[210:213], v[34:37]
	v_mfma_f32_16x16x32_bf16 v[34:37], v[184:187], v[206:209], v[34:37]
	v_mfma_f32_16x16x32_bf16 v[42:45], v[176:179], v[206:209], v[42:45]
	v_mfma_f32_16x16x32_bf16 v[38:41], v[158:161], v[206:209], v[38:41]
	v_mfma_f32_16x16x32_bf16 v[46:49], v[142:145], v[206:209], v[46:49]
	v_mfma_f32_16x16x32_bf16 v[30:33], v[142:145], v[214:217], v[30:33]
	v_mfma_f32_16x16x32_bf16 v[22:25], v[158:161], v[214:217], v[22:25]
	v_mfma_f32_16x16x32_bf16 v[26:29], v[176:179], v[214:217], v[26:29]
	v_mfma_f32_16x16x32_bf16 v[18:21], v[184:187], v[214:217], v[18:21]
	v_mfma_f32_16x16x32_bf16 v[18:21], v[188:191], v[218:221], v[18:21]
	v_mfma_f32_16x16x32_bf16 v[26:29], v[180:183], v[218:221], v[26:29]
	v_mfma_f32_16x16x32_bf16 v[22:25], v[168:171], v[218:221], v[22:25]
	v_mfma_f32_16x16x32_bf16 v[30:33], v[154:157], v[218:221], v[30:33]
	v_mfma_f32_16x16x32_bf16 v[14:17], v[154:157], v[226:229], v[14:17]
	v_mfma_f32_16x16x32_bf16 v[6:9], v[168:171], v[226:229], v[6:9]
	v_mfma_f32_16x16x32_bf16 v[10:13], v[180:183], v[226:229], v[10:13]
	v_mfma_f32_16x16x32_bf16 v[2:5], v[188:191], v[226:229], v[2:5]
	v_mfma_f32_16x16x32_bf16 v[2:5], v[184:187], v[222:225], v[2:5]
	v_mfma_f32_16x16x32_bf16 v[10:13], v[176:179], v[222:225], v[10:13]
	v_mfma_f32_16x16x32_bf16 v[6:9], v[158:161], v[222:225], v[6:9]
	v_mfma_f32_16x16x32_bf16 v[14:17], v[142:145], v[222:225], v[14:17]
	s_setprio 0
	s_barrier
	s_add_i32 s61, s61, 2
	s_add_u32 s20, s20, 0x100
	s_addc_u32 s21, s21, 0
	s_add_u32 s57, s57, 0x100
	s_addc_u32 s60, s60, 0
	s_cmp_gt_u32 s61, 61
	s_cbranch_scc0 .LBB0_1172
	s_and_b64 vcc, exec, s[16:17]
	s_cbranch_vccz .LBB0_1175
	s_barrier

.LBB0_1418:
	s_add_u32 s56, s22, 0xffd50000
	s_addc_u32 s57, s23, -1
	s_mov_b32 m0, s40
	ds_read_b128 v[142:145], v156
	global_load_lds_dwordx4 v130, s[56:57]
	s_mov_b32 m0, s41
	ds_read_b128 v[168:171], v156 offset:1024
	global_load_lds_dwordx4 v134, s[56:57]
	s_mov_b32 m0, s42
	ds_read_b128 v[176:179], v156 offset:2048
	global_load_lds_dwordx4 v138, s[22:23]
	s_mov_b32 m0, s43
	ds_read_b128 v[180:183], v156 offset:3072
	global_load_lds_dwordx4 v140, s[22:23]
	ds_read_b128 v[184:187], v157
	ds_read_b128 v[188:191], v157 offset:1024
	ds_read_b128 v[192:195], v157 offset:2048
	ds_read_b128 v[204:207], v157 offset:3072
	s_add_u32 s24, s22, 0xffd50080
	s_addc_u32 s25, s23, -1
	s_cmpk_eq_i32 s55, 0xa8
	s_cselect_b32 s27, s19, s25
	s_cselect_b32 s26, s18, s24
	s_cselect_b32 s25, s17, s54
	s_cselect_b32 s24, s16, s53
	ds_read_b128 v[208:211], v158
	ds_read_b128 v[212:215], v158 offset:1024
	ds_read_b128 v[216:219], v158 offset:2048
	ds_read_b128 v[220:223], v158 offset:3072
	ds_read_b128 v[224:227], v158 offset:4096
	ds_read_b128 v[228:231], v158 offset:5120
	ds_read_b128 v[232:235], v158 offset:6144
	ds_read_b128 v[236:239], v158 offset:7168
	s_waitcnt vmcnt(8)
	s_waitcnt lgkmcnt(0)
	s_barrier
	s_setprio 1
	s_waitcnt lgkmcnt(0)
	v_mfma_f32_16x16x32_bf16 v[126:129], v[142:145], v[208:211], v[126:129]
	v_mfma_f32_16x16x32_bf16 v[122:125], v[176:179], v[208:211], v[122:125]
	v_mfma_f32_16x16x32_bf16 v[118:121], v[184:187], v[208:211], v[118:121]
	v_mfma_f32_16x16x32_bf16 v[114:117], v[192:195], v[208:211], v[114:117]
	v_mfma_f32_16x16x32_bf16 v[114:117], v[204:207], v[212:215], v[114:117]
	v_mfma_f32_16x16x32_bf16 v[118:121], v[188:191], v[212:215], v[118:121]
	v_mfma_f32_16x16x32_bf16 v[122:125], v[180:183], v[212:215], v[122:125]
	v_mfma_f32_16x16x32_bf16 v[126:129], v[168:171], v[212:215], v[126:129]
	v_mfma_f32_16x16x32_bf16 v[110:113], v[168:171], v[220:223], v[110:113]
	v_mfma_f32_16x16x32_bf16 v[106:109], v[180:183], v[220:223], v[106:109]
	v_mfma_f32_16x16x32_bf16 v[102:105], v[188:191], v[220:223], v[102:105]
	v_mfma_f32_16x16x32_bf16 v[98:101], v[204:207], v[220:223], v[98:101]
	v_mfma_f32_16x16x32_bf16 v[98:101], v[192:195], v[216:219], v[98:101]
	v_mfma_f32_16x16x32_bf16 v[102:105], v[184:187], v[216:219], v[102:105]
	v_mfma_f32_16x16x32_bf16 v[106:109], v[176:179], v[216:219], v[106:109]
	v_mfma_f32_16x16x32_bf16 v[110:113], v[142:145], v[216:219], v[110:113]
	v_mfma_f32_16x16x32_bf16 v[94:97], v[142:145], v[224:227], v[94:97]
	v_mfma_f32_16x16x32_bf16 v[90:93], v[176:179], v[224:227], v[90:93]
	v_mfma_f32_16x16x32_bf16 v[86:89], v[184:187], v[224:227], v[86:89]
	v_mfma_f32_16x16x32_bf16 v[82:85], v[192:195], v[224:227], v[82:85]
	v_mfma_f32_16x16x32_bf16 v[82:85], v[204:207], v[228:231], v[82:85]
	v_mfma_f32_16x16x32_bf16 v[86:89], v[188:191], v[228:231], v[86:89]
	v_mfma_f32_16x16x32_bf16 v[90:93], v[180:183], v[228:231], v[90:93]
	v_mfma_f32_16x16x32_bf16 v[94:97], v[168:171], v[228:231], v[94:97]
	v_mfma_f32_16x16x32_bf16 v[78:81], v[168:171], v[236:239], v[78:81]
	v_mfma_f32_16x16x32_bf16 v[74:77], v[180:183], v[236:239], v[74:77]
	v_mfma_f32_16x16x32_bf16 v[70:73], v[188:191], v[236:239], v[70:73]
	v_mfma_f32_16x16x32_bf16 v[66:69], v[204:207], v[236:239], v[66:69]
	v_mfma_f32_16x16x32_bf16 v[66:69], v[192:195], v[232:235], v[66:69]
	v_mfma_f32_16x16x32_bf16 v[70:73], v[184:187], v[232:235], v[70:73]
	v_mfma_f32_16x16x32_bf16 v[74:77], v[176:179], v[232:235], v[74:77]
	v_mfma_f32_16x16x32_bf16 v[78:81], v[142:145], v[232:235], v[78:81]
	s_setprio 0
	s_barrier
	s_mov_b32 m0, s44
	s_add_u32 s56, s24, 0x2b0000
	global_load_lds_dwordx4 v132, s[24:25]
	s_mov_b32 m0, s45
	s_addc_u32 s57, s25, 0
	global_load_lds_dwordx4 v136, s[24:25]
	s_mov_b32 m0, s46
	ds_read_b128 v[208:211], v158 offset:16384
	global_load_lds_dwordx4 v132, s[56:57]
	s_mov_b32 m0, s47
	ds_read_b128 v[212:215], v158 offset:17408
	global_load_lds_dwordx4 v136, s[56:57]
	ds_read_b128 v[216:219], v158 offset:18432
	ds_read_b128 v[220:223], v158 offset:19456
	ds_read_b128 v[224:227], v158 offset:20480
	ds_read_b128 v[228:231], v158 offset:21504
	ds_read_b128 v[232:235], v158 offset:22528
	ds_read_b128 v[236:239], v158 offset:23552
	s_waitcnt vmcnt(6)
	s_waitcnt lgkmcnt(0)
	s_barrier
	s_setprio 1
	s_waitcnt lgkmcnt(0)
	v_mfma_f32_16x16x32_bf16 v[62:65], v[142:145], v[208:211], v[62:65]
	v_mfma_f32_16x16x32_bf16 v[58:61], v[176:179], v[208:211], v[58:61]
	v_mfma_f32_16x16x32_bf16 v[54:57], v[184:187], v[208:211], v[54:57]
	v_mfma_f32_16x16x32_bf16 v[50:53], v[192:195], v[208:211], v[50:53]
	v_mfma_f32_16x16x32_bf16 v[50:53], v[204:207], v[212:215], v[50:53]
	v_mfma_f32_16x16x32_bf16 v[54:57], v[188:191], v[212:215], v[54:57]
	v_mfma_f32_16x16x32_bf16 v[58:61], v[180:183], v[212:215], v[58:61]
	v_mfma_f32_16x16x32_bf16 v[62:65], v[168:171], v[212:215], v[62:65]
	v_mfma_f32_16x16x32_bf16 v[46:49], v[168:171], v[220:223], v[46:49]
	v_mfma_f32_16x16x32_bf16 v[42:45], v[180:183], v[220:223], v[42:45]
	v_mfma_f32_16x16x32_bf16 v[38:41], v[188:191], v[220:223], v[38:41]
	v_mfma_f32_16x16x32_bf16 v[34:37], v[204:207], v[220:223], v[34:37]
	v_mfma_f32_16x16x32_bf16 v[34:37], v[192:195], v[216:219], v[34:37]
	v_mfma_f32_16x16x32_bf16 v[38:41], v[184:187], v[216:219], v[38:41]
	v_mfma_f32_16x16x32_bf16 v[42:45], v[176:179], v[216:219], v[42:45]
	v_mfma_f32_16x16x32_bf16 v[46:49], v[142:145], v[216:219], v[46:49]
	v_mfma_f32_16x16x32_bf16 v[30:33], v[142:145], v[224:227], v[30:33]
	v_mfma_f32_16x16x32_bf16 v[26:29], v[176:179], v[224:227], v[26:29]
	v_mfma_f32_16x16x32_bf16 v[22:25], v[184:187], v[224:227], v[22:25]
	v_mfma_f32_16x16x32_bf16 v[18:21], v[192:195], v[224:227], v[18:21]
	v_mfma_f32_16x16x32_bf16 v[18:21], v[204:207], v[228:231], v[18:21]
	v_mfma_f32_16x16x32_bf16 v[22:25], v[188:191], v[228:231], v[22:25]
	v_mfma_f32_16x16x32_bf16 v[26:29], v[180:183], v[228:231], v[26:29]
	v_mfma_f32_16x16x32_bf16 v[30:33], v[168:171], v[228:231], v[30:33]
	v_mfma_f32_16x16x32_bf16 v[14:17], v[168:171], v[236:239], v[14:17]
	v_mfma_f32_16x16x32_bf16 v[10:13], v[180:183], v[236:239], v[10:13]
	v_mfma_f32_16x16x32_bf16 v[6:9], v[188:191], v[236:239], v[6:9]
	v_mfma_f32_16x16x32_bf16 v[2:5], v[204:207], v[236:239], v[2:5]
	v_mfma_f32_16x16x32_bf16 v[2:5], v[192:195], v[232:235], v[2:5]
	v_mfma_f32_16x16x32_bf16 v[6:9], v[184:187], v[232:235], v[6:9]
	v_mfma_f32_16x16x32_bf16 v[10:13], v[176:179], v[232:235], v[10:13]
	v_mfma_f32_16x16x32_bf16 v[14:17], v[142:145], v[232:235], v[14:17]
	s_setprio 0
	s_barrier
	s_mov_b32 m0, s35
	ds_read_b128 v[142:145], v159
	global_load_lds_dwordx4 v130, s[26:27]
	s_mov_b32 m0, s36
	ds_read_b128 v[168:171], v159 offset:1024
	global_load_lds_dwordx4 v134, s[26:27]
	s_add_u32 s26, s26, 0x2b0000
	s_addc_u32 s27, s27, 0
	s_mov_b32 m0, s37
	ds_read_b128 v[176:179], v159 offset:2048
	global_load_lds_dwordx4 v130, s[26:27]
	s_mov_b32 m0, s38
	ds_read_b128 v[180:183], v159 offset:3072
	global_load_lds_dwordx4 v134, s[26:27]
	ds_read_b128 v[184:187], v160
	ds_read_b128 v[188:191], v160 offset:1024
	ds_read_b128 v[192:195], v160 offset:2048
	ds_read_b128 v[204:207], v160 offset:3072
	ds_read_b128 v[208:211], v158 offset:32768
	ds_read_b128 v[212:215], v158 offset:33792
	ds_read_b128 v[216:219], v158 offset:34816
	ds_read_b128 v[220:223], v158 offset:35840
	ds_read_b128 v[224:227], v158 offset:36864
	ds_read_b128 v[228:231], v158 offset:37888
	ds_read_b128 v[232:235], v158 offset:38912
	ds_read_b128 v[236:239], v158 offset:39936
	s_waitcnt vmcnt(8)
	s_waitcnt lgkmcnt(0)
	s_barrier
	s_setprio 1
	s_waitcnt lgkmcnt(0)
	v_mfma_f32_16x16x32_bf16 v[126:129], v[142:145], v[208:211], v[126:129]
	v_mfma_f32_16x16x32_bf16 v[122:125], v[176:179], v[208:211], v[122:125]
	v_mfma_f32_16x16x32_bf16 v[118:121], v[184:187], v[208:211], v[118:121]
	v_mfma_f32_16x16x32_bf16 v[114:117], v[192:195], v[208:211], v[114:117]
	v_mfma_f32_16x16x32_bf16 v[114:117], v[204:207], v[212:215], v[114:117]
	v_mfma_f32_16x16x32_bf16 v[118:121], v[188:191], v[212:215], v[118:121]
	v_mfma_f32_16x16x32_bf16 v[122:125], v[180:183], v[212:215], v[122:125]
	v_mfma_f32_16x16x32_bf16 v[126:129], v[168:171], v[212:215], v[126:129]
	v_mfma_f32_16x16x32_bf16 v[110:113], v[168:171], v[220:223], v[110:113]
	v_mfma_f32_16x16x32_bf16 v[106:109], v[180:183], v[220:223], v[106:109]
	v_mfma_f32_16x16x32_bf16 v[102:105], v[188:191], v[220:223], v[102:105]
	v_mfma_f32_16x16x32_bf16 v[98:101], v[204:207], v[220:223], v[98:101]
	v_mfma_f32_16x16x32_bf16 v[98:101], v[192:195], v[216:219], v[98:101]
	v_mfma_f32_16x16x32_bf16 v[102:105], v[184:187], v[216:219], v[102:105]
	v_mfma_f32_16x16x32_bf16 v[106:109], v[176:179], v[216:219], v[106:109]
	v_mfma_f32_16x16x32_bf16 v[110:113], v[142:145], v[216:219], v[110:113]
	v_mfma_f32_16x16x32_bf16 v[94:97], v[142:145], v[224:227], v[94:97]
	v_mfma_f32_16x16x32_bf16 v[90:93], v[176:179], v[224:227], v[90:93]
	v_mfma_f32_16x16x32_bf16 v[86:89], v[184:187], v[224:227], v[86:89]
	v_mfma_f32_16x16x32_bf16 v[82:85], v[192:195], v[224:227], v[82:85]
	v_mfma_f32_16x16x32_bf16 v[82:85], v[204:207], v[228:231], v[82:85]
	v_mfma_f32_16x16x32_bf16 v[86:89], v[188:191], v[228:231], v[86:89]
	v_mfma_f32_16x16x32_bf16 v[90:93], v[180:183], v[228:231], v[90:93]
	v_mfma_f32_16x16x32_bf16 v[94:97], v[168:171], v[228:231], v[94:97]
	v_mfma_f32_16x16x32_bf16 v[78:81], v[168:171], v[236:239], v[78:81]
	v_mfma_f32_16x16x32_bf16 v[74:77], v[180:183], v[236:239], v[74:77]
	v_mfma_f32_16x16x32_bf16 v[70:73], v[188:191], v[236:239], v[70:73]
	v_mfma_f32_16x16x32_bf16 v[66:69], v[204:207], v[236:239], v[66:69]
	v_mfma_f32_16x16x32_bf16 v[66:69], v[192:195], v[232:235], v[66:69]
	v_mfma_f32_16x16x32_bf16 v[70:73], v[184:187], v[232:235], v[70:73]
	v_mfma_f32_16x16x32_bf16 v[74:77], v[176:179], v[232:235], v[74:77]
	v_mfma_f32_16x16x32_bf16 v[78:81], v[142:145], v[232:235], v[78:81]
	s_setprio 0
	s_barrier
	s_mov_b32 m0, s48
	s_add_u32 s24, s24, 0x80
	s_addc_u32 s25, s25, 0
	global_load_lds_dwordx4 v132, s[24:25]
	s_mov_b32 m0, s49
	ds_read_b128 v[208:211], v158 offset:49152
	global_load_lds_dwordx4 v136, s[24:25]
	s_mov_b32 m0, s50
	s_add_u32 s24, s24, 0x2b0000
	s_addc_u32 s25, s25, 0
	global_load_lds_dwordx4 v132, s[24:25]
	s_add_i32 m0, s50, 0x2000
	ds_read_b128 v[212:215], v158 offset:50176
	global_load_lds_dwordx4 v136, s[24:25]
	ds_read_b128 v[216:219], v158 offset:51200
	ds_read_b128 v[220:223], v158 offset:52224
	ds_read_b128 v[224:227], v158 offset:53248
	ds_read_b128 v[228:231], v158 offset:54272
	ds_read_b128 v[232:235], v158 offset:55296
	ds_read_b128 v[236:239], v158 offset:56320
	s_waitcnt vmcnt(6)
	s_waitcnt lgkmcnt(0)
	s_barrier
	s_setprio 1
	s_waitcnt lgkmcnt(0)
	v_mfma_f32_16x16x32_bf16 v[62:65], v[142:145], v[208:211], v[62:65]
	v_mfma_f32_16x16x32_bf16 v[58:61], v[176:179], v[208:211], v[58:61]
	v_mfma_f32_16x16x32_bf16 v[54:57], v[184:187], v[208:211], v[54:57]
	v_mfma_f32_16x16x32_bf16 v[50:53], v[192:195], v[208:211], v[50:53]
	v_mfma_f32_16x16x32_bf16 v[50:53], v[204:207], v[212:215], v[50:53]
	v_mfma_f32_16x16x32_bf16 v[54:57], v[188:191], v[212:215], v[54:57]
	v_mfma_f32_16x16x32_bf16 v[58:61], v[180:183], v[212:215], v[58:61]
	v_mfma_f32_16x16x32_bf16 v[62:65], v[168:171], v[212:215], v[62:65]
	v_mfma_f32_16x16x32_bf16 v[46:49], v[168:171], v[220:223], v[46:49]
	v_mfma_f32_16x16x32_bf16 v[42:45], v[180:183], v[220:223], v[42:45]
	v_mfma_f32_16x16x32_bf16 v[38:41], v[188:191], v[220:223], v[38:41]
	v_mfma_f32_16x16x32_bf16 v[34:37], v[204:207], v[220:223], v[34:37]
	v_mfma_f32_16x16x32_bf16 v[34:37], v[192:195], v[216:219], v[34:37]
	v_mfma_f32_16x16x32_bf16 v[38:41], v[184:187], v[216:219], v[38:41]
	v_mfma_f32_16x16x32_bf16 v[42:45], v[176:179], v[216:219], v[42:45]
	v_mfma_f32_16x16x32_bf16 v[46:49], v[142:145], v[216:219], v[46:49]
	v_mfma_f32_16x16x32_bf16 v[30:33], v[142:145], v[224:227], v[30:33]
	v_mfma_f32_16x16x32_bf16 v[26:29], v[176:179], v[224:227], v[26:29]
	v_mfma_f32_16x16x32_bf16 v[22:25], v[184:187], v[224:227], v[22:25]
	v_mfma_f32_16x16x32_bf16 v[18:21], v[192:195], v[224:227], v[18:21]
	v_mfma_f32_16x16x32_bf16 v[18:21], v[204:207], v[228:231], v[18:21]
	v_mfma_f32_16x16x32_bf16 v[22:25], v[188:191], v[228:231], v[22:25]
	v_mfma_f32_16x16x32_bf16 v[26:29], v[180:183], v[228:231], v[26:29]
	v_mfma_f32_16x16x32_bf16 v[30:33], v[168:171], v[228:231], v[30:33]
	v_mfma_f32_16x16x32_bf16 v[14:17], v[168:171], v[236:239], v[14:17]
	v_mfma_f32_16x16x32_bf16 v[10:13], v[180:183], v[236:239], v[10:13]
	v_mfma_f32_16x16x32_bf16 v[6:9], v[188:191], v[236:239], v[6:9]
	v_mfma_f32_16x16x32_bf16 v[2:5], v[204:207], v[236:239], v[2:5]
	v_mfma_f32_16x16x32_bf16 v[2:5], v[192:195], v[232:235], v[2:5]
	v_mfma_f32_16x16x32_bf16 v[6:9], v[184:187], v[232:235], v[6:9]
	v_mfma_f32_16x16x32_bf16 v[10:13], v[176:179], v[232:235], v[10:13]
	v_mfma_f32_16x16x32_bf16 v[14:17], v[142:145], v[232:235], v[14:17]
	s_setprio 0
	s_barrier
	s_add_i32 s55, s55, 2
	s_add_u32 s22, s22, 0x100
	s_addc_u32 s23, s23, 0
	s_add_u32 s53, s53, 0x100
	s_addc_u32 s54, s54, 0
	s_cmpk_gt_u32 s55, 0xa9
	s_cbranch_scc0 .LBB0_1418
	s_and_b64 vcc, exec, s[14:15]
	s_cbranch_vccz .LBB0_1421
	s_barrier

.LBB0_1432:
	ds_read_b128 v[150:153], v139
	ds_read_b128 v[154:157], v139 offset:1024
	ds_read_b128 v[158:161], v139 offset:2048
	ds_read_b128 v[168:171], v139 offset:3072
	ds_read_b128 v[176:179], v144
	ds_read_b128 v[180:183], v144 offset:1024
	ds_read_b128 v[184:187], v144 offset:2048
	ds_read_b128 v[188:191], v144 offset:3072
	s_add_i32 s42, s15, 2
	s_add_u32 s14, s12, 0xc2050080
	s_addc_u32 s16, s13, -1
	s_cmp_lg_u32 s30, s15
	s_cselect_b32 s14, s14, 0
	s_cselect_b32 s15, s16, 0
	s_add_u32 s16, s4, s14
	s_addc_u32 s17, s5, s15
	s_add_u32 s14, s8, s14
	s_addc_u32 s15, s9, s15
	s_mov_b32 m0, s31
	v_lshl_add_u64 v[172:173], v[140:141], 0, s[12:13]
	ds_read_b128 v[192:195], v145
	ds_read_b128 v[204:207], v145 offset:1024
	ds_read_b128 v[208:211], v145 offset:2048
	ds_read_b128 v[212:215], v145 offset:3072
	ds_read_b128 v[216:219], v145 offset:4096
	ds_read_b128 v[220:223], v145 offset:5120
	ds_read_b128 v[224:227], v145 offset:6144
	ds_read_b128 v[228:231], v145 offset:7168
	global_load_lds_dwordx4 v[172:173], off
	v_lshl_add_u64 v[172:173], v[142:143], 0, s[12:13]
	s_mov_b32 m0, s33
	s_nop 0
	global_load_lds_dwordx4 v[172:173], off
	s_waitcnt vmcnt(8)
	s_waitcnt lgkmcnt(0)
	s_barrier
	s_setprio 1
	s_waitcnt lgkmcnt(0)
	v_mfma_f32_16x16x32_bf16 v[126:129], v[150:153], v[192:195], v[126:129]
	v_mfma_f32_16x16x32_bf16 v[122:125], v[158:161], v[192:195], v[122:125]
	v_mfma_f32_16x16x32_bf16 v[110:113], v[176:179], v[192:195], v[110:113]
	v_mfma_f32_16x16x32_bf16 v[106:109], v[184:187], v[192:195], v[106:109]
	v_mfma_f32_16x16x32_bf16 v[106:109], v[188:191], v[204:207], v[106:109]
	v_mfma_f32_16x16x32_bf16 v[110:113], v[180:183], v[204:207], v[110:113]
	v_mfma_f32_16x16x32_bf16 v[122:125], v[168:171], v[204:207], v[122:125]
	v_mfma_f32_16x16x32_bf16 v[126:129], v[154:157], v[204:207], v[126:129]
	v_mfma_f32_16x16x32_bf16 v[118:121], v[154:157], v[212:215], v[118:121]
	v_mfma_f32_16x16x32_bf16 v[114:117], v[168:171], v[212:215], v[114:117]
	v_mfma_f32_16x16x32_bf16 v[94:97], v[180:183], v[212:215], v[94:97]
	v_mfma_f32_16x16x32_bf16 v[90:93], v[188:191], v[212:215], v[90:93]
	v_mfma_f32_16x16x32_bf16 v[90:93], v[184:187], v[208:211], v[90:93]
	v_mfma_f32_16x16x32_bf16 v[94:97], v[176:179], v[208:211], v[94:97]
	v_mfma_f32_16x16x32_bf16 v[114:117], v[158:161], v[208:211], v[114:117]
	v_mfma_f32_16x16x32_bf16 v[118:121], v[150:153], v[208:211], v[118:121]
	v_mfma_f32_16x16x32_bf16 v[102:105], v[150:153], v[216:219], v[102:105]
	v_mfma_f32_16x16x32_bf16 v[98:101], v[158:161], v[216:219], v[98:101]
	v_mfma_f32_16x16x32_bf16 v[78:81], v[176:179], v[216:219], v[78:81]
	v_mfma_f32_16x16x32_bf16 v[74:77], v[184:187], v[216:219], v[74:77]
	v_mfma_f32_16x16x32_bf16 v[74:77], v[188:191], v[220:223], v[74:77]
	v_mfma_f32_16x16x32_bf16 v[78:81], v[180:183], v[220:223], v[78:81]
	v_mfma_f32_16x16x32_bf16 v[98:101], v[168:171], v[220:223], v[98:101]
	v_mfma_f32_16x16x32_bf16 v[102:105], v[154:157], v[220:223], v[102:105]
	v_mfma_f32_16x16x32_bf16 v[86:89], v[154:157], v[228:231], v[86:89]
	v_mfma_f32_16x16x32_bf16 v[82:85], v[168:171], v[228:231], v[82:85]
	v_mfma_f32_16x16x32_bf16 v[70:73], v[180:183], v[228:231], v[70:73]
	v_mfma_f32_16x16x32_bf16 v[66:69], v[188:191], v[228:231], v[66:69]
	v_mfma_f32_16x16x32_bf16 v[66:69], v[184:187], v[224:227], v[66:69]
	v_mfma_f32_16x16x32_bf16 v[70:73], v[176:179], v[224:227], v[70:73]
	v_mfma_f32_16x16x32_bf16 v[82:85], v[158:161], v[224:227], v[82:85]
	v_mfma_f32_16x16x32_bf16 v[86:89], v[150:153], v[224:227], v[86:89]
	s_setprio 0
	s_barrier
	s_mov_b32 m0, s34
	v_lshl_add_u64 v[172:173], s[14:15], 0, v[132:133]
	s_add_u32 s44, s14, 0x2b0000
	ds_read_b128 v[192:195], v145 offset:16384
	ds_read_b128 v[204:207], v145 offset:17408
	ds_read_b128 v[208:211], v145 offset:18432
	ds_read_b128 v[212:215], v145 offset:19456
	ds_read_b128 v[216:219], v145 offset:20480
	ds_read_b128 v[220:223], v145 offset:21504
	ds_read_b128 v[224:227], v145 offset:22528
	ds_read_b128 v[228:231], v145 offset:23552
	global_load_lds_dwordx4 v[172:173], off
	v_lshl_add_u64 v[196:197], s[14:15], 0, v[136:137]
	s_mov_b32 m0, s35
	s_addc_u32 s45, s15, 0
	global_load_lds_dwordx4 v[196:197], off
	v_lshl_add_u64 v[232:233], s[44:45], 0, v[132:133]
	s_mov_b32 m0, s36
	v_lshl_add_u64 v[234:235], s[16:17], 0, v[134:135]
	global_load_lds_dwordx4 v[232:233], off
	v_lshl_add_u64 v[232:233], s[44:45], 0, v[136:137]
	s_mov_b32 m0, s37
	s_nop 0
	global_load_lds_dwordx4 v[232:233], off
	v_lshl_add_u64 v[232:233], s[16:17], 0, v[130:131]
	s_mov_b32 m0, s21
	s_nop 0
	global_load_lds_dwordx4 v[232:233], off
	s_mov_b32 m0, s22
	s_nop 0
	global_load_lds_dwordx4 v[234:235], off
	s_waitcnt vmcnt(8)
	s_waitcnt lgkmcnt(0)
	s_barrier
	s_setprio 1
	s_waitcnt lgkmcnt(0)
	v_mfma_f32_16x16x32_bf16 v[62:65], v[150:153], v[192:195], v[62:65]
	v_mfma_f32_16x16x32_bf16 v[58:61], v[158:161], v[192:195], v[58:61]
	v_mfma_f32_16x16x32_bf16 v[46:49], v[176:179], v[192:195], v[46:49]
	v_mfma_f32_16x16x32_bf16 v[42:45], v[184:187], v[192:195], v[42:45]
	v_mfma_f32_16x16x32_bf16 v[42:45], v[188:191], v[204:207], v[42:45]
	v_mfma_f32_16x16x32_bf16 v[46:49], v[180:183], v[204:207], v[46:49]
	v_mfma_f32_16x16x32_bf16 v[58:61], v[168:171], v[204:207], v[58:61]
	v_mfma_f32_16x16x32_bf16 v[62:65], v[154:157], v[204:207], v[62:65]
	v_mfma_f32_16x16x32_bf16 v[54:57], v[154:157], v[212:215], v[54:57]
	v_mfma_f32_16x16x32_bf16 v[50:53], v[168:171], v[212:215], v[50:53]
	v_mfma_f32_16x16x32_bf16 v[30:33], v[180:183], v[212:215], v[30:33]
	v_mfma_f32_16x16x32_bf16 v[26:29], v[188:191], v[212:215], v[26:29]
	v_mfma_f32_16x16x32_bf16 v[26:29], v[184:187], v[208:211], v[26:29]
	v_mfma_f32_16x16x32_bf16 v[30:33], v[176:179], v[208:211], v[30:33]
	v_mfma_f32_16x16x32_bf16 v[50:53], v[158:161], v[208:211], v[50:53]
	v_mfma_f32_16x16x32_bf16 v[54:57], v[150:153], v[208:211], v[54:57]
	v_mfma_f32_16x16x32_bf16 v[38:41], v[150:153], v[216:219], v[38:41]
	v_mfma_f32_16x16x32_bf16 v[34:37], v[158:161], v[216:219], v[34:37]
	v_mfma_f32_16x16x32_bf16 v[14:17], v[176:179], v[216:219], v[14:17]
	v_mfma_f32_16x16x32_bf16 v[10:13], v[184:187], v[216:219], v[10:13]
	v_mfma_f32_16x16x32_bf16 v[10:13], v[188:191], v[220:223], v[10:13]
	v_mfma_f32_16x16x32_bf16 v[14:17], v[180:183], v[220:223], v[14:17]
	v_mfma_f32_16x16x32_bf16 v[34:37], v[168:171], v[220:223], v[34:37]
	v_mfma_f32_16x16x32_bf16 v[38:41], v[154:157], v[220:223], v[38:41]
	v_mfma_f32_16x16x32_bf16 v[22:25], v[154:157], v[228:231], v[22:25]
	v_mfma_f32_16x16x32_bf16 v[18:21], v[168:171], v[228:231], v[18:21]
	v_mfma_f32_16x16x32_bf16 v[6:9], v[180:183], v[228:231], v[6:9]
	v_mfma_f32_16x16x32_bf16 v[2:5], v[188:191], v[228:231], v[2:5]
	v_mfma_f32_16x16x32_bf16 v[2:5], v[184:187], v[224:227], v[2:5]
	v_mfma_f32_16x16x32_bf16 v[6:9], v[176:179], v[224:227], v[6:9]
	v_mfma_f32_16x16x32_bf16 v[18:21], v[158:161], v[224:227], v[18:21]
	v_mfma_f32_16x16x32_bf16 v[22:25], v[150:153], v[224:227], v[22:25]
	s_setprio 0
	s_barrier
	ds_read_b128 v[150:153], v146
	ds_read_b128 v[154:157], v146 offset:1024
	ds_read_b128 v[158:161], v146 offset:2048
	ds_read_b128 v[168:171], v146 offset:3072
	ds_read_b128 v[176:179], v147
	ds_read_b128 v[180:183], v147 offset:1024
	ds_read_b128 v[184:187], v147 offset:2048
	ds_read_b128 v[188:191], v147 offset:3072
	s_add_u32 s16, s16, 0x2b0000
	s_addc_u32 s17, s17, 0
	s_mov_b32 m0, s23
	v_lshl_add_u64 v[236:237], s[16:17], 0, v[130:131]
	ds_read_b128 v[192:195], v145 offset:32768
	ds_read_b128 v[204:207], v145 offset:33792
	ds_read_b128 v[208:211], v145 offset:34816
	ds_read_b128 v[212:215], v145 offset:35840
	ds_read_b128 v[216:219], v145 offset:36864
	ds_read_b128 v[220:223], v145 offset:37888
	ds_read_b128 v[224:227], v145 offset:38912
	ds_read_b128 v[228:231], v145 offset:39936
	global_load_lds_dwordx4 v[236:237], off
	v_lshl_add_u64 v[236:237], s[16:17], 0, v[134:135]
	s_mov_b32 m0, s24
	s_nop 0
	global_load_lds_dwordx4 v[236:237], off
	s_waitcnt vmcnt(8)
	s_waitcnt lgkmcnt(0)
	s_barrier
	s_setprio 1
	s_waitcnt lgkmcnt(0)
	v_mfma_f32_16x16x32_bf16 v[126:129], v[150:153], v[192:195], v[126:129]
	v_mfma_f32_16x16x32_bf16 v[122:125], v[158:161], v[192:195], v[122:125]
	v_mfma_f32_16x16x32_bf16 v[110:113], v[176:179], v[192:195], v[110:113]
	v_mfma_f32_16x16x32_bf16 v[106:109], v[184:187], v[192:195], v[106:109]
	v_mfma_f32_16x16x32_bf16 v[106:109], v[188:191], v[204:207], v[106:109]
	v_mfma_f32_16x16x32_bf16 v[110:113], v[180:183], v[204:207], v[110:113]
	v_mfma_f32_16x16x32_bf16 v[122:125], v[168:171], v[204:207], v[122:125]
	v_mfma_f32_16x16x32_bf16 v[126:129], v[154:157], v[204:207], v[126:129]
	v_mfma_f32_16x16x32_bf16 v[118:121], v[154:157], v[212:215], v[118:121]
	v_mfma_f32_16x16x32_bf16 v[114:117], v[168:171], v[212:215], v[114:117]
	v_mfma_f32_16x16x32_bf16 v[94:97], v[180:183], v[212:215], v[94:97]
	v_mfma_f32_16x16x32_bf16 v[90:93], v[188:191], v[212:215], v[90:93]
	v_mfma_f32_16x16x32_bf16 v[90:93], v[184:187], v[208:211], v[90:93]
	v_mfma_f32_16x16x32_bf16 v[94:97], v[176:179], v[208:211], v[94:97]
	v_mfma_f32_16x16x32_bf16 v[114:117], v[158:161], v[208:211], v[114:117]
	v_mfma_f32_16x16x32_bf16 v[118:121], v[150:153], v[208:211], v[118:121]
	v_mfma_f32_16x16x32_bf16 v[102:105], v[150:153], v[216:219], v[102:105]
	v_mfma_f32_16x16x32_bf16 v[98:101], v[158:161], v[216:219], v[98:101]
	v_mfma_f32_16x16x32_bf16 v[78:81], v[176:179], v[216:219], v[78:81]
	v_mfma_f32_16x16x32_bf16 v[74:77], v[184:187], v[216:219], v[74:77]
	v_mfma_f32_16x16x32_bf16 v[74:77], v[188:191], v[220:223], v[74:77]
	v_mfma_f32_16x16x32_bf16 v[78:81], v[180:183], v[220:223], v[78:81]
	v_mfma_f32_16x16x32_bf16 v[98:101], v[168:171], v[220:223], v[98:101]
	v_mfma_f32_16x16x32_bf16 v[102:105], v[154:157], v[220:223], v[102:105]
	v_mfma_f32_16x16x32_bf16 v[86:89], v[154:157], v[228:231], v[86:89]
	v_mfma_f32_16x16x32_bf16 v[82:85], v[168:171], v[228:231], v[82:85]
	v_mfma_f32_16x16x32_bf16 v[70:73], v[180:183], v[228:231], v[70:73]
	v_mfma_f32_16x16x32_bf16 v[66:69], v[188:191], v[228:231], v[66:69]
	v_mfma_f32_16x16x32_bf16 v[66:69], v[184:187], v[224:227], v[66:69]
	v_mfma_f32_16x16x32_bf16 v[70:73], v[176:179], v[224:227], v[70:73]
	v_mfma_f32_16x16x32_bf16 v[82:85], v[158:161], v[224:227], v[82:85]
	v_mfma_f32_16x16x32_bf16 v[86:89], v[150:153], v[224:227], v[86:89]
	s_setprio 0
	s_barrier
	s_mov_b32 m0, s38
	v_lshl_add_u64 v[172:173], v[172:173], 0, s[10:11]
	s_add_u32 s14, s14, 0x2b0080
	ds_read_b128 v[192:195], v145 offset:49152
	ds_read_b128 v[204:207], v145 offset:50176
	ds_read_b128 v[208:211], v145 offset:51200
	ds_read_b128 v[212:215], v145 offset:52224
	ds_read_b128 v[216:219], v145 offset:53248
	ds_read_b128 v[220:223], v145 offset:54272
	ds_read_b128 v[224:227], v145 offset:55296
	ds_read_b128 v[228:231], v145 offset:56320
	global_load_lds_dwordx4 v[172:173], off
	v_lshl_add_u64 v[172:173], v[196:197], 0, s[10:11]
	s_mov_b32 m0, s39
	s_addc_u32 s15, s15, 0
	global_load_lds_dwordx4 v[172:173], off
	v_lshl_add_u64 v[172:173], s[14:15], 0, v[132:133]
	s_mov_b32 m0, s40
	s_nop 0
	global_load_lds_dwordx4 v[172:173], off
	v_lshl_add_u64 v[172:173], s[14:15], 0, v[136:137]
	s_mov_b32 m0, s41
	s_nop 0
	global_load_lds_dwordx4 v[172:173], off
	v_lshl_add_u64 v[172:173], v[232:233], 0, s[10:11]
	s_mov_b32 m0, s26
	s_nop 0
	global_load_lds_dwordx4 v[172:173], off
	v_lshl_add_u64 v[172:173], v[234:235], 0, s[10:11]
	s_mov_b32 m0, s27
	s_nop 0
	global_load_lds_dwordx4 v[172:173], off
	s_waitcnt vmcnt(8)
	s_waitcnt lgkmcnt(0)
	s_barrier
	s_setprio 1
	s_waitcnt lgkmcnt(0)
	v_mfma_f32_16x16x32_bf16 v[62:65], v[150:153], v[192:195], v[62:65]
	v_mfma_f32_16x16x32_bf16 v[58:61], v[158:161], v[192:195], v[58:61]
	v_mfma_f32_16x16x32_bf16 v[46:49], v[176:179], v[192:195], v[46:49]
	v_mfma_f32_16x16x32_bf16 v[42:45], v[184:187], v[192:195], v[42:45]
	v_mfma_f32_16x16x32_bf16 v[42:45], v[188:191], v[204:207], v[42:45]
	v_mfma_f32_16x16x32_bf16 v[46:49], v[180:183], v[204:207], v[46:49]
	v_mfma_f32_16x16x32_bf16 v[58:61], v[168:171], v[204:207], v[58:61]
	v_mfma_f32_16x16x32_bf16 v[62:65], v[154:157], v[204:207], v[62:65]
	v_mfma_f32_16x16x32_bf16 v[54:57], v[154:157], v[212:215], v[54:57]
	v_mfma_f32_16x16x32_bf16 v[50:53], v[168:171], v[212:215], v[50:53]
	v_mfma_f32_16x16x32_bf16 v[30:33], v[180:183], v[212:215], v[30:33]
	v_mfma_f32_16x16x32_bf16 v[26:29], v[188:191], v[212:215], v[26:29]
	v_mfma_f32_16x16x32_bf16 v[26:29], v[184:187], v[208:211], v[26:29]
	v_mfma_f32_16x16x32_bf16 v[30:33], v[176:179], v[208:211], v[30:33]
	v_mfma_f32_16x16x32_bf16 v[50:53], v[158:161], v[208:211], v[50:53]
	v_mfma_f32_16x16x32_bf16 v[54:57], v[150:153], v[208:211], v[54:57]
	v_mfma_f32_16x16x32_bf16 v[38:41], v[150:153], v[216:219], v[38:41]
	v_mfma_f32_16x16x32_bf16 v[34:37], v[158:161], v[216:219], v[34:37]
	v_mfma_f32_16x16x32_bf16 v[14:17], v[176:179], v[216:219], v[14:17]
	v_mfma_f32_16x16x32_bf16 v[10:13], v[184:187], v[216:219], v[10:13]
	v_mfma_f32_16x16x32_bf16 v[10:13], v[188:191], v[220:223], v[10:13]
	v_mfma_f32_16x16x32_bf16 v[14:17], v[180:183], v[220:223], v[14:17]
	v_mfma_f32_16x16x32_bf16 v[34:37], v[168:171], v[220:223], v[34:37]
	v_mfma_f32_16x16x32_bf16 v[38:41], v[154:157], v[220:223], v[38:41]
	v_mfma_f32_16x16x32_bf16 v[22:25], v[154:157], v[228:231], v[22:25]
	v_mfma_f32_16x16x32_bf16 v[18:21], v[168:171], v[228:231], v[18:21]
	v_mfma_f32_16x16x32_bf16 v[6:9], v[180:183], v[228:231], v[6:9]
	v_mfma_f32_16x16x32_bf16 v[2:5], v[188:191], v[228:231], v[2:5]
	v_mfma_f32_16x16x32_bf16 v[2:5], v[184:187], v[224:227], v[2:5]
	v_mfma_f32_16x16x32_bf16 v[6:9], v[176:179], v[224:227], v[6:9]
	v_mfma_f32_16x16x32_bf16 v[18:21], v[158:161], v[224:227], v[18:21]
	v_mfma_f32_16x16x32_bf16 v[22:25], v[150:153], v[224:227], v[22:25]
	s_setprio 0
	s_barrier
	s_add_u32 s12, s12, 0x100
	s_addc_u32 s13, s13, 0
	s_cmp_ge_u32 s42, s19
	s_mov_b32 s15, s42
	s_cbranch_scc0 .LBB0_1432
	s_lshl_b32 s4, s18, 21
	v_readlane_b32 s0, v249, 29
	v_lshl_or_b32 v130, s20, 8, v148
	v_mov_b32_e32 v139, 0
	s_add_u32 s4, s0, s4
	v_readlane_b32 s0, v249, 31
	v_or_b32_e32 v130, s25, v130
	v_cvt_pk_bf16_f32 v70, v70, v71
	v_cvt_pk_bf16_f32 v71, v72, v73
	v_cvt_pk_bf16_f32 v72, v66, v67
	v_add_u32_e32 v66, 0x80, v138
	v_mov_b32_e32 v67, v139
	s_addc_u32 s5, s0, 0
	v_ashrrev_i32_e32 v131, 31, v130
	v_lshlrev_b64 v[132:133], 13, v[138:139]
	v_cvt_pk_bf16_f32 v110, v110, v111
	v_cvt_pk_bf16_f32 v111, v112, v113
	v_cvt_pk_bf16_f32 v112, v106, v107
	v_or_b32_e32 v106, 16, v138
	v_mov_b32_e32 v107, v139
	v_lshlrev_b64 v[66:67], 13, v[66:67]
	v_cvt_pk_bf16_f32 v46, v46, v47
	v_cvt_pk_bf16_f32 v47, v48, v49
	v_cvt_pk_bf16_f32 v48, v42, v43
	v_add_u32_e32 v42, 0x90, v138
	v_mov_b32_e32 v43, v139
	v_lshl_add_u64 v[132:133], s[4:5], 0, v[132:133]
	v_lshlrev_b64 v[130:131], 1, v[130:131]
	v_lshlrev_b64 v[106:107], 13, v[106:107]
	v_cvt_pk_bf16_f32 v94, v94, v95
	v_cvt_pk_bf16_f32 v95, v96, v97
	v_cvt_pk_bf16_f32 v96, v90, v91
	v_or_b32_e32 v90, 32, v138
	v_mov_b32_e32 v91, v139
	v_lshl_add_u64 v[66:67], s[4:5], 0, v[66:67]
	v_lshlrev_b64 v[42:43], 13, v[42:43]
	v_cvt_pk_bf16_f32 v30, v30, v31
	v_cvt_pk_bf16_f32 v31, v32, v33
	v_cvt_pk_bf16_f32 v32, v26, v27
	v_add_u32_e32 v26, 0xa0, v138
	v_mov_b32_e32 v27, v139
	v_lshl_add_u64 v[132:133], v[132:133], 0, v[130:131]
	v_cvt_pk_bf16_f32 v113, v108, v109
	v_lshl_add_u64 v[106:107], s[4:5], 0, v[106:107]
	v_lshlrev_b64 v[90:91], 13, v[90:91]
	v_cvt_pk_bf16_f32 v78, v78, v79
	v_cvt_pk_bf16_f32 v79, v80, v81
	v_cvt_pk_bf16_f32 v80, v74, v75
	v_or_b32_e32 v74, 48, v138
	v_mov_b32_e32 v75, v139
	v_lshl_add_u64 v[66:67], v[66:67], 0, v[130:131]
	v_cvt_pk_bf16_f32 v49, v44, v45
	v_lshl_add_u64 v[42:43], s[4:5], 0, v[42:43]
	v_lshlrev_b64 v[26:27], 13, v[26:27]
	v_add_u32_e32 v138, 0xb0, v138
	global_store_dwordx4 v[132:133], v[110:113], off offset:256
	v_cvt_pk_bf16_f32 v97, v92, v93
	v_lshl_add_u64 v[90:91], s[4:5], 0, v[90:91]
	v_lshl_add_u64 v[110:111], v[106:107], 0, v[130:131]
	v_lshlrev_b64 v[74:75], 13, v[74:75]
	global_store_dwordx4 v[66:67], v[46:49], off offset:256
	v_cvt_pk_bf16_f32 v33, v28, v29
	v_lshl_add_u64 v[26:27], s[4:5], 0, v[26:27]
	v_lshl_add_u64 v[46:47], v[42:43], 0, v[130:131]
	v_cvt_pk_bf16_f32 v14, v14, v15
	v_cvt_pk_bf16_f32 v15, v16, v17
	v_cvt_pk_bf16_f32 v16, v10, v11
	v_lshlrev_b64 v[10:11], 13, v[138:139]
	global_store_dwordx4 v[110:111], v[94:97], off offset:256
	v_cvt_pk_bf16_f32 v81, v76, v77
	v_lshl_add_u64 v[74:75], s[4:5], 0, v[74:75]
	v_lshl_add_u64 v[94:95], v[90:91], 0, v[130:131]
	global_store_dwordx4 v[46:47], v[30:33], off offset:256
	v_cvt_pk_bf16_f32 v17, v12, v13
	v_lshl_add_u64 v[10:11], s[4:5], 0, v[10:11]
	v_lshl_add_u64 v[30:31], v[26:27], 0, v[130:131]
	v_cvt_pk_bf16_f32 v126, v126, v127
	v_cvt_pk_bf16_f32 v127, v128, v129
	v_cvt_pk_bf16_f32 v128, v122, v123
	v_cvt_pk_bf16_f32 v129, v124, v125
	v_cvt_pk_bf16_f32 v106, v118, v119
	v_cvt_pk_bf16_f32 v107, v120, v121
	v_cvt_pk_bf16_f32 v108, v114, v115
	v_cvt_pk_bf16_f32 v109, v116, v117
	v_cvt_pk_bf16_f32 v90, v102, v103
	v_cvt_pk_bf16_f32 v91, v104, v105
	v_cvt_pk_bf16_f32 v92, v98, v99
	v_cvt_pk_bf16_f32 v93, v100, v101
	global_store_dwordx4 v[94:95], v[78:81], off offset:256
	v_cvt_pk_bf16_f32 v76, v82, v83
	v_cvt_pk_bf16_f32 v77, v84, v85
	v_lshl_add_u64 v[78:79], v[74:75], 0, v[130:131]
	v_cvt_pk_bf16_f32 v74, v86, v87
	v_cvt_pk_bf16_f32 v75, v88, v89
	v_cvt_pk_bf16_f32 v73, v68, v69
	v_cvt_pk_bf16_f32 v62, v62, v63
	v_cvt_pk_bf16_f32 v63, v64, v65
	v_cvt_pk_bf16_f32 v64, v58, v59
	v_cvt_pk_bf16_f32 v65, v60, v61
	v_cvt_pk_bf16_f32 v42, v54, v55
	v_cvt_pk_bf16_f32 v43, v56, v57
	v_cvt_pk_bf16_f32 v44, v50, v51
	v_cvt_pk_bf16_f32 v45, v52, v53
	v_cvt_pk_bf16_f32 v26, v38, v39
	v_cvt_pk_bf16_f32 v27, v40, v41
	v_cvt_pk_bf16_f32 v28, v34, v35
	v_cvt_pk_bf16_f32 v29, v36, v37
	global_store_dwordx4 v[30:31], v[14:17], off offset:256
	v_cvt_pk_bf16_f32 v12, v18, v19
	v_cvt_pk_bf16_f32 v13, v20, v21
	v_lshl_add_u64 v[14:15], v[10:11], 0, v[130:131]
	v_cvt_pk_bf16_f32 v10, v22, v23
	v_cvt_pk_bf16_f32 v11, v24, v25
	v_cvt_pk_bf16_f32 v6, v6, v7
	v_cvt_pk_bf16_f32 v7, v8, v9
	v_cvt_pk_bf16_f32 v8, v2, v3
	v_cvt_pk_bf16_f32 v9, v4, v5
	global_store_dwordx4 v[132:133], v[126:129], off
	global_store_dwordx4 v[110:111], v[106:109], off
	global_store_dwordx4 v[94:95], v[90:93], off
	global_store_dwordx4 v[78:79], v[74:77], off
	global_store_dwordx4 v[78:79], v[70:73], off offset:256
	global_store_dwordx4 v[66:67], v[62:65], off
	global_store_dwordx4 v[46:47], v[42:45], off
	global_store_dwordx4 v[30:31], v[26:29], off
	global_store_dwordx4 v[14:15], v[10:13], off
	global_store_dwordx4 v[14:15], v[6:9], off offset:256
	s_waitcnt vmcnt(0)
	s_cmpk_lt_u32 s3, 0x100
	s_cbranch_scc0 .LBB0_1435
	s_barrier

.LBB0_1565:
	ds_read_b128 v[130:133], v204
	ds_read_b128 v[134:137], v204 offset:1024
	ds_read_b128 v[138:141], v204 offset:2048
	ds_read_b128 v[142:145], v204 offset:3072
	ds_read_b128 v[146:149], v205
	ds_read_b128 v[150:153], v205 offset:1024
	ds_read_b128 v[154:157], v205 offset:2048
	ds_read_b128 v[158:161], v205 offset:3072
	s_add_u32 s8, s6, 0xfff00080
	s_addc_u32 s9, s7, -1
	s_cmp_eq_u32 s66, 60
	s_cselect_b32 s73, s41, s9
	s_cselect_b32 s72, s50, s8
	s_cselect_b32 s9, s13, s57
	s_cselect_b32 s8, s51, s56
	v_lshl_add_u64 v[196:197], s[6:7], 0, v[180:181]
	s_add_i32 m0, s42, 0xc000
	ds_read_b128 v[184:187], v206
	ds_read_b128 v[188:191], v206 offset:1024
	ds_read_b128 v[192:195], v206 offset:2048
	ds_read_b128 v[210:213], v206 offset:3072
	ds_read_b128 v[214:217], v206 offset:4096
	ds_read_b128 v[218:221], v206 offset:5120
	ds_read_b128 v[222:225], v206 offset:6144
	ds_read_b128 v[226:229], v206 offset:7168
	global_load_lds_dwordx4 v[196:197], off
	v_lshl_add_u64 v[196:197], s[6:7], 0, v[182:183]
	s_add_i32 m0, s42, 0xe000
	s_nop 0
	global_load_lds_dwordx4 v[196:197], off
	s_waitcnt vmcnt(8)
	s_waitcnt lgkmcnt(0)
	s_barrier
	s_setprio 1
	s_waitcnt lgkmcnt(0)
	v_mfma_f32_16x16x32_bf16 v[126:129], v[130:133], v[184:187], v[126:129]
	v_mfma_f32_16x16x32_bf16 v[122:125], v[138:141], v[184:187], v[122:125]
	v_mfma_f32_16x16x32_bf16 v[118:121], v[146:149], v[184:187], v[118:121]
	v_mfma_f32_16x16x32_bf16 v[114:117], v[154:157], v[184:187], v[114:117]
	v_mfma_f32_16x16x32_bf16 v[114:117], v[158:161], v[188:191], v[114:117]
	v_mfma_f32_16x16x32_bf16 v[118:121], v[150:153], v[188:191], v[118:121]
	v_mfma_f32_16x16x32_bf16 v[122:125], v[142:145], v[188:191], v[122:125]
	v_mfma_f32_16x16x32_bf16 v[126:129], v[134:137], v[188:191], v[126:129]
	v_mfma_f32_16x16x32_bf16 v[110:113], v[134:137], v[210:213], v[110:113]
	v_mfma_f32_16x16x32_bf16 v[106:109], v[142:145], v[210:213], v[106:109]
	v_mfma_f32_16x16x32_bf16 v[102:105], v[150:153], v[210:213], v[102:105]
	v_mfma_f32_16x16x32_bf16 v[98:101], v[158:161], v[210:213], v[98:101]
	v_mfma_f32_16x16x32_bf16 v[98:101], v[154:157], v[192:195], v[98:101]
	v_mfma_f32_16x16x32_bf16 v[102:105], v[146:149], v[192:195], v[102:105]
	v_mfma_f32_16x16x32_bf16 v[106:109], v[138:141], v[192:195], v[106:109]
	v_mfma_f32_16x16x32_bf16 v[110:113], v[130:133], v[192:195], v[110:113]
	v_mfma_f32_16x16x32_bf16 v[94:97], v[130:133], v[214:217], v[94:97]
	v_mfma_f32_16x16x32_bf16 v[90:93], v[138:141], v[214:217], v[90:93]
	v_mfma_f32_16x16x32_bf16 v[86:89], v[146:149], v[214:217], v[86:89]
	v_mfma_f32_16x16x32_bf16 v[82:85], v[154:157], v[214:217], v[82:85]
	v_mfma_f32_16x16x32_bf16 v[82:85], v[158:161], v[218:221], v[82:85]
	v_mfma_f32_16x16x32_bf16 v[86:89], v[150:153], v[218:221], v[86:89]
	v_mfma_f32_16x16x32_bf16 v[90:93], v[142:145], v[218:221], v[90:93]
	v_mfma_f32_16x16x32_bf16 v[94:97], v[134:137], v[218:221], v[94:97]
	v_mfma_f32_16x16x32_bf16 v[78:81], v[134:137], v[226:229], v[78:81]
	v_mfma_f32_16x16x32_bf16 v[74:77], v[142:145], v[226:229], v[74:77]
	v_mfma_f32_16x16x32_bf16 v[70:73], v[150:153], v[226:229], v[70:73]
	v_mfma_f32_16x16x32_bf16 v[66:69], v[158:161], v[226:229], v[66:69]
	v_mfma_f32_16x16x32_bf16 v[66:69], v[154:157], v[222:225], v[66:69]
	v_mfma_f32_16x16x32_bf16 v[70:73], v[146:149], v[222:225], v[70:73]
	v_mfma_f32_16x16x32_bf16 v[74:77], v[138:141], v[222:225], v[74:77]
	v_mfma_f32_16x16x32_bf16 v[78:81], v[130:133], v[222:225], v[78:81]
	s_setprio 0
	s_barrier
	s_add_i32 s67, s54, s35
	v_lshl_add_u64 v[196:197], s[8:9], 0, v[168:169]
	s_mov_b32 m0, s67
	ds_read_b128 v[184:187], v206 offset:16384
	ds_read_b128 v[188:191], v206 offset:17408
	ds_read_b128 v[192:195], v206 offset:18432
	ds_read_b128 v[210:213], v206 offset:19456
	ds_read_b128 v[214:217], v206 offset:20480
	ds_read_b128 v[218:221], v206 offset:21504
	ds_read_b128 v[222:225], v206 offset:22528
	ds_read_b128 v[226:229], v206 offset:23552
	global_load_lds_dwordx4 v[196:197], off
	s_add_i32 m0, s67, 0x2000
	s_add_u32 s68, s8, 0x100000
	v_lshl_add_u64 v[230:231], s[8:9], 0, v[170:171]
	s_addc_u32 s69, s9, 0
	s_add_i32 s67, s55, s35
	global_load_lds_dwordx4 v[230:231], off
	v_lshl_add_u64 v[232:233], s[68:69], 0, v[168:169]
	s_mov_b32 m0, s67
	v_lshl_add_u64 v[234:235], s[72:73], 0, v[170:171]
	global_load_lds_dwordx4 v[232:233], off
	v_lshl_add_u64 v[232:233], s[68:69], 0, v[170:171]
	s_add_i32 m0, s67, 0x2000
	s_nop 0
	global_load_lds_dwordx4 v[232:233], off
	v_lshl_add_u64 v[232:233], s[72:73], 0, v[168:169]
	s_mov_b32 m0, s42
	s_nop 0
	global_load_lds_dwordx4 v[232:233], off
	s_mov_b32 m0, s43
	s_nop 0
	global_load_lds_dwordx4 v[234:235], off
	s_waitcnt vmcnt(8)
	s_waitcnt lgkmcnt(0)
	s_barrier
	s_setprio 1
	s_waitcnt lgkmcnt(0)
	v_mfma_f32_16x16x32_bf16 v[62:65], v[130:133], v[184:187], v[62:65]
	v_mfma_f32_16x16x32_bf16 v[58:61], v[138:141], v[184:187], v[58:61]
	v_mfma_f32_16x16x32_bf16 v[54:57], v[146:149], v[184:187], v[54:57]
	v_mfma_f32_16x16x32_bf16 v[50:53], v[154:157], v[184:187], v[50:53]
	v_mfma_f32_16x16x32_bf16 v[50:53], v[158:161], v[188:191], v[50:53]
	v_mfma_f32_16x16x32_bf16 v[54:57], v[150:153], v[188:191], v[54:57]
	v_mfma_f32_16x16x32_bf16 v[58:61], v[142:145], v[188:191], v[58:61]
	v_mfma_f32_16x16x32_bf16 v[62:65], v[134:137], v[188:191], v[62:65]
	v_mfma_f32_16x16x32_bf16 v[46:49], v[134:137], v[210:213], v[46:49]
	v_mfma_f32_16x16x32_bf16 v[42:45], v[142:145], v[210:213], v[42:45]
	v_mfma_f32_16x16x32_bf16 v[38:41], v[150:153], v[210:213], v[38:41]
	v_mfma_f32_16x16x32_bf16 v[34:37], v[158:161], v[210:213], v[34:37]
	v_mfma_f32_16x16x32_bf16 v[34:37], v[154:157], v[192:195], v[34:37]
	v_mfma_f32_16x16x32_bf16 v[38:41], v[146:149], v[192:195], v[38:41]
	v_mfma_f32_16x16x32_bf16 v[42:45], v[138:141], v[192:195], v[42:45]
	v_mfma_f32_16x16x32_bf16 v[46:49], v[130:133], v[192:195], v[46:49]
	v_mfma_f32_16x16x32_bf16 v[30:33], v[130:133], v[214:217], v[30:33]
	v_mfma_f32_16x16x32_bf16 v[26:29], v[138:141], v[214:217], v[26:29]
	v_mfma_f32_16x16x32_bf16 v[22:25], v[146:149], v[214:217], v[22:25]
	v_mfma_f32_16x16x32_bf16 v[18:21], v[154:157], v[214:217], v[18:21]
	v_mfma_f32_16x16x32_bf16 v[18:21], v[158:161], v[218:221], v[18:21]
	v_mfma_f32_16x16x32_bf16 v[22:25], v[150:153], v[218:221], v[22:25]
	v_mfma_f32_16x16x32_bf16 v[26:29], v[142:145], v[218:221], v[26:29]
	v_mfma_f32_16x16x32_bf16 v[30:33], v[134:137], v[218:221], v[30:33]
	v_mfma_f32_16x16x32_bf16 v[14:17], v[134:137], v[226:229], v[14:17]
	v_mfma_f32_16x16x32_bf16 v[10:13], v[142:145], v[226:229], v[10:13]
	v_mfma_f32_16x16x32_bf16 v[6:9], v[150:153], v[226:229], v[6:9]
	v_mfma_f32_16x16x32_bf16 v[2:5], v[158:161], v[226:229], v[2:5]
	v_mfma_f32_16x16x32_bf16 v[2:5], v[154:157], v[222:225], v[2:5]
	v_mfma_f32_16x16x32_bf16 v[6:9], v[146:149], v[222:225], v[6:9]
	v_mfma_f32_16x16x32_bf16 v[10:13], v[138:141], v[222:225], v[10:13]
	v_mfma_f32_16x16x32_bf16 v[14:17], v[130:133], v[222:225], v[14:17]
	s_setprio 0
	s_barrier
	s_add_i32 s67, 0, 0x18000
	s_add_i32 s70, 0, 0x1c000
	v_add_u32_e32 v142, s67, v203
	v_add_u32_e32 v158, s70, v203
	ds_read_b128 v[130:133], v142
	ds_read_b128 v[134:137], v142 offset:1024
	ds_read_b128 v[138:141], v142 offset:2048
	ds_read_b128 v[142:145], v142 offset:3072
	ds_read_b128 v[146:149], v158
	ds_read_b128 v[150:153], v158 offset:1024
	ds_read_b128 v[154:157], v158 offset:2048
	ds_read_b128 v[158:161], v158 offset:3072
	s_add_u32 s68, s72, 0x100000
	s_addc_u32 s69, s73, 0
	s_mov_b32 m0, s44
	v_lshl_add_u64 v[236:237], s[68:69], 0, v[168:169]
	ds_read_b128 v[184:187], v206 offset:32768
	ds_read_b128 v[188:191], v206 offset:33792
	ds_read_b128 v[192:195], v206 offset:34816
	ds_read_b128 v[210:213], v206 offset:35840
	ds_read_b128 v[214:217], v206 offset:36864
	ds_read_b128 v[218:221], v206 offset:37888
	ds_read_b128 v[222:225], v206 offset:38912
	ds_read_b128 v[226:229], v206 offset:39936
	global_load_lds_dwordx4 v[236:237], off
	v_lshl_add_u64 v[236:237], s[68:69], 0, v[170:171]
	s_mov_b32 m0, s45
	s_nop 0
	global_load_lds_dwordx4 v[236:237], off
	s_waitcnt vmcnt(8)
	s_waitcnt lgkmcnt(0)
	s_barrier
	s_setprio 1
	s_waitcnt lgkmcnt(0)
	v_mfma_f32_16x16x32_bf16 v[126:129], v[130:133], v[184:187], v[126:129]
	v_mfma_f32_16x16x32_bf16 v[122:125], v[138:141], v[184:187], v[122:125]
	v_mfma_f32_16x16x32_bf16 v[118:121], v[146:149], v[184:187], v[118:121]
	v_mfma_f32_16x16x32_bf16 v[114:117], v[154:157], v[184:187], v[114:117]
	v_mfma_f32_16x16x32_bf16 v[114:117], v[158:161], v[188:191], v[114:117]
	v_mfma_f32_16x16x32_bf16 v[118:121], v[150:153], v[188:191], v[118:121]
	v_mfma_f32_16x16x32_bf16 v[122:125], v[142:145], v[188:191], v[122:125]
	v_mfma_f32_16x16x32_bf16 v[126:129], v[134:137], v[188:191], v[126:129]
	v_mfma_f32_16x16x32_bf16 v[110:113], v[134:137], v[210:213], v[110:113]
	v_mfma_f32_16x16x32_bf16 v[106:109], v[142:145], v[210:213], v[106:109]
	v_mfma_f32_16x16x32_bf16 v[102:105], v[150:153], v[210:213], v[102:105]
	v_mfma_f32_16x16x32_bf16 v[98:101], v[158:161], v[210:213], v[98:101]
	v_mfma_f32_16x16x32_bf16 v[98:101], v[154:157], v[192:195], v[98:101]
	v_mfma_f32_16x16x32_bf16 v[102:105], v[146:149], v[192:195], v[102:105]
	v_mfma_f32_16x16x32_bf16 v[106:109], v[138:141], v[192:195], v[106:109]
	v_mfma_f32_16x16x32_bf16 v[110:113], v[130:133], v[192:195], v[110:113]
	v_mfma_f32_16x16x32_bf16 v[94:97], v[130:133], v[214:217], v[94:97]
	v_mfma_f32_16x16x32_bf16 v[90:93], v[138:141], v[214:217], v[90:93]
	v_mfma_f32_16x16x32_bf16 v[86:89], v[146:149], v[214:217], v[86:89]
	v_mfma_f32_16x16x32_bf16 v[82:85], v[154:157], v[214:217], v[82:85]
	v_mfma_f32_16x16x32_bf16 v[82:85], v[158:161], v[218:221], v[82:85]
	v_mfma_f32_16x16x32_bf16 v[86:89], v[150:153], v[218:221], v[86:89]
	v_mfma_f32_16x16x32_bf16 v[90:93], v[142:145], v[218:221], v[90:93]
	v_mfma_f32_16x16x32_bf16 v[94:97], v[134:137], v[218:221], v[94:97]
	v_mfma_f32_16x16x32_bf16 v[78:81], v[134:137], v[226:229], v[78:81]
	v_mfma_f32_16x16x32_bf16 v[74:77], v[142:145], v[226:229], v[74:77]
	v_mfma_f32_16x16x32_bf16 v[70:73], v[150:153], v[226:229], v[70:73]
	v_mfma_f32_16x16x32_bf16 v[66:69], v[158:161], v[226:229], v[66:69]
	v_mfma_f32_16x16x32_bf16 v[66:69], v[154:157], v[222:225], v[66:69]
	v_mfma_f32_16x16x32_bf16 v[70:73], v[146:149], v[222:225], v[70:73]
	v_mfma_f32_16x16x32_bf16 v[74:77], v[138:141], v[222:225], v[74:77]
	v_mfma_f32_16x16x32_bf16 v[78:81], v[130:133], v[222:225], v[78:81]
	s_setprio 0
	s_barrier
	s_add_i32 s67, s67, s35
	v_lshl_add_u64 v[196:197], v[196:197], 0, s[22:23]
	s_mov_b32 m0, s67
	ds_read_b128 v[184:187], v206 offset:49152
	ds_read_b128 v[188:191], v206 offset:50176
	ds_read_b128 v[192:195], v206 offset:51200
	ds_read_b128 v[210:213], v206 offset:52224
	ds_read_b128 v[214:217], v206 offset:53248
	ds_read_b128 v[218:221], v206 offset:54272
	ds_read_b128 v[222:225], v206 offset:55296
	ds_read_b128 v[226:229], v206 offset:56320
	global_load_lds_dwordx4 v[196:197], off
	s_add_i32 m0, s67, 0x2000
	s_add_u32 s8, s8, 0x100080
	v_lshl_add_u64 v[196:197], v[230:231], 0, s[22:23]
	s_addc_u32 s9, s9, 0
	s_add_i32 s67, s70, s35
	global_load_lds_dwordx4 v[196:197], off
	v_lshl_add_u64 v[196:197], s[8:9], 0, v[168:169]
	s_mov_b32 m0, s67
	s_nop 0
	global_load_lds_dwordx4 v[196:197], off
	v_lshl_add_u64 v[196:197], s[8:9], 0, v[170:171]
	s_add_i32 m0, s67, 0x2000
	s_nop 0
	global_load_lds_dwordx4 v[196:197], off
	v_lshl_add_u64 v[196:197], v[232:233], 0, s[22:23]
	s_mov_b32 m0, s48
	s_nop 0
	global_load_lds_dwordx4 v[196:197], off
	v_lshl_add_u64 v[196:197], v[234:235], 0, s[22:23]
	s_mov_b32 m0, s49
	s_nop 0
	global_load_lds_dwordx4 v[196:197], off
	s_waitcnt vmcnt(8)
	s_waitcnt lgkmcnt(0)
	s_barrier
	s_setprio 1
	s_waitcnt lgkmcnt(0)
	v_mfma_f32_16x16x32_bf16 v[62:65], v[130:133], v[184:187], v[62:65]
	v_mfma_f32_16x16x32_bf16 v[58:61], v[138:141], v[184:187], v[58:61]
	v_mfma_f32_16x16x32_bf16 v[54:57], v[146:149], v[184:187], v[54:57]
	v_mfma_f32_16x16x32_bf16 v[50:53], v[154:157], v[184:187], v[50:53]
	v_mfma_f32_16x16x32_bf16 v[50:53], v[158:161], v[188:191], v[50:53]
	v_mfma_f32_16x16x32_bf16 v[54:57], v[150:153], v[188:191], v[54:57]
	v_mfma_f32_16x16x32_bf16 v[58:61], v[142:145], v[188:191], v[58:61]
	v_mfma_f32_16x16x32_bf16 v[62:65], v[134:137], v[188:191], v[62:65]
	v_mfma_f32_16x16x32_bf16 v[46:49], v[134:137], v[210:213], v[46:49]
	v_mfma_f32_16x16x32_bf16 v[42:45], v[142:145], v[210:213], v[42:45]
	v_mfma_f32_16x16x32_bf16 v[38:41], v[150:153], v[210:213], v[38:41]
	v_mfma_f32_16x16x32_bf16 v[34:37], v[158:161], v[210:213], v[34:37]
	v_mfma_f32_16x16x32_bf16 v[34:37], v[154:157], v[192:195], v[34:37]
	v_mfma_f32_16x16x32_bf16 v[38:41], v[146:149], v[192:195], v[38:41]
	v_mfma_f32_16x16x32_bf16 v[42:45], v[138:141], v[192:195], v[42:45]
	v_mfma_f32_16x16x32_bf16 v[46:49], v[130:133], v[192:195], v[46:49]
	v_mfma_f32_16x16x32_bf16 v[30:33], v[130:133], v[214:217], v[30:33]
	v_mfma_f32_16x16x32_bf16 v[26:29], v[138:141], v[214:217], v[26:29]
	v_mfma_f32_16x16x32_bf16 v[22:25], v[146:149], v[214:217], v[22:25]
	v_mfma_f32_16x16x32_bf16 v[18:21], v[154:157], v[214:217], v[18:21]
	v_mfma_f32_16x16x32_bf16 v[18:21], v[158:161], v[218:221], v[18:21]
	v_mfma_f32_16x16x32_bf16 v[22:25], v[150:153], v[218:221], v[22:25]
	v_mfma_f32_16x16x32_bf16 v[26:29], v[142:145], v[218:221], v[26:29]
	v_mfma_f32_16x16x32_bf16 v[30:33], v[134:137], v[218:221], v[30:33]
	v_mfma_f32_16x16x32_bf16 v[14:17], v[134:137], v[226:229], v[14:17]
	v_mfma_f32_16x16x32_bf16 v[10:13], v[142:145], v[226:229], v[10:13]
	v_mfma_f32_16x16x32_bf16 v[6:9], v[150:153], v[226:229], v[6:9]
	v_mfma_f32_16x16x32_bf16 v[2:5], v[158:161], v[226:229], v[2:5]
	v_mfma_f32_16x16x32_bf16 v[2:5], v[154:157], v[222:225], v[2:5]
	v_mfma_f32_16x16x32_bf16 v[6:9], v[146:149], v[222:225], v[6:9]
	v_mfma_f32_16x16x32_bf16 v[10:13], v[138:141], v[222:225], v[10:13]
	v_mfma_f32_16x16x32_bf16 v[14:17], v[130:133], v[222:225], v[14:17]
	s_setprio 0
	s_barrier
	s_add_i32 s66, s66, 2
	s_add_u32 s6, s6, 0x100
	s_addc_u32 s7, s7, 0
	s_add_u32 s56, s56, 0x100
	s_addc_u32 s57, s57, 0
	s_cmp_gt_u32 s66, 61
	s_cbranch_scc0 .LBB0_1565
	s_and_b64 vcc, exec, s[24:25]
	s_cbranch_vccz .LBB0_1568
	s_barrier

.LBB0_2230:
	ds_read_b128 v[142:145], v154
	ds_read_b128 v[158:161], v154 offset:1024
	ds_read_b128 v[168:171], v154 offset:2048
	ds_read_b128 v[176:179], v154 offset:3072
	ds_read_b128 v[180:183], v155
	ds_read_b128 v[184:187], v155 offset:1024
	ds_read_b128 v[188:191], v155 offset:2048
	ds_read_b128 v[192:195], v155 offset:3072
	s_add_u32 s24, s22, 0xfff00080
	s_addc_u32 s25, s23, -1
	s_cmp_eq_u32 s48, 60
	s_cselect_b32 s27, s19, s25
	s_cselect_b32 s26, s44, s24
	s_cselect_b32 s25, s7, s47
	s_cselect_b32 s24, s45, s46
	s_mov_b32 m0, s40
	v_lshl_add_u64 v[146:147], s[22:23], 0, v[138:139]
	ds_read_b128 v[204:207], v156
	ds_read_b128 v[208:211], v156 offset:1024
	ds_read_b128 v[212:215], v156 offset:2048
	ds_read_b128 v[216:219], v156 offset:3072
	ds_read_b128 v[220:223], v156 offset:4096
	ds_read_b128 v[224:227], v156 offset:5120
	ds_read_b128 v[228:231], v156 offset:6144
	ds_read_b128 v[232:235], v156 offset:7168
	global_load_lds_dwordx4 v[146:147], off
	v_lshl_add_u64 v[146:147], s[22:23], 0, v[140:141]
	s_mov_b32 m0, s41
	s_nop 0
	global_load_lds_dwordx4 v[146:147], off
	s_waitcnt vmcnt(8)
	s_waitcnt lgkmcnt(0)
	s_barrier
	s_setprio 1
	s_waitcnt lgkmcnt(0)
	v_mfma_f32_16x16x32_bf16 v[126:129], v[142:145], v[204:207], v[126:129]
	v_mfma_f32_16x16x32_bf16 v[122:125], v[168:171], v[204:207], v[122:125]
	v_mfma_f32_16x16x32_bf16 v[118:121], v[180:183], v[204:207], v[118:121]
	v_mfma_f32_16x16x32_bf16 v[114:117], v[188:191], v[204:207], v[114:117]
	v_mfma_f32_16x16x32_bf16 v[114:117], v[192:195], v[208:211], v[114:117]
	v_mfma_f32_16x16x32_bf16 v[118:121], v[184:187], v[208:211], v[118:121]
	v_mfma_f32_16x16x32_bf16 v[122:125], v[176:179], v[208:211], v[122:125]
	v_mfma_f32_16x16x32_bf16 v[126:129], v[158:161], v[208:211], v[126:129]
	v_mfma_f32_16x16x32_bf16 v[110:113], v[158:161], v[216:219], v[110:113]
	v_mfma_f32_16x16x32_bf16 v[106:109], v[176:179], v[216:219], v[106:109]
	v_mfma_f32_16x16x32_bf16 v[102:105], v[184:187], v[216:219], v[102:105]
	v_mfma_f32_16x16x32_bf16 v[98:101], v[192:195], v[216:219], v[98:101]
	v_mfma_f32_16x16x32_bf16 v[98:101], v[188:191], v[212:215], v[98:101]
	v_mfma_f32_16x16x32_bf16 v[102:105], v[180:183], v[212:215], v[102:105]
	v_mfma_f32_16x16x32_bf16 v[106:109], v[168:171], v[212:215], v[106:109]
	v_mfma_f32_16x16x32_bf16 v[110:113], v[142:145], v[212:215], v[110:113]
	v_mfma_f32_16x16x32_bf16 v[94:97], v[142:145], v[220:223], v[94:97]
	v_mfma_f32_16x16x32_bf16 v[90:93], v[168:171], v[220:223], v[90:93]
	v_mfma_f32_16x16x32_bf16 v[86:89], v[180:183], v[220:223], v[86:89]
	v_mfma_f32_16x16x32_bf16 v[82:85], v[188:191], v[220:223], v[82:85]
	v_mfma_f32_16x16x32_bf16 v[82:85], v[192:195], v[224:227], v[82:85]
	v_mfma_f32_16x16x32_bf16 v[86:89], v[184:187], v[224:227], v[86:89]
	v_mfma_f32_16x16x32_bf16 v[90:93], v[176:179], v[224:227], v[90:93]
	v_mfma_f32_16x16x32_bf16 v[94:97], v[158:161], v[224:227], v[94:97]
	v_mfma_f32_16x16x32_bf16 v[78:81], v[158:161], v[232:235], v[78:81]
	v_mfma_f32_16x16x32_bf16 v[74:77], v[176:179], v[232:235], v[74:77]
	v_mfma_f32_16x16x32_bf16 v[70:73], v[184:187], v[232:235], v[70:73]
	v_mfma_f32_16x16x32_bf16 v[66:69], v[192:195], v[232:235], v[66:69]
	v_mfma_f32_16x16x32_bf16 v[66:69], v[188:191], v[228:231], v[66:69]
	v_mfma_f32_16x16x32_bf16 v[70:73], v[180:183], v[228:231], v[70:73]
	v_mfma_f32_16x16x32_bf16 v[74:77], v[168:171], v[228:231], v[74:77]
	v_mfma_f32_16x16x32_bf16 v[78:81], v[142:145], v[228:231], v[78:81]
	s_setprio 0
	s_barrier
	s_add_i32 s49, s38, s28
	v_lshl_add_u64 v[146:147], s[24:25], 0, v[132:133]
	s_mov_b32 m0, s49
	ds_read_b128 v[204:207], v156 offset:16384
	ds_read_b128 v[208:211], v156 offset:17408
	ds_read_b128 v[212:215], v156 offset:18432
	ds_read_b128 v[216:219], v156 offset:19456
	ds_read_b128 v[220:223], v156 offset:20480
	ds_read_b128 v[224:227], v156 offset:21504
	ds_read_b128 v[228:231], v156 offset:22528
	ds_read_b128 v[232:235], v156 offset:23552
	global_load_lds_dwordx4 v[146:147], off
	s_add_i32 m0, s49, 0x2000
	s_add_u32 s50, s24, 0x100000
	v_lshl_add_u64 v[172:173], s[24:25], 0, v[136:137]
	s_addc_u32 s51, s25, 0
	s_add_i32 s49, s39, s28
	global_load_lds_dwordx4 v[172:173], off
	v_lshl_add_u64 v[196:197], s[50:51], 0, v[132:133]
	s_mov_b32 m0, s49
	v_lshl_add_u64 v[236:237], s[26:27], 0, v[134:135]
	global_load_lds_dwordx4 v[196:197], off
	v_lshl_add_u64 v[196:197], s[50:51], 0, v[136:137]
	s_add_i32 m0, s49, 0x2000
	s_nop 0
	global_load_lds_dwordx4 v[196:197], off
	v_lshl_add_u64 v[196:197], s[26:27], 0, v[130:131]
	s_mov_b32 m0, s30
	s_nop 0
	global_load_lds_dwordx4 v[196:197], off
	s_mov_b32 m0, s31
	s_nop 0
	global_load_lds_dwordx4 v[236:237], off
	s_waitcnt vmcnt(8)
	s_waitcnt lgkmcnt(0)
	s_barrier
	s_setprio 1
	s_waitcnt lgkmcnt(0)
	v_mfma_f32_16x16x32_bf16 v[62:65], v[142:145], v[204:207], v[62:65]
	v_mfma_f32_16x16x32_bf16 v[58:61], v[168:171], v[204:207], v[58:61]
	v_mfma_f32_16x16x32_bf16 v[54:57], v[180:183], v[204:207], v[54:57]
	v_mfma_f32_16x16x32_bf16 v[50:53], v[188:191], v[204:207], v[50:53]
	v_mfma_f32_16x16x32_bf16 v[50:53], v[192:195], v[208:211], v[50:53]
	v_mfma_f32_16x16x32_bf16 v[54:57], v[184:187], v[208:211], v[54:57]
	v_mfma_f32_16x16x32_bf16 v[58:61], v[176:179], v[208:211], v[58:61]
	v_mfma_f32_16x16x32_bf16 v[62:65], v[158:161], v[208:211], v[62:65]
	v_mfma_f32_16x16x32_bf16 v[46:49], v[158:161], v[216:219], v[46:49]
	v_mfma_f32_16x16x32_bf16 v[42:45], v[176:179], v[216:219], v[42:45]
	v_mfma_f32_16x16x32_bf16 v[38:41], v[184:187], v[216:219], v[38:41]
	v_mfma_f32_16x16x32_bf16 v[34:37], v[192:195], v[216:219], v[34:37]
	v_mfma_f32_16x16x32_bf16 v[34:37], v[188:191], v[212:215], v[34:37]
	v_mfma_f32_16x16x32_bf16 v[38:41], v[180:183], v[212:215], v[38:41]
	v_mfma_f32_16x16x32_bf16 v[42:45], v[168:171], v[212:215], v[42:45]
	v_mfma_f32_16x16x32_bf16 v[46:49], v[142:145], v[212:215], v[46:49]
	v_mfma_f32_16x16x32_bf16 v[30:33], v[142:145], v[220:223], v[30:33]
	v_mfma_f32_16x16x32_bf16 v[26:29], v[168:171], v[220:223], v[26:29]
	v_mfma_f32_16x16x32_bf16 v[22:25], v[180:183], v[220:223], v[22:25]
	v_mfma_f32_16x16x32_bf16 v[18:21], v[188:191], v[220:223], v[18:21]
	v_mfma_f32_16x16x32_bf16 v[18:21], v[192:195], v[224:227], v[18:21]
	v_mfma_f32_16x16x32_bf16 v[22:25], v[184:187], v[224:227], v[22:25]
	v_mfma_f32_16x16x32_bf16 v[26:29], v[176:179], v[224:227], v[26:29]
	v_mfma_f32_16x16x32_bf16 v[30:33], v[158:161], v[224:227], v[30:33]
	v_mfma_f32_16x16x32_bf16 v[14:17], v[158:161], v[232:235], v[14:17]
	v_mfma_f32_16x16x32_bf16 v[10:13], v[176:179], v[232:235], v[10:13]
	v_mfma_f32_16x16x32_bf16 v[6:9], v[184:187], v[232:235], v[6:9]
	v_mfma_f32_16x16x32_bf16 v[2:5], v[192:195], v[232:235], v[2:5]
	v_mfma_f32_16x16x32_bf16 v[2:5], v[188:191], v[228:231], v[2:5]
	v_mfma_f32_16x16x32_bf16 v[6:9], v[180:183], v[228:231], v[6:9]
	v_mfma_f32_16x16x32_bf16 v[10:13], v[168:171], v[228:231], v[10:13]
	v_mfma_f32_16x16x32_bf16 v[14:17], v[142:145], v[228:231], v[14:17]
	s_setprio 0
	s_barrier
	s_add_i32 s49, 0, 0x18000
	v_add_u32_e32 v157, s49, v152
	s_add_i32 s50, 0, 0x1c000
	ds_read_b128 v[142:145], v157
	ds_read_b128 v[158:161], v157 offset:1024
	ds_read_b128 v[168:171], v157 offset:2048
	ds_read_b128 v[176:179], v157 offset:3072
	v_add_u32_e32 v157, s50, v152
	ds_read_b128 v[180:183], v157
	ds_read_b128 v[184:187], v157 offset:1024
	ds_read_b128 v[188:191], v157 offset:2048
	ds_read_b128 v[192:195], v157 offset:3072
	s_add_u32 s26, s26, 0x100000
	s_addc_u32 s27, s27, 0
	s_mov_b32 m0, s33
	v_lshl_add_u64 v[238:239], s[26:27], 0, v[130:131]
	ds_read_b128 v[204:207], v156 offset:32768
	ds_read_b128 v[208:211], v156 offset:33792
	ds_read_b128 v[212:215], v156 offset:34816
	ds_read_b128 v[216:219], v156 offset:35840
	ds_read_b128 v[220:223], v156 offset:36864
	ds_read_b128 v[224:227], v156 offset:37888
	ds_read_b128 v[228:231], v156 offset:38912
	ds_read_b128 v[232:235], v156 offset:39936
	global_load_lds_dwordx4 v[238:239], off
	v_lshl_add_u64 v[238:239], s[26:27], 0, v[134:135]
	s_mov_b32 m0, s34
	s_nop 0
	global_load_lds_dwordx4 v[238:239], off
	s_waitcnt vmcnt(8)
	s_waitcnt lgkmcnt(0)
	s_barrier
	s_setprio 1
	s_waitcnt lgkmcnt(0)
	v_mfma_f32_16x16x32_bf16 v[126:129], v[142:145], v[204:207], v[126:129]
	v_mfma_f32_16x16x32_bf16 v[122:125], v[168:171], v[204:207], v[122:125]
	v_mfma_f32_16x16x32_bf16 v[118:121], v[180:183], v[204:207], v[118:121]
	v_mfma_f32_16x16x32_bf16 v[114:117], v[188:191], v[204:207], v[114:117]
	v_mfma_f32_16x16x32_bf16 v[114:117], v[192:195], v[208:211], v[114:117]
	v_mfma_f32_16x16x32_bf16 v[118:121], v[184:187], v[208:211], v[118:121]
	v_mfma_f32_16x16x32_bf16 v[122:125], v[176:179], v[208:211], v[122:125]
	v_mfma_f32_16x16x32_bf16 v[126:129], v[158:161], v[208:211], v[126:129]
	v_mfma_f32_16x16x32_bf16 v[110:113], v[158:161], v[216:219], v[110:113]
	v_mfma_f32_16x16x32_bf16 v[106:109], v[176:179], v[216:219], v[106:109]
	v_mfma_f32_16x16x32_bf16 v[102:105], v[184:187], v[216:219], v[102:105]
	v_mfma_f32_16x16x32_bf16 v[98:101], v[192:195], v[216:219], v[98:101]
	v_mfma_f32_16x16x32_bf16 v[98:101], v[188:191], v[212:215], v[98:101]
	v_mfma_f32_16x16x32_bf16 v[102:105], v[180:183], v[212:215], v[102:105]
	v_mfma_f32_16x16x32_bf16 v[106:109], v[168:171], v[212:215], v[106:109]
	v_mfma_f32_16x16x32_bf16 v[110:113], v[142:145], v[212:215], v[110:113]
	v_mfma_f32_16x16x32_bf16 v[94:97], v[142:145], v[220:223], v[94:97]
	v_mfma_f32_16x16x32_bf16 v[90:93], v[168:171], v[220:223], v[90:93]
	v_mfma_f32_16x16x32_bf16 v[86:89], v[180:183], v[220:223], v[86:89]
	v_mfma_f32_16x16x32_bf16 v[82:85], v[188:191], v[220:223], v[82:85]
	v_mfma_f32_16x16x32_bf16 v[82:85], v[192:195], v[224:227], v[82:85]
	v_mfma_f32_16x16x32_bf16 v[86:89], v[184:187], v[224:227], v[86:89]
	v_mfma_f32_16x16x32_bf16 v[90:93], v[176:179], v[224:227], v[90:93]
	v_mfma_f32_16x16x32_bf16 v[94:97], v[158:161], v[224:227], v[94:97]
	v_mfma_f32_16x16x32_bf16 v[78:81], v[158:161], v[232:235], v[78:81]
	v_mfma_f32_16x16x32_bf16 v[74:77], v[176:179], v[232:235], v[74:77]
	v_mfma_f32_16x16x32_bf16 v[70:73], v[184:187], v[232:235], v[70:73]
	v_mfma_f32_16x16x32_bf16 v[66:69], v[192:195], v[232:235], v[66:69]
	v_mfma_f32_16x16x32_bf16 v[66:69], v[188:191], v[228:231], v[66:69]
	v_mfma_f32_16x16x32_bf16 v[70:73], v[180:183], v[228:231], v[70:73]
	v_mfma_f32_16x16x32_bf16 v[74:77], v[168:171], v[228:231], v[74:77]
	v_mfma_f32_16x16x32_bf16 v[78:81], v[142:145], v[228:231], v[78:81]
	s_setprio 0
	s_barrier
	s_add_i32 s26, s49, s28
	v_lshl_add_u64 v[146:147], v[146:147], 0, s[14:15]
	s_mov_b32 m0, s26
	ds_read_b128 v[204:207], v156 offset:49152
	ds_read_b128 v[208:211], v156 offset:50176
	ds_read_b128 v[212:215], v156 offset:51200
	ds_read_b128 v[216:219], v156 offset:52224
	ds_read_b128 v[220:223], v156 offset:53248
	ds_read_b128 v[224:227], v156 offset:54272
	ds_read_b128 v[228:231], v156 offset:55296
	ds_read_b128 v[232:235], v156 offset:56320
	global_load_lds_dwordx4 v[146:147], off
	s_add_i32 m0, s26, 0x2000
	s_add_u32 s24, s24, 0x100080
	v_lshl_add_u64 v[146:147], v[172:173], 0, s[14:15]
	s_addc_u32 s25, s25, 0
	s_add_i32 s26, s50, s28
	global_load_lds_dwordx4 v[146:147], off
	v_lshl_add_u64 v[146:147], s[24:25], 0, v[132:133]
	s_mov_b32 m0, s26
	s_nop 0
	global_load_lds_dwordx4 v[146:147], off
	v_lshl_add_u64 v[146:147], s[24:25], 0, v[136:137]
	s_add_i32 m0, s26, 0x2000
	s_nop 0
	global_load_lds_dwordx4 v[146:147], off
	v_lshl_add_u64 v[146:147], v[196:197], 0, s[14:15]
	s_mov_b32 m0, s36
	s_nop 0
	global_load_lds_dwordx4 v[146:147], off
	v_lshl_add_u64 v[146:147], v[236:237], 0, s[14:15]
	s_mov_b32 m0, s37
	s_nop 0
	global_load_lds_dwordx4 v[146:147], off
	s_waitcnt vmcnt(8)
	s_waitcnt lgkmcnt(0)
	s_barrier
	s_setprio 1
	s_waitcnt lgkmcnt(0)
	v_mfma_f32_16x16x32_bf16 v[62:65], v[142:145], v[204:207], v[62:65]
	v_mfma_f32_16x16x32_bf16 v[58:61], v[168:171], v[204:207], v[58:61]
	v_mfma_f32_16x16x32_bf16 v[54:57], v[180:183], v[204:207], v[54:57]
	v_mfma_f32_16x16x32_bf16 v[50:53], v[188:191], v[204:207], v[50:53]
	v_mfma_f32_16x16x32_bf16 v[50:53], v[192:195], v[208:211], v[50:53]
	v_mfma_f32_16x16x32_bf16 v[54:57], v[184:187], v[208:211], v[54:57]
	v_mfma_f32_16x16x32_bf16 v[58:61], v[176:179], v[208:211], v[58:61]
	v_mfma_f32_16x16x32_bf16 v[62:65], v[158:161], v[208:211], v[62:65]
	v_mfma_f32_16x16x32_bf16 v[46:49], v[158:161], v[216:219], v[46:49]
	v_mfma_f32_16x16x32_bf16 v[42:45], v[176:179], v[216:219], v[42:45]
	v_mfma_f32_16x16x32_bf16 v[38:41], v[184:187], v[216:219], v[38:41]
	v_mfma_f32_16x16x32_bf16 v[34:37], v[192:195], v[216:219], v[34:37]
	v_mfma_f32_16x16x32_bf16 v[34:37], v[188:191], v[212:215], v[34:37]
	v_mfma_f32_16x16x32_bf16 v[38:41], v[180:183], v[212:215], v[38:41]
	v_mfma_f32_16x16x32_bf16 v[42:45], v[168:171], v[212:215], v[42:45]
	v_mfma_f32_16x16x32_bf16 v[46:49], v[142:145], v[212:215], v[46:49]
	v_mfma_f32_16x16x32_bf16 v[30:33], v[142:145], v[220:223], v[30:33]
	v_mfma_f32_16x16x32_bf16 v[26:29], v[168:171], v[220:223], v[26:29]
	v_mfma_f32_16x16x32_bf16 v[22:25], v[180:183], v[220:223], v[22:25]
	v_mfma_f32_16x16x32_bf16 v[18:21], v[188:191], v[220:223], v[18:21]
	v_mfma_f32_16x16x32_bf16 v[18:21], v[192:195], v[224:227], v[18:21]
	v_mfma_f32_16x16x32_bf16 v[22:25], v[184:187], v[224:227], v[22:25]
	v_mfma_f32_16x16x32_bf16 v[26:29], v[176:179], v[224:227], v[26:29]
	v_mfma_f32_16x16x32_bf16 v[30:33], v[158:161], v[224:227], v[30:33]
	v_mfma_f32_16x16x32_bf16 v[14:17], v[158:161], v[232:235], v[14:17]
	v_mfma_f32_16x16x32_bf16 v[10:13], v[176:179], v[232:235], v[10:13]
	v_mfma_f32_16x16x32_bf16 v[6:9], v[184:187], v[232:235], v[6:9]
	v_mfma_f32_16x16x32_bf16 v[2:5], v[192:195], v[232:235], v[2:5]
	v_mfma_f32_16x16x32_bf16 v[2:5], v[188:191], v[228:231], v[2:5]
	v_mfma_f32_16x16x32_bf16 v[6:9], v[180:183], v[228:231], v[6:9]
	v_mfma_f32_16x16x32_bf16 v[10:13], v[168:171], v[228:231], v[10:13]
	v_mfma_f32_16x16x32_bf16 v[14:17], v[142:145], v[228:231], v[14:17]
	s_setprio 0
	s_barrier
	s_add_i32 s48, s48, 2
	s_add_u32 s22, s22, 0x100
	s_addc_u32 s23, s23, 0
	s_add_u32 s46, s46, 0x100
	s_addc_u32 s47, s47, 0
	s_cmp_gt_u32 s48, 61
	s_cbranch_scc0 .LBB0_2230
	s_and_b64 vcc, exec, s[16:17]
	s_cbranch_vccz .LBB0_2233
	s_barrier

.LBB0_2240:
	s_add_i32 s20, s24, 0x100
	s_and_b64 s[18:19], s[18:19], exec
	s_cselect_b32 s19, 0, s20
	s_cselect_b32 s18, 0, 0
	s_add_u32 s20, s8, s19
	ds_read_b128 v[144:147], v139
	ds_read_b128 v[150:153], v139 offset:1024
	ds_read_b128 v[154:157], v139 offset:2048
	ds_read_b128 v[158:161], v139 offset:3072
	ds_read_b128 v[168:171], v140
	ds_read_b128 v[176:179], v140 offset:1024
	ds_read_b128 v[180:183], v140 offset:2048
	ds_read_b128 v[184:187], v140 offset:3072
	s_addc_u32 s21, s9, s18
	s_add_u32 s22, s10, s19
	s_addc_u32 s23, s11, s18
	s_add_u32 s28, s12, s24
	s_addc_u32 s29, s13, 0
	s_add_u32 s24, s22, 0x100000
	s_addc_u32 s25, s23, 0
	s_add_u32 s18, s20, 0x100000
	s_addc_u32 s19, s21, 0
	s_add_u32 s26, s22, 0x100080
	s_addc_u32 s27, s23, 0
	v_lshl_add_u64 v[172:173], s[28:29], 0, v[130:131]
	s_mov_b32 m0, s38
	v_lshl_add_u64 v[172:173], v[172:173], 0, s[14:15]
	ds_read_b128 v[188:191], v141
	ds_read_b128 v[192:195], v141 offset:1024
	ds_read_b128 v[204:207], v141 offset:2048
	ds_read_b128 v[208:211], v141 offset:3072
	ds_read_b128 v[212:215], v141 offset:4096
	ds_read_b128 v[216:219], v141 offset:5120
	ds_read_b128 v[220:223], v141 offset:6144
	ds_read_b128 v[224:227], v141 offset:7168
	global_load_lds_dwordx4 v[172:173], off
	v_lshl_add_u64 v[172:173], s[28:29], 0, v[134:135]
	v_lshl_add_u64 v[172:173], v[172:173], 0, s[14:15]
	s_mov_b32 m0, s39
	s_nop 0
	global_load_lds_dwordx4 v[172:173], off
	s_waitcnt vmcnt(8)
	s_waitcnt lgkmcnt(0)
	s_barrier
	s_setprio 1
	s_waitcnt lgkmcnt(0)
	v_mfma_f32_16x16x32_bf16 v[126:129], v[144:147], v[188:191], v[126:129]
	v_mfma_f32_16x16x32_bf16 v[122:125], v[154:157], v[188:191], v[122:125]
	v_mfma_f32_16x16x32_bf16 v[110:113], v[168:171], v[188:191], v[110:113]
	v_mfma_f32_16x16x32_bf16 v[106:109], v[180:183], v[188:191], v[106:109]
	v_mfma_f32_16x16x32_bf16 v[106:109], v[184:187], v[192:195], v[106:109]
	v_mfma_f32_16x16x32_bf16 v[110:113], v[176:179], v[192:195], v[110:113]
	v_mfma_f32_16x16x32_bf16 v[122:125], v[158:161], v[192:195], v[122:125]
	v_mfma_f32_16x16x32_bf16 v[126:129], v[150:153], v[192:195], v[126:129]
	v_mfma_f32_16x16x32_bf16 v[118:121], v[150:153], v[208:211], v[118:121]
	v_mfma_f32_16x16x32_bf16 v[114:117], v[158:161], v[208:211], v[114:117]
	v_mfma_f32_16x16x32_bf16 v[94:97], v[176:179], v[208:211], v[94:97]
	v_mfma_f32_16x16x32_bf16 v[90:93], v[184:187], v[208:211], v[90:93]
	v_mfma_f32_16x16x32_bf16 v[90:93], v[180:183], v[204:207], v[90:93]
	v_mfma_f32_16x16x32_bf16 v[94:97], v[168:171], v[204:207], v[94:97]
	v_mfma_f32_16x16x32_bf16 v[114:117], v[154:157], v[204:207], v[114:117]
	v_mfma_f32_16x16x32_bf16 v[118:121], v[144:147], v[204:207], v[118:121]
	v_mfma_f32_16x16x32_bf16 v[102:105], v[144:147], v[212:215], v[102:105]
	v_mfma_f32_16x16x32_bf16 v[98:101], v[154:157], v[212:215], v[98:101]
	v_mfma_f32_16x16x32_bf16 v[78:81], v[168:171], v[212:215], v[78:81]
	v_mfma_f32_16x16x32_bf16 v[74:77], v[180:183], v[212:215], v[74:77]
	v_mfma_f32_16x16x32_bf16 v[74:77], v[184:187], v[216:219], v[74:77]
	v_mfma_f32_16x16x32_bf16 v[78:81], v[176:179], v[216:219], v[78:81]
	v_mfma_f32_16x16x32_bf16 v[98:101], v[158:161], v[216:219], v[98:101]
	v_mfma_f32_16x16x32_bf16 v[102:105], v[150:153], v[216:219], v[102:105]
	v_mfma_f32_16x16x32_bf16 v[86:89], v[150:153], v[224:227], v[86:89]
	v_mfma_f32_16x16x32_bf16 v[82:85], v[158:161], v[224:227], v[82:85]
	v_mfma_f32_16x16x32_bf16 v[70:73], v[176:179], v[224:227], v[70:73]
	v_mfma_f32_16x16x32_bf16 v[66:69], v[184:187], v[224:227], v[66:69]
	v_mfma_f32_16x16x32_bf16 v[66:69], v[180:183], v[220:223], v[66:69]
	v_mfma_f32_16x16x32_bf16 v[70:73], v[168:171], v[220:223], v[70:73]
	v_mfma_f32_16x16x32_bf16 v[82:85], v[154:157], v[220:223], v[82:85]
	v_mfma_f32_16x16x32_bf16 v[86:89], v[144:147], v[220:223], v[86:89]
	s_setprio 0
	s_barrier
	s_mov_b32 m0, s40
	v_lshl_add_u64 v[172:173], s[22:23], 0, v[132:133]
	ds_read_b128 v[188:191], v141 offset:16384
	ds_read_b128 v[192:195], v141 offset:17408
	ds_read_b128 v[204:207], v141 offset:18432
	ds_read_b128 v[208:211], v141 offset:19456
	ds_read_b128 v[212:215], v141 offset:20480
	ds_read_b128 v[216:219], v141 offset:21504
	ds_read_b128 v[220:223], v141 offset:22528
	ds_read_b128 v[224:227], v141 offset:23552
	global_load_lds_dwordx4 v[172:173], off
	v_lshl_add_u64 v[196:197], s[22:23], 0, v[136:137]
	s_mov_b32 m0, s41
	v_lshl_add_u64 v[228:229], s[24:25], 0, v[132:133]
	global_load_lds_dwordx4 v[196:197], off
	s_mov_b32 m0, s42
	v_lshl_add_u64 v[230:231], s[20:21], 0, v[134:135]
	global_load_lds_dwordx4 v[228:229], off
	v_lshl_add_u64 v[228:229], s[24:25], 0, v[136:137]
	s_mov_b32 m0, s43
	s_nop 0
	global_load_lds_dwordx4 v[228:229], off
	v_lshl_add_u64 v[228:229], s[20:21], 0, v[130:131]
	s_mov_b32 m0, s7
	s_nop 0
	global_load_lds_dwordx4 v[228:229], off
	s_mov_b32 m0, s31
	s_nop 0
	global_load_lds_dwordx4 v[230:231], off
	s_waitcnt vmcnt(8)
	s_waitcnt lgkmcnt(0)
	s_barrier
	s_setprio 1
	s_waitcnt lgkmcnt(0)
	v_mfma_f32_16x16x32_bf16 v[62:65], v[144:147], v[188:191], v[62:65]
	v_mfma_f32_16x16x32_bf16 v[58:61], v[154:157], v[188:191], v[58:61]
	v_mfma_f32_16x16x32_bf16 v[46:49], v[168:171], v[188:191], v[46:49]
	v_mfma_f32_16x16x32_bf16 v[42:45], v[180:183], v[188:191], v[42:45]
	v_mfma_f32_16x16x32_bf16 v[42:45], v[184:187], v[192:195], v[42:45]
	v_mfma_f32_16x16x32_bf16 v[46:49], v[176:179], v[192:195], v[46:49]
	v_mfma_f32_16x16x32_bf16 v[58:61], v[158:161], v[192:195], v[58:61]
	v_mfma_f32_16x16x32_bf16 v[62:65], v[150:153], v[192:195], v[62:65]
	v_mfma_f32_16x16x32_bf16 v[54:57], v[150:153], v[208:211], v[54:57]
	v_mfma_f32_16x16x32_bf16 v[50:53], v[158:161], v[208:211], v[50:53]
	v_mfma_f32_16x16x32_bf16 v[30:33], v[176:179], v[208:211], v[30:33]
	v_mfma_f32_16x16x32_bf16 v[26:29], v[184:187], v[208:211], v[26:29]
	v_mfma_f32_16x16x32_bf16 v[26:29], v[180:183], v[204:207], v[26:29]
	v_mfma_f32_16x16x32_bf16 v[30:33], v[168:171], v[204:207], v[30:33]
	v_mfma_f32_16x16x32_bf16 v[50:53], v[154:157], v[204:207], v[50:53]
	v_mfma_f32_16x16x32_bf16 v[54:57], v[144:147], v[204:207], v[54:57]
	v_mfma_f32_16x16x32_bf16 v[38:41], v[144:147], v[212:215], v[38:41]
	v_mfma_f32_16x16x32_bf16 v[34:37], v[154:157], v[212:215], v[34:37]
	v_mfma_f32_16x16x32_bf16 v[14:17], v[168:171], v[212:215], v[14:17]
	v_mfma_f32_16x16x32_bf16 v[10:13], v[180:183], v[212:215], v[10:13]
	v_mfma_f32_16x16x32_bf16 v[10:13], v[184:187], v[216:219], v[10:13]
	v_mfma_f32_16x16x32_bf16 v[14:17], v[176:179], v[216:219], v[14:17]
	v_mfma_f32_16x16x32_bf16 v[34:37], v[158:161], v[216:219], v[34:37]
	v_mfma_f32_16x16x32_bf16 v[38:41], v[150:153], v[216:219], v[38:41]
	v_mfma_f32_16x16x32_bf16 v[22:25], v[150:153], v[224:227], v[22:25]
	v_mfma_f32_16x16x32_bf16 v[18:21], v[158:161], v[224:227], v[18:21]
	v_mfma_f32_16x16x32_bf16 v[6:9], v[176:179], v[224:227], v[6:9]
	v_mfma_f32_16x16x32_bf16 v[2:5], v[184:187], v[224:227], v[2:5]
	v_mfma_f32_16x16x32_bf16 v[2:5], v[180:183], v[220:223], v[2:5]
	v_mfma_f32_16x16x32_bf16 v[6:9], v[168:171], v[220:223], v[6:9]
	v_mfma_f32_16x16x32_bf16 v[18:21], v[154:157], v[220:223], v[18:21]
	v_mfma_f32_16x16x32_bf16 v[22:25], v[144:147], v[220:223], v[22:25]
	s_setprio 0
	s_barrier
	ds_read_b128 v[144:147], v142
	ds_read_b128 v[150:153], v142 offset:1024
	ds_read_b128 v[154:157], v142 offset:2048
	ds_read_b128 v[158:161], v142 offset:3072
	ds_read_b128 v[168:171], v143
	ds_read_b128 v[176:179], v143 offset:1024
	ds_read_b128 v[180:183], v143 offset:2048
	ds_read_b128 v[184:187], v143 offset:3072
	s_mov_b32 m0, s33
	v_lshl_add_u64 v[232:233], s[18:19], 0, v[130:131]
	ds_read_b128 v[188:191], v141 offset:32768
	ds_read_b128 v[192:195], v141 offset:33792
	ds_read_b128 v[204:207], v141 offset:34816
	ds_read_b128 v[208:211], v141 offset:35840
	ds_read_b128 v[212:215], v141 offset:36864
	ds_read_b128 v[216:219], v141 offset:37888
	ds_read_b128 v[220:223], v141 offset:38912
	ds_read_b128 v[224:227], v141 offset:39936
	global_load_lds_dwordx4 v[232:233], off
	v_lshl_add_u64 v[232:233], s[18:19], 0, v[134:135]
	s_mov_b32 m0, s34
	s_nop 0
	global_load_lds_dwordx4 v[232:233], off
	s_waitcnt vmcnt(8)
	s_waitcnt lgkmcnt(0)
	s_barrier
	s_setprio 1
	s_waitcnt lgkmcnt(0)
	v_mfma_f32_16x16x32_bf16 v[126:129], v[144:147], v[188:191], v[126:129]
	v_mfma_f32_16x16x32_bf16 v[122:125], v[154:157], v[188:191], v[122:125]
	v_mfma_f32_16x16x32_bf16 v[110:113], v[168:171], v[188:191], v[110:113]
	v_mfma_f32_16x16x32_bf16 v[106:109], v[180:183], v[188:191], v[106:109]
	v_mfma_f32_16x16x32_bf16 v[106:109], v[184:187], v[192:195], v[106:109]
	v_mfma_f32_16x16x32_bf16 v[110:113], v[176:179], v[192:195], v[110:113]
	v_mfma_f32_16x16x32_bf16 v[122:125], v[158:161], v[192:195], v[122:125]
	v_mfma_f32_16x16x32_bf16 v[126:129], v[150:153], v[192:195], v[126:129]
	v_mfma_f32_16x16x32_bf16 v[118:121], v[150:153], v[208:211], v[118:121]
	v_mfma_f32_16x16x32_bf16 v[114:117], v[158:161], v[208:211], v[114:117]
	v_mfma_f32_16x16x32_bf16 v[94:97], v[176:179], v[208:211], v[94:97]
	v_mfma_f32_16x16x32_bf16 v[90:93], v[184:187], v[208:211], v[90:93]
	v_mfma_f32_16x16x32_bf16 v[90:93], v[180:183], v[204:207], v[90:93]
	v_mfma_f32_16x16x32_bf16 v[94:97], v[168:171], v[204:207], v[94:97]
	v_mfma_f32_16x16x32_bf16 v[114:117], v[154:157], v[204:207], v[114:117]
	v_mfma_f32_16x16x32_bf16 v[118:121], v[144:147], v[204:207], v[118:121]
	v_mfma_f32_16x16x32_bf16 v[102:105], v[144:147], v[212:215], v[102:105]
	v_mfma_f32_16x16x32_bf16 v[98:101], v[154:157], v[212:215], v[98:101]
	v_mfma_f32_16x16x32_bf16 v[78:81], v[168:171], v[212:215], v[78:81]
	v_mfma_f32_16x16x32_bf16 v[74:77], v[180:183], v[212:215], v[74:77]
	v_mfma_f32_16x16x32_bf16 v[74:77], v[184:187], v[216:219], v[74:77]
	v_mfma_f32_16x16x32_bf16 v[78:81], v[176:179], v[216:219], v[78:81]
	v_mfma_f32_16x16x32_bf16 v[98:101], v[158:161], v[216:219], v[98:101]
	v_mfma_f32_16x16x32_bf16 v[102:105], v[150:153], v[216:219], v[102:105]
	v_mfma_f32_16x16x32_bf16 v[86:89], v[150:153], v[224:227], v[86:89]
	v_mfma_f32_16x16x32_bf16 v[82:85], v[158:161], v[224:227], v[82:85]
	v_mfma_f32_16x16x32_bf16 v[70:73], v[176:179], v[224:227], v[70:73]
	v_mfma_f32_16x16x32_bf16 v[66:69], v[184:187], v[224:227], v[66:69]
	v_mfma_f32_16x16x32_bf16 v[66:69], v[180:183], v[220:223], v[66:69]
	v_mfma_f32_16x16x32_bf16 v[70:73], v[168:171], v[220:223], v[70:73]
	v_mfma_f32_16x16x32_bf16 v[82:85], v[154:157], v[220:223], v[82:85]
	v_mfma_f32_16x16x32_bf16 v[86:89], v[144:147], v[220:223], v[86:89]
	s_setprio 0
	s_barrier
	s_mov_b32 m0, s44
	v_lshl_add_u64 v[172:173], v[172:173], 0, s[14:15]
	ds_read_b128 v[188:191], v141 offset:49152
	ds_read_b128 v[192:195], v141 offset:50176
	ds_read_b128 v[204:207], v141 offset:51200
	ds_read_b128 v[208:211], v141 offset:52224
	ds_read_b128 v[212:215], v141 offset:53248
	ds_read_b128 v[216:219], v141 offset:54272
	ds_read_b128 v[220:223], v141 offset:55296
	ds_read_b128 v[224:227], v141 offset:56320
	global_load_lds_dwordx4 v[172:173], off
	v_lshl_add_u64 v[172:173], v[196:197], 0, s[14:15]
	s_mov_b32 m0, s45
	s_nop 0
	global_load_lds_dwordx4 v[172:173], off
	v_lshl_add_u64 v[172:173], s[26:27], 0, v[132:133]
	s_mov_b32 m0, s46
	s_nop 0
	global_load_lds_dwordx4 v[172:173], off
	v_lshl_add_u64 v[172:173], s[26:27], 0, v[136:137]
	s_mov_b32 m0, s47
	s_nop 0
	global_load_lds_dwordx4 v[172:173], off
	v_lshl_add_u64 v[172:173], v[228:229], 0, s[14:15]
	s_mov_b32 m0, s36
	s_nop 0
	global_load_lds_dwordx4 v[172:173], off
	v_lshl_add_u64 v[172:173], v[230:231], 0, s[14:15]
	s_mov_b32 m0, s37
	s_nop 0
	global_load_lds_dwordx4 v[172:173], off
	s_waitcnt vmcnt(8)
	s_waitcnt lgkmcnt(0)
	s_barrier
	s_setprio 1
	s_waitcnt lgkmcnt(0)
	v_mfma_f32_16x16x32_bf16 v[62:65], v[144:147], v[188:191], v[62:65]
	v_mfma_f32_16x16x32_bf16 v[58:61], v[154:157], v[188:191], v[58:61]
	v_mfma_f32_16x16x32_bf16 v[46:49], v[168:171], v[188:191], v[46:49]
	v_mfma_f32_16x16x32_bf16 v[42:45], v[180:183], v[188:191], v[42:45]
	v_mfma_f32_16x16x32_bf16 v[42:45], v[184:187], v[192:195], v[42:45]
	v_mfma_f32_16x16x32_bf16 v[46:49], v[176:179], v[192:195], v[46:49]
	v_mfma_f32_16x16x32_bf16 v[58:61], v[158:161], v[192:195], v[58:61]
	v_mfma_f32_16x16x32_bf16 v[62:65], v[150:153], v[192:195], v[62:65]
	v_mfma_f32_16x16x32_bf16 v[54:57], v[150:153], v[208:211], v[54:57]
	v_mfma_f32_16x16x32_bf16 v[50:53], v[158:161], v[208:211], v[50:53]
	v_mfma_f32_16x16x32_bf16 v[30:33], v[176:179], v[208:211], v[30:33]
	v_mfma_f32_16x16x32_bf16 v[26:29], v[184:187], v[208:211], v[26:29]
	v_mfma_f32_16x16x32_bf16 v[26:29], v[180:183], v[204:207], v[26:29]
	v_mfma_f32_16x16x32_bf16 v[30:33], v[168:171], v[204:207], v[30:33]
	v_mfma_f32_16x16x32_bf16 v[50:53], v[154:157], v[204:207], v[50:53]
	v_mfma_f32_16x16x32_bf16 v[54:57], v[144:147], v[204:207], v[54:57]
	v_mfma_f32_16x16x32_bf16 v[38:41], v[144:147], v[212:215], v[38:41]
	v_mfma_f32_16x16x32_bf16 v[34:37], v[154:157], v[212:215], v[34:37]
	v_mfma_f32_16x16x32_bf16 v[14:17], v[168:171], v[212:215], v[14:17]
	v_mfma_f32_16x16x32_bf16 v[10:13], v[180:183], v[212:215], v[10:13]
	v_mfma_f32_16x16x32_bf16 v[10:13], v[184:187], v[216:219], v[10:13]
	v_mfma_f32_16x16x32_bf16 v[14:17], v[176:179], v[216:219], v[14:17]
	v_mfma_f32_16x16x32_bf16 v[34:37], v[158:161], v[216:219], v[34:37]
	v_mfma_f32_16x16x32_bf16 v[38:41], v[150:153], v[216:219], v[38:41]
	v_mfma_f32_16x16x32_bf16 v[22:25], v[150:153], v[224:227], v[22:25]
	v_mfma_f32_16x16x32_bf16 v[18:21], v[158:161], v[224:227], v[18:21]
	v_mfma_f32_16x16x32_bf16 v[6:9], v[176:179], v[224:227], v[6:9]
	v_mfma_f32_16x16x32_bf16 v[2:5], v[184:187], v[224:227], v[2:5]
	v_mfma_f32_16x16x32_bf16 v[2:5], v[180:183], v[220:223], v[2:5]
	v_mfma_f32_16x16x32_bf16 v[6:9], v[168:171], v[220:223], v[6:9]
	v_mfma_f32_16x16x32_bf16 v[18:21], v[154:157], v[220:223], v[18:21]
	v_mfma_f32_16x16x32_bf16 v[22:25], v[144:147], v[220:223], v[22:25]
	s_setprio 0
	s_barrier
	s_andn2_b64 vcc, exec, s[16:17]
	s_mov_b64 s[18:19], -1
	s_mov_b64 s[16:17], 0
	s_movk_i32 s24, 0x100
	s_cbranch_vccz .LBB0_2240
	s_lshl_b32 s7, s30, 21
	v_readlane_b32 s0, v249, 29
	v_lshl_or_b32 v130, s6, 8, v148
	v_mov_b32_e32 v139, 0
	s_add_u32 s8, s0, s7
	v_readlane_b32 s0, v249, 31
	v_or_b32_e32 v130, s35, v130
	v_cvt_pk_bf16_f32 v70, v70, v71
	v_cvt_pk_bf16_f32 v71, v72, v73
	v_cvt_pk_bf16_f32 v72, v66, v67
	v_add_u32_e32 v66, 0x80, v138
	v_mov_b32_e32 v67, v139
	s_addc_u32 s9, s0, 0
	v_ashrrev_i32_e32 v131, 31, v130
	v_lshlrev_b64 v[132:133], 13, v[138:139]
	v_cvt_pk_bf16_f32 v110, v110, v111
	v_cvt_pk_bf16_f32 v111, v112, v113
	v_cvt_pk_bf16_f32 v112, v106, v107
	v_or_b32_e32 v106, 16, v138
	v_mov_b32_e32 v107, v139
	v_lshlrev_b64 v[66:67], 13, v[66:67]
	v_cvt_pk_bf16_f32 v46, v46, v47
	v_cvt_pk_bf16_f32 v47, v48, v49
	v_cvt_pk_bf16_f32 v48, v42, v43
	v_add_u32_e32 v42, 0x90, v138
	v_mov_b32_e32 v43, v139
	v_lshl_add_u64 v[132:133], s[8:9], 0, v[132:133]
	v_lshlrev_b64 v[130:131], 1, v[130:131]
	v_lshlrev_b64 v[106:107], 13, v[106:107]
	v_cvt_pk_bf16_f32 v94, v94, v95
	v_cvt_pk_bf16_f32 v95, v96, v97
	v_cvt_pk_bf16_f32 v96, v90, v91
	v_or_b32_e32 v90, 32, v138
	v_mov_b32_e32 v91, v139
	v_lshl_add_u64 v[66:67], s[8:9], 0, v[66:67]
	v_lshlrev_b64 v[42:43], 13, v[42:43]
	v_cvt_pk_bf16_f32 v30, v30, v31
	v_cvt_pk_bf16_f32 v31, v32, v33
	v_cvt_pk_bf16_f32 v32, v26, v27
	v_add_u32_e32 v26, 0xa0, v138
	v_mov_b32_e32 v27, v139
	v_lshl_add_u64 v[132:133], v[132:133], 0, v[130:131]
	v_cvt_pk_bf16_f32 v113, v108, v109
	v_lshl_add_u64 v[106:107], s[8:9], 0, v[106:107]
	v_lshlrev_b64 v[90:91], 13, v[90:91]
	v_cvt_pk_bf16_f32 v78, v78, v79
	v_cvt_pk_bf16_f32 v79, v80, v81
	v_cvt_pk_bf16_f32 v80, v74, v75
	v_or_b32_e32 v74, 48, v138
	v_mov_b32_e32 v75, v139
	v_lshl_add_u64 v[66:67], v[66:67], 0, v[130:131]
	v_cvt_pk_bf16_f32 v49, v44, v45
	v_lshl_add_u64 v[42:43], s[8:9], 0, v[42:43]
	v_lshlrev_b64 v[26:27], 13, v[26:27]
	v_add_u32_e32 v138, 0xb0, v138
	global_store_dwordx4 v[132:133], v[110:113], off offset:256
	v_cvt_pk_bf16_f32 v97, v92, v93
	v_lshl_add_u64 v[90:91], s[8:9], 0, v[90:91]
	v_lshl_add_u64 v[110:111], v[106:107], 0, v[130:131]
	v_lshlrev_b64 v[74:75], 13, v[74:75]
	global_store_dwordx4 v[66:67], v[46:49], off offset:256
	v_cvt_pk_bf16_f32 v33, v28, v29
	v_lshl_add_u64 v[26:27], s[8:9], 0, v[26:27]
	v_lshl_add_u64 v[46:47], v[42:43], 0, v[130:131]
	v_cvt_pk_bf16_f32 v14, v14, v15
	v_cvt_pk_bf16_f32 v15, v16, v17
	v_cvt_pk_bf16_f32 v16, v10, v11
	v_lshlrev_b64 v[10:11], 13, v[138:139]
	global_store_dwordx4 v[110:111], v[94:97], off offset:256
	v_cvt_pk_bf16_f32 v81, v76, v77
	v_lshl_add_u64 v[74:75], s[8:9], 0, v[74:75]
	v_lshl_add_u64 v[94:95], v[90:91], 0, v[130:131]
	global_store_dwordx4 v[46:47], v[30:33], off offset:256
	v_cvt_pk_bf16_f32 v17, v12, v13
	v_lshl_add_u64 v[10:11], s[8:9], 0, v[10:11]
	v_lshl_add_u64 v[30:31], v[26:27], 0, v[130:131]
	v_cvt_pk_bf16_f32 v126, v126, v127
	v_cvt_pk_bf16_f32 v127, v128, v129
	v_cvt_pk_bf16_f32 v128, v122, v123
	v_cvt_pk_bf16_f32 v129, v124, v125
	v_cvt_pk_bf16_f32 v106, v118, v119
	v_cvt_pk_bf16_f32 v107, v120, v121
	v_cvt_pk_bf16_f32 v108, v114, v115
	v_cvt_pk_bf16_f32 v109, v116, v117
	v_cvt_pk_bf16_f32 v90, v102, v103
	v_cvt_pk_bf16_f32 v91, v104, v105
	v_cvt_pk_bf16_f32 v92, v98, v99
	v_cvt_pk_bf16_f32 v93, v100, v101
	global_store_dwordx4 v[94:95], v[78:81], off offset:256
	v_cvt_pk_bf16_f32 v76, v82, v83
	v_cvt_pk_bf16_f32 v77, v84, v85
	v_lshl_add_u64 v[78:79], v[74:75], 0, v[130:131]
	v_cvt_pk_bf16_f32 v74, v86, v87
	v_cvt_pk_bf16_f32 v75, v88, v89
	v_cvt_pk_bf16_f32 v73, v68, v69
	v_cvt_pk_bf16_f32 v62, v62, v63
	v_cvt_pk_bf16_f32 v63, v64, v65
	v_cvt_pk_bf16_f32 v64, v58, v59
	v_cvt_pk_bf16_f32 v65, v60, v61
	v_cvt_pk_bf16_f32 v42, v54, v55
	v_cvt_pk_bf16_f32 v43, v56, v57
	v_cvt_pk_bf16_f32 v44, v50, v51
	v_cvt_pk_bf16_f32 v45, v52, v53
	v_cvt_pk_bf16_f32 v26, v38, v39
	v_cvt_pk_bf16_f32 v27, v40, v41
	v_cvt_pk_bf16_f32 v28, v34, v35
	v_cvt_pk_bf16_f32 v29, v36, v37
	global_store_dwordx4 v[30:31], v[14:17], off offset:256
	v_cvt_pk_bf16_f32 v12, v18, v19
	v_cvt_pk_bf16_f32 v13, v20, v21
	v_lshl_add_u64 v[14:15], v[10:11], 0, v[130:131]
	v_cvt_pk_bf16_f32 v10, v22, v23
	v_cvt_pk_bf16_f32 v11, v24, v25
	v_cvt_pk_bf16_f32 v6, v6, v7
	v_cvt_pk_bf16_f32 v7, v8, v9
	v_cvt_pk_bf16_f32 v8, v2, v3
	v_cvt_pk_bf16_f32 v9, v4, v5
	global_store_dwordx4 v[132:133], v[126:129], off
	global_store_dwordx4 v[110:111], v[106:109], off
	global_store_dwordx4 v[94:95], v[90:93], off
	global_store_dwordx4 v[78:79], v[74:77], off
	global_store_dwordx4 v[78:79], v[70:73], off offset:256
	global_store_dwordx4 v[66:67], v[62:65], off
	global_store_dwordx4 v[46:47], v[42:45], off
	global_store_dwordx4 v[30:31], v[26:29], off
	global_store_dwordx4 v[14:15], v[10:13], off
	global_store_dwordx4 v[14:15], v[6:9], off offset:256
	s_waitcnt vmcnt(0)
	s_cmpk_lt_u32 s3, 0x100
	s_cbranch_scc0 .LBB0_2243
	s_barrier

.LBB0_2373:
	s_add_u32 s60, s20, 0xfff00000
	s_addc_u32 s61, s21, -1
	s_mov_b32 m0, s35
	ds_read_b128 v[142:145], v148
	global_load_lds_dwordx4 v130, s[60:61]
	s_mov_b32 m0, s36
	ds_read_b128 v[154:157], v148 offset:1024
	global_load_lds_dwordx4 v134, s[60:61]
	s_mov_b32 m0, s40
	ds_read_b128 v[158:161], v148 offset:2048
	global_load_lds_dwordx4 v138, s[20:21]
	s_mov_b32 m0, s41
	ds_read_b128 v[168:171], v148 offset:3072
	global_load_lds_dwordx4 v140, s[20:21]
	ds_read_b128 v[176:179], v149
	ds_read_b128 v[180:183], v149 offset:1024
	ds_read_b128 v[184:187], v149 offset:2048
	ds_read_b128 v[188:191], v149 offset:3072
	s_add_u32 s22, s20, 0xfff00080
	s_addc_u32 s23, s21, -1
	s_cmp_eq_u32 s57, 60
	s_cselect_b32 s25, s52, s23
	s_cselect_b32 s24, s53, s22
	s_cselect_b32 s23, s7, s56
	s_cselect_b32 s22, s54, s55
	ds_read_b128 v[192:195], v150
	ds_read_b128 v[204:207], v150 offset:1024
	ds_read_b128 v[208:211], v150 offset:2048
	ds_read_b128 v[212:215], v150 offset:3072
	ds_read_b128 v[216:219], v150 offset:4096
	ds_read_b128 v[220:223], v150 offset:5120
	ds_read_b128 v[224:227], v150 offset:6144
	ds_read_b128 v[228:231], v150 offset:7168
	s_waitcnt vmcnt(8)
	s_waitcnt lgkmcnt(0)
	s_barrier
	s_setprio 1
	s_waitcnt lgkmcnt(0)
	v_mfma_f32_16x16x32_bf16 v[126:129], v[142:145], v[192:195], v[126:129]
	v_mfma_f32_16x16x32_bf16 v[122:125], v[158:161], v[192:195], v[122:125]
	v_mfma_f32_16x16x32_bf16 v[118:121], v[176:179], v[192:195], v[118:121]
	v_mfma_f32_16x16x32_bf16 v[114:117], v[184:187], v[192:195], v[114:117]
	v_mfma_f32_16x16x32_bf16 v[114:117], v[188:191], v[204:207], v[114:117]
	v_mfma_f32_16x16x32_bf16 v[118:121], v[180:183], v[204:207], v[118:121]
	v_mfma_f32_16x16x32_bf16 v[122:125], v[168:171], v[204:207], v[122:125]
	v_mfma_f32_16x16x32_bf16 v[126:129], v[154:157], v[204:207], v[126:129]
	v_mfma_f32_16x16x32_bf16 v[110:113], v[154:157], v[212:215], v[110:113]
	v_mfma_f32_16x16x32_bf16 v[106:109], v[168:171], v[212:215], v[106:109]
	v_mfma_f32_16x16x32_bf16 v[102:105], v[180:183], v[212:215], v[102:105]
	v_mfma_f32_16x16x32_bf16 v[98:101], v[188:191], v[212:215], v[98:101]
	v_mfma_f32_16x16x32_bf16 v[98:101], v[184:187], v[208:211], v[98:101]
	v_mfma_f32_16x16x32_bf16 v[102:105], v[176:179], v[208:211], v[102:105]
	v_mfma_f32_16x16x32_bf16 v[106:109], v[158:161], v[208:211], v[106:109]
	v_mfma_f32_16x16x32_bf16 v[110:113], v[142:145], v[208:211], v[110:113]
	v_mfma_f32_16x16x32_bf16 v[94:97], v[142:145], v[216:219], v[94:97]
	v_mfma_f32_16x16x32_bf16 v[90:93], v[158:161], v[216:219], v[90:93]
	v_mfma_f32_16x16x32_bf16 v[86:89], v[176:179], v[216:219], v[86:89]
	v_mfma_f32_16x16x32_bf16 v[82:85], v[184:187], v[216:219], v[82:85]
	v_mfma_f32_16x16x32_bf16 v[82:85], v[188:191], v[220:223], v[82:85]
	v_mfma_f32_16x16x32_bf16 v[86:89], v[180:183], v[220:223], v[86:89]
	v_mfma_f32_16x16x32_bf16 v[90:93], v[168:171], v[220:223], v[90:93]
	v_mfma_f32_16x16x32_bf16 v[94:97], v[154:157], v[220:223], v[94:97]
	v_mfma_f32_16x16x32_bf16 v[78:81], v[154:157], v[228:231], v[78:81]
	v_mfma_f32_16x16x32_bf16 v[74:77], v[168:171], v[228:231], v[74:77]
	v_mfma_f32_16x16x32_bf16 v[70:73], v[180:183], v[228:231], v[70:73]
	v_mfma_f32_16x16x32_bf16 v[66:69], v[188:191], v[228:231], v[66:69]
	v_mfma_f32_16x16x32_bf16 v[66:69], v[184:187], v[224:227], v[66:69]
	v_mfma_f32_16x16x32_bf16 v[70:73], v[176:179], v[224:227], v[70:73]
	v_mfma_f32_16x16x32_bf16 v[74:77], v[158:161], v[224:227], v[74:77]
	v_mfma_f32_16x16x32_bf16 v[78:81], v[142:145], v[224:227], v[78:81]
	s_setprio 0
	s_barrier
	s_mov_b32 m0, s42
	s_add_u32 s60, s22, 0x100000
	global_load_lds_dwordx4 v132, s[22:23]
	s_mov_b32 m0, s43
	s_addc_u32 s61, s23, 0
	global_load_lds_dwordx4 v136, s[22:23]
	s_mov_b32 m0, s44
	ds_read_b128 v[192:195], v150 offset:16384
	global_load_lds_dwordx4 v132, s[60:61]
	s_mov_b32 m0, s45
	ds_read_b128 v[204:207], v150 offset:17408
	global_load_lds_dwordx4 v136, s[60:61]
	ds_read_b128 v[208:211], v150 offset:18432
	ds_read_b128 v[212:215], v150 offset:19456
	ds_read_b128 v[216:219], v150 offset:20480
	ds_read_b128 v[220:223], v150 offset:21504
	ds_read_b128 v[224:227], v150 offset:22528
	ds_read_b128 v[228:231], v150 offset:23552
	s_waitcnt vmcnt(6)
	s_waitcnt lgkmcnt(0)
	s_barrier
	s_setprio 1
	s_waitcnt lgkmcnt(0)
	v_mfma_f32_16x16x32_bf16 v[62:65], v[142:145], v[192:195], v[62:65]
	v_mfma_f32_16x16x32_bf16 v[58:61], v[158:161], v[192:195], v[58:61]
	v_mfma_f32_16x16x32_bf16 v[54:57], v[176:179], v[192:195], v[54:57]
	v_mfma_f32_16x16x32_bf16 v[50:53], v[184:187], v[192:195], v[50:53]
	v_mfma_f32_16x16x32_bf16 v[50:53], v[188:191], v[204:207], v[50:53]
	v_mfma_f32_16x16x32_bf16 v[54:57], v[180:183], v[204:207], v[54:57]
	v_mfma_f32_16x16x32_bf16 v[58:61], v[168:171], v[204:207], v[58:61]
	v_mfma_f32_16x16x32_bf16 v[62:65], v[154:157], v[204:207], v[62:65]
	v_mfma_f32_16x16x32_bf16 v[46:49], v[154:157], v[212:215], v[46:49]
	v_mfma_f32_16x16x32_bf16 v[42:45], v[168:171], v[212:215], v[42:45]
	v_mfma_f32_16x16x32_bf16 v[38:41], v[180:183], v[212:215], v[38:41]
	v_mfma_f32_16x16x32_bf16 v[34:37], v[188:191], v[212:215], v[34:37]
	v_mfma_f32_16x16x32_bf16 v[34:37], v[184:187], v[208:211], v[34:37]
	v_mfma_f32_16x16x32_bf16 v[38:41], v[176:179], v[208:211], v[38:41]
	v_mfma_f32_16x16x32_bf16 v[42:45], v[158:161], v[208:211], v[42:45]
	v_mfma_f32_16x16x32_bf16 v[46:49], v[142:145], v[208:211], v[46:49]
	v_mfma_f32_16x16x32_bf16 v[30:33], v[142:145], v[216:219], v[30:33]
	v_mfma_f32_16x16x32_bf16 v[26:29], v[158:161], v[216:219], v[26:29]
	v_mfma_f32_16x16x32_bf16 v[22:25], v[176:179], v[216:219], v[22:25]
	v_mfma_f32_16x16x32_bf16 v[18:21], v[184:187], v[216:219], v[18:21]
	v_mfma_f32_16x16x32_bf16 v[18:21], v[188:191], v[220:223], v[18:21]
	v_mfma_f32_16x16x32_bf16 v[22:25], v[180:183], v[220:223], v[22:25]
	v_mfma_f32_16x16x32_bf16 v[26:29], v[168:171], v[220:223], v[26:29]
	v_mfma_f32_16x16x32_bf16 v[30:33], v[154:157], v[220:223], v[30:33]
	v_mfma_f32_16x16x32_bf16 v[14:17], v[154:157], v[228:231], v[14:17]
	v_mfma_f32_16x16x32_bf16 v[10:13], v[168:171], v[228:231], v[10:13]
	v_mfma_f32_16x16x32_bf16 v[6:9], v[180:183], v[228:231], v[6:9]
	v_mfma_f32_16x16x32_bf16 v[2:5], v[188:191], v[228:231], v[2:5]
	v_mfma_f32_16x16x32_bf16 v[2:5], v[184:187], v[224:227], v[2:5]
	v_mfma_f32_16x16x32_bf16 v[6:9], v[176:179], v[224:227], v[6:9]
	v_mfma_f32_16x16x32_bf16 v[10:13], v[158:161], v[224:227], v[10:13]
	v_mfma_f32_16x16x32_bf16 v[14:17], v[142:145], v[224:227], v[14:17]
	s_setprio 0
	s_barrier
	s_mov_b32 m0, s29
	ds_read_b128 v[142:145], v151
	global_load_lds_dwordx4 v130, s[24:25]
	s_mov_b32 m0, s30
	ds_read_b128 v[154:157], v151 offset:1024
	global_load_lds_dwordx4 v134, s[24:25]
	s_add_u32 s24, s24, 0x100000
	s_addc_u32 s25, s25, 0
	s_mov_b32 m0, s31
	ds_read_b128 v[158:161], v151 offset:2048
	global_load_lds_dwordx4 v130, s[24:25]
	s_mov_b32 m0, s33
	ds_read_b128 v[168:171], v151 offset:3072
	global_load_lds_dwordx4 v134, s[24:25]
	ds_read_b128 v[176:179], v152
	ds_read_b128 v[180:183], v152 offset:1024
	ds_read_b128 v[184:187], v152 offset:2048
	ds_read_b128 v[188:191], v152 offset:3072
	ds_read_b128 v[192:195], v150 offset:32768
	ds_read_b128 v[204:207], v150 offset:33792
	ds_read_b128 v[208:211], v150 offset:34816
	ds_read_b128 v[212:215], v150 offset:35840
	ds_read_b128 v[216:219], v150 offset:36864
	ds_read_b128 v[220:223], v150 offset:37888
	ds_read_b128 v[224:227], v150 offset:38912
	ds_read_b128 v[228:231], v150 offset:39936
	s_waitcnt vmcnt(8)
	s_waitcnt lgkmcnt(0)
	s_barrier
	s_setprio 1
	s_waitcnt lgkmcnt(0)
	v_mfma_f32_16x16x32_bf16 v[126:129], v[142:145], v[192:195], v[126:129]
	v_mfma_f32_16x16x32_bf16 v[122:125], v[158:161], v[192:195], v[122:125]
	v_mfma_f32_16x16x32_bf16 v[118:121], v[176:179], v[192:195], v[118:121]
	v_mfma_f32_16x16x32_bf16 v[114:117], v[184:187], v[192:195], v[114:117]
	v_mfma_f32_16x16x32_bf16 v[114:117], v[188:191], v[204:207], v[114:117]
	v_mfma_f32_16x16x32_bf16 v[118:121], v[180:183], v[204:207], v[118:121]
	v_mfma_f32_16x16x32_bf16 v[122:125], v[168:171], v[204:207], v[122:125]
	v_mfma_f32_16x16x32_bf16 v[126:129], v[154:157], v[204:207], v[126:129]
	v_mfma_f32_16x16x32_bf16 v[110:113], v[154:157], v[212:215], v[110:113]
	v_mfma_f32_16x16x32_bf16 v[106:109], v[168:171], v[212:215], v[106:109]
	v_mfma_f32_16x16x32_bf16 v[102:105], v[180:183], v[212:215], v[102:105]
	v_mfma_f32_16x16x32_bf16 v[98:101], v[188:191], v[212:215], v[98:101]
	v_mfma_f32_16x16x32_bf16 v[98:101], v[184:187], v[208:211], v[98:101]
	v_mfma_f32_16x16x32_bf16 v[102:105], v[176:179], v[208:211], v[102:105]
	v_mfma_f32_16x16x32_bf16 v[106:109], v[158:161], v[208:211], v[106:109]
	v_mfma_f32_16x16x32_bf16 v[110:113], v[142:145], v[208:211], v[110:113]
	v_mfma_f32_16x16x32_bf16 v[94:97], v[142:145], v[216:219], v[94:97]
	v_mfma_f32_16x16x32_bf16 v[90:93], v[158:161], v[216:219], v[90:93]
	v_mfma_f32_16x16x32_bf16 v[86:89], v[176:179], v[216:219], v[86:89]
	v_mfma_f32_16x16x32_bf16 v[82:85], v[184:187], v[216:219], v[82:85]
	v_mfma_f32_16x16x32_bf16 v[82:85], v[188:191], v[220:223], v[82:85]
	v_mfma_f32_16x16x32_bf16 v[86:89], v[180:183], v[220:223], v[86:89]
	v_mfma_f32_16x16x32_bf16 v[90:93], v[168:171], v[220:223], v[90:93]
	v_mfma_f32_16x16x32_bf16 v[94:97], v[154:157], v[220:223], v[94:97]
	v_mfma_f32_16x16x32_bf16 v[78:81], v[154:157], v[228:231], v[78:81]
	v_mfma_f32_16x16x32_bf16 v[74:77], v[168:171], v[228:231], v[74:77]
	v_mfma_f32_16x16x32_bf16 v[70:73], v[180:183], v[228:231], v[70:73]
	v_mfma_f32_16x16x32_bf16 v[66:69], v[188:191], v[228:231], v[66:69]
	v_mfma_f32_16x16x32_bf16 v[66:69], v[184:187], v[224:227], v[66:69]
	v_mfma_f32_16x16x32_bf16 v[70:73], v[176:179], v[224:227], v[70:73]
	v_mfma_f32_16x16x32_bf16 v[74:77], v[158:161], v[224:227], v[74:77]
	v_mfma_f32_16x16x32_bf16 v[78:81], v[142:145], v[224:227], v[78:81]
	s_setprio 0
	s_barrier
	s_mov_b32 m0, s46
	s_add_u32 s22, s22, 0x80
	s_addc_u32 s23, s23, 0
	global_load_lds_dwordx4 v132, s[22:23]
	s_mov_b32 m0, s47
	ds_read_b128 v[192:195], v150 offset:49152
	global_load_lds_dwordx4 v136, s[22:23]
	s_mov_b32 m0, s48
	s_add_u32 s22, s22, 0x100000
	s_addc_u32 s23, s23, 0
	global_load_lds_dwordx4 v132, s[22:23]
	s_mov_b32 m0, s49
	ds_read_b128 v[204:207], v150 offset:50176
	global_load_lds_dwordx4 v136, s[22:23]
	ds_read_b128 v[208:211], v150 offset:51200
	ds_read_b128 v[212:215], v150 offset:52224
	ds_read_b128 v[216:219], v150 offset:53248
	ds_read_b128 v[220:223], v150 offset:54272
	ds_read_b128 v[224:227], v150 offset:55296
	ds_read_b128 v[228:231], v150 offset:56320
	s_waitcnt vmcnt(6)
	s_waitcnt lgkmcnt(0)
	s_barrier
	s_setprio 1
	s_waitcnt lgkmcnt(0)
	v_mfma_f32_16x16x32_bf16 v[62:65], v[142:145], v[192:195], v[62:65]
	v_mfma_f32_16x16x32_bf16 v[58:61], v[158:161], v[192:195], v[58:61]
	v_mfma_f32_16x16x32_bf16 v[54:57], v[176:179], v[192:195], v[54:57]
	v_mfma_f32_16x16x32_bf16 v[50:53], v[184:187], v[192:195], v[50:53]
	v_mfma_f32_16x16x32_bf16 v[50:53], v[188:191], v[204:207], v[50:53]
	v_mfma_f32_16x16x32_bf16 v[54:57], v[180:183], v[204:207], v[54:57]
	v_mfma_f32_16x16x32_bf16 v[58:61], v[168:171], v[204:207], v[58:61]
	v_mfma_f32_16x16x32_bf16 v[62:65], v[154:157], v[204:207], v[62:65]
	v_mfma_f32_16x16x32_bf16 v[46:49], v[154:157], v[212:215], v[46:49]
	v_mfma_f32_16x16x32_bf16 v[42:45], v[168:171], v[212:215], v[42:45]
	v_mfma_f32_16x16x32_bf16 v[38:41], v[180:183], v[212:215], v[38:41]
	v_mfma_f32_16x16x32_bf16 v[34:37], v[188:191], v[212:215], v[34:37]
	v_mfma_f32_16x16x32_bf16 v[34:37], v[184:187], v[208:211], v[34:37]
	v_mfma_f32_16x16x32_bf16 v[38:41], v[176:179], v[208:211], v[38:41]
	v_mfma_f32_16x16x32_bf16 v[42:45], v[158:161], v[208:211], v[42:45]
	v_mfma_f32_16x16x32_bf16 v[46:49], v[142:145], v[208:211], v[46:49]
	v_mfma_f32_16x16x32_bf16 v[30:33], v[142:145], v[216:219], v[30:33]
	v_mfma_f32_16x16x32_bf16 v[26:29], v[158:161], v[216:219], v[26:29]
	v_mfma_f32_16x16x32_bf16 v[22:25], v[176:179], v[216:219], v[22:25]
	v_mfma_f32_16x16x32_bf16 v[18:21], v[184:187], v[216:219], v[18:21]
	v_mfma_f32_16x16x32_bf16 v[18:21], v[188:191], v[220:223], v[18:21]
	v_mfma_f32_16x16x32_bf16 v[22:25], v[180:183], v[220:223], v[22:25]
	v_mfma_f32_16x16x32_bf16 v[26:29], v[168:171], v[220:223], v[26:29]
	v_mfma_f32_16x16x32_bf16 v[30:33], v[154:157], v[220:223], v[30:33]
	v_mfma_f32_16x16x32_bf16 v[14:17], v[154:157], v[228:231], v[14:17]
	v_mfma_f32_16x16x32_bf16 v[10:13], v[168:171], v[228:231], v[10:13]
	v_mfma_f32_16x16x32_bf16 v[6:9], v[180:183], v[228:231], v[6:9]
	v_mfma_f32_16x16x32_bf16 v[2:5], v[188:191], v[228:231], v[2:5]
	v_mfma_f32_16x16x32_bf16 v[2:5], v[184:187], v[224:227], v[2:5]
	v_mfma_f32_16x16x32_bf16 v[6:9], v[176:179], v[224:227], v[6:9]
	v_mfma_f32_16x16x32_bf16 v[10:13], v[158:161], v[224:227], v[10:13]
	v_mfma_f32_16x16x32_bf16 v[14:17], v[142:145], v[224:227], v[14:17]
	s_setprio 0
	s_barrier
	s_add_i32 s57, s57, 2
	s_add_u32 s20, s20, 0x100
	s_addc_u32 s21, s21, 0
	s_add_u32 s55, s55, 0x100
	s_addc_u32 s56, s56, 0
	s_cmp_gt_u32 s57, 61
	s_cbranch_scc0 .LBB0_2373
	s_and_b64 vcc, exec, s[16:17]
	s_cbranch_vccz .LBB0_2376
	s_barrier

.LBB0_2618:
	s_add_u32 s64, s28, 0xffd50000
	s_addc_u32 s65, s29, -1
	s_mov_b32 m0, s44
	ds_read_b128 v[142:145], v156
	global_load_lds_dwordx4 v130, s[64:65]
	s_mov_b32 m0, s45
	ds_read_b128 v[168:171], v156 offset:1024
	global_load_lds_dwordx4 v134, s[64:65]
	s_mov_b32 m0, s46
	ds_read_b128 v[172:175], v156 offset:2048
	global_load_lds_dwordx4 v138, s[28:29]
	s_mov_b32 m0, s47
	ds_read_b128 v[176:179], v156 offset:3072
	global_load_lds_dwordx4 v140, s[28:29]
	ds_read_b128 v[180:183], v157
	ds_read_b128 v[184:187], v157 offset:1024
	ds_read_b128 v[188:191], v157 offset:2048
	ds_read_b128 v[192:195], v157 offset:3072
	s_add_u32 s30, s28, 0xffd50080
	s_addc_u32 s31, s29, -1
	s_cmpk_eq_i32 s62, 0xa8
	s_cselect_b32 s35, s25, s31
	s_cselect_b32 s34, s24, s30
	s_cselect_b32 s31, s23, s61
	s_cselect_b32 s30, s22, s60
	ds_read_b128 v[196:199], v158
	ds_read_b128 v[200:203], v158 offset:1024
	ds_read_b128 v[204:207], v158 offset:2048
	ds_read_b128 v[208:211], v158 offset:3072
	ds_read_b128 v[212:215], v158 offset:4096
	ds_read_b128 v[216:219], v158 offset:5120
	ds_read_b128 v[220:223], v158 offset:6144
	ds_read_b128 v[224:227], v158 offset:7168
	s_waitcnt vmcnt(8)
	s_waitcnt lgkmcnt(0)
	s_barrier
	s_setprio 1
	s_waitcnt lgkmcnt(0)
	v_mfma_f32_16x16x32_bf16 v[126:129], v[142:145], v[196:199], v[126:129]
	v_mfma_f32_16x16x32_bf16 v[122:125], v[172:175], v[196:199], v[122:125]
	v_mfma_f32_16x16x32_bf16 v[118:121], v[180:183], v[196:199], v[118:121]
	v_mfma_f32_16x16x32_bf16 v[114:117], v[188:191], v[196:199], v[114:117]
	v_mfma_f32_16x16x32_bf16 v[114:117], v[192:195], v[200:203], v[114:117]
	v_mfma_f32_16x16x32_bf16 v[118:121], v[184:187], v[200:203], v[118:121]
	v_mfma_f32_16x16x32_bf16 v[122:125], v[176:179], v[200:203], v[122:125]
	v_mfma_f32_16x16x32_bf16 v[126:129], v[168:171], v[200:203], v[126:129]
	v_mfma_f32_16x16x32_bf16 v[110:113], v[168:171], v[208:211], v[110:113]
	v_mfma_f32_16x16x32_bf16 v[106:109], v[176:179], v[208:211], v[106:109]
	v_mfma_f32_16x16x32_bf16 v[102:105], v[184:187], v[208:211], v[102:105]
	v_mfma_f32_16x16x32_bf16 v[98:101], v[192:195], v[208:211], v[98:101]
	v_mfma_f32_16x16x32_bf16 v[98:101], v[188:191], v[204:207], v[98:101]
	v_mfma_f32_16x16x32_bf16 v[102:105], v[180:183], v[204:207], v[102:105]
	v_mfma_f32_16x16x32_bf16 v[106:109], v[172:175], v[204:207], v[106:109]
	v_mfma_f32_16x16x32_bf16 v[110:113], v[142:145], v[204:207], v[110:113]
	v_mfma_f32_16x16x32_bf16 v[94:97], v[142:145], v[212:215], v[94:97]
	v_mfma_f32_16x16x32_bf16 v[90:93], v[172:175], v[212:215], v[90:93]
	v_mfma_f32_16x16x32_bf16 v[86:89], v[180:183], v[212:215], v[86:89]
	v_mfma_f32_16x16x32_bf16 v[82:85], v[188:191], v[212:215], v[82:85]
	v_mfma_f32_16x16x32_bf16 v[82:85], v[192:195], v[216:219], v[82:85]
	v_mfma_f32_16x16x32_bf16 v[86:89], v[184:187], v[216:219], v[86:89]
	v_mfma_f32_16x16x32_bf16 v[90:93], v[176:179], v[216:219], v[90:93]
	v_mfma_f32_16x16x32_bf16 v[94:97], v[168:171], v[216:219], v[94:97]
	v_mfma_f32_16x16x32_bf16 v[78:81], v[168:171], v[224:227], v[78:81]
	v_mfma_f32_16x16x32_bf16 v[74:77], v[176:179], v[224:227], v[74:77]
	v_mfma_f32_16x16x32_bf16 v[70:73], v[184:187], v[224:227], v[70:73]
	v_mfma_f32_16x16x32_bf16 v[66:69], v[192:195], v[224:227], v[66:69]
	v_mfma_f32_16x16x32_bf16 v[66:69], v[188:191], v[220:223], v[66:69]
	v_mfma_f32_16x16x32_bf16 v[70:73], v[180:183], v[220:223], v[70:73]
	v_mfma_f32_16x16x32_bf16 v[74:77], v[172:175], v[220:223], v[74:77]
	v_mfma_f32_16x16x32_bf16 v[78:81], v[142:145], v[220:223], v[78:81]
	s_setprio 0
	s_barrier
	s_mov_b32 m0, s48
	s_add_u32 s64, s30, 0x2b0000
	global_load_lds_dwordx4 v132, s[30:31]
	s_mov_b32 m0, s49
	s_addc_u32 s65, s31, 0
	global_load_lds_dwordx4 v136, s[30:31]
	s_mov_b32 m0, s50
	ds_read_b128 v[196:199], v158 offset:16384
	global_load_lds_dwordx4 v132, s[64:65]
	s_mov_b32 m0, s51
	ds_read_b128 v[200:203], v158 offset:17408
	global_load_lds_dwordx4 v136, s[64:65]
	ds_read_b128 v[204:207], v158 offset:18432
	ds_read_b128 v[208:211], v158 offset:19456
	ds_read_b128 v[212:215], v158 offset:20480
	ds_read_b128 v[216:219], v158 offset:21504
	ds_read_b128 v[220:223], v158 offset:22528
	ds_read_b128 v[224:227], v158 offset:23552
	s_waitcnt vmcnt(6)
	s_waitcnt lgkmcnt(0)
	s_barrier
	s_setprio 1
	s_waitcnt lgkmcnt(0)
	v_mfma_f32_16x16x32_bf16 v[62:65], v[142:145], v[196:199], v[62:65]
	v_mfma_f32_16x16x32_bf16 v[58:61], v[172:175], v[196:199], v[58:61]
	v_mfma_f32_16x16x32_bf16 v[54:57], v[180:183], v[196:199], v[54:57]
	v_mfma_f32_16x16x32_bf16 v[50:53], v[188:191], v[196:199], v[50:53]
	v_mfma_f32_16x16x32_bf16 v[50:53], v[192:195], v[200:203], v[50:53]
	v_mfma_f32_16x16x32_bf16 v[54:57], v[184:187], v[200:203], v[54:57]
	v_mfma_f32_16x16x32_bf16 v[58:61], v[176:179], v[200:203], v[58:61]
	v_mfma_f32_16x16x32_bf16 v[62:65], v[168:171], v[200:203], v[62:65]
	v_mfma_f32_16x16x32_bf16 v[46:49], v[168:171], v[208:211], v[46:49]
	v_mfma_f32_16x16x32_bf16 v[42:45], v[176:179], v[208:211], v[42:45]
	v_mfma_f32_16x16x32_bf16 v[38:41], v[184:187], v[208:211], v[38:41]
	v_mfma_f32_16x16x32_bf16 v[34:37], v[192:195], v[208:211], v[34:37]
	v_mfma_f32_16x16x32_bf16 v[34:37], v[188:191], v[204:207], v[34:37]
	v_mfma_f32_16x16x32_bf16 v[38:41], v[180:183], v[204:207], v[38:41]
	v_mfma_f32_16x16x32_bf16 v[42:45], v[172:175], v[204:207], v[42:45]
	v_mfma_f32_16x16x32_bf16 v[46:49], v[142:145], v[204:207], v[46:49]
	v_mfma_f32_16x16x32_bf16 v[30:33], v[142:145], v[212:215], v[30:33]
	v_mfma_f32_16x16x32_bf16 v[26:29], v[172:175], v[212:215], v[26:29]
	v_mfma_f32_16x16x32_bf16 v[22:25], v[180:183], v[212:215], v[22:25]
	v_mfma_f32_16x16x32_bf16 v[18:21], v[188:191], v[212:215], v[18:21]
	v_mfma_f32_16x16x32_bf16 v[18:21], v[192:195], v[216:219], v[18:21]
	v_mfma_f32_16x16x32_bf16 v[22:25], v[184:187], v[216:219], v[22:25]
	v_mfma_f32_16x16x32_bf16 v[26:29], v[176:179], v[216:219], v[26:29]
	v_mfma_f32_16x16x32_bf16 v[30:33], v[168:171], v[216:219], v[30:33]
	v_mfma_f32_16x16x32_bf16 v[14:17], v[168:171], v[224:227], v[14:17]
	v_mfma_f32_16x16x32_bf16 v[10:13], v[176:179], v[224:227], v[10:13]
	v_mfma_f32_16x16x32_bf16 v[6:9], v[184:187], v[224:227], v[6:9]
	v_mfma_f32_16x16x32_bf16 v[2:5], v[192:195], v[224:227], v[2:5]
	v_mfma_f32_16x16x32_bf16 v[2:5], v[188:191], v[220:223], v[2:5]
	v_mfma_f32_16x16x32_bf16 v[6:9], v[180:183], v[220:223], v[6:9]
	v_mfma_f32_16x16x32_bf16 v[10:13], v[172:175], v[220:223], v[10:13]
	v_mfma_f32_16x16x32_bf16 v[14:17], v[142:145], v[220:223], v[14:17]
	s_setprio 0
	s_barrier
	s_mov_b32 m0, s39
	ds_read_b128 v[142:145], v159
	global_load_lds_dwordx4 v130, s[34:35]
	s_mov_b32 m0, s40
	ds_read_b128 v[168:171], v159 offset:1024
	global_load_lds_dwordx4 v134, s[34:35]
	s_add_u32 s34, s34, 0x2b0000
	s_addc_u32 s35, s35, 0
	s_mov_b32 m0, s41
	ds_read_b128 v[172:175], v159 offset:2048
	global_load_lds_dwordx4 v130, s[34:35]
	s_mov_b32 m0, s42
	ds_read_b128 v[176:179], v159 offset:3072
	global_load_lds_dwordx4 v134, s[34:35]
	ds_read_b128 v[180:183], v160
	ds_read_b128 v[184:187], v160 offset:1024
	ds_read_b128 v[188:191], v160 offset:2048
	ds_read_b128 v[192:195], v160 offset:3072
	ds_read_b128 v[196:199], v158 offset:32768
	ds_read_b128 v[200:203], v158 offset:33792
	ds_read_b128 v[204:207], v158 offset:34816
	ds_read_b128 v[208:211], v158 offset:35840
	ds_read_b128 v[212:215], v158 offset:36864
	ds_read_b128 v[216:219], v158 offset:37888
	ds_read_b128 v[220:223], v158 offset:38912
	ds_read_b128 v[224:227], v158 offset:39936
	s_waitcnt vmcnt(8)
	s_waitcnt lgkmcnt(0)
	s_barrier
	s_setprio 1
	s_waitcnt lgkmcnt(0)
	v_mfma_f32_16x16x32_bf16 v[126:129], v[142:145], v[196:199], v[126:129]
	v_mfma_f32_16x16x32_bf16 v[122:125], v[172:175], v[196:199], v[122:125]
	v_mfma_f32_16x16x32_bf16 v[118:121], v[180:183], v[196:199], v[118:121]
	v_mfma_f32_16x16x32_bf16 v[114:117], v[188:191], v[196:199], v[114:117]
	v_mfma_f32_16x16x32_bf16 v[114:117], v[192:195], v[200:203], v[114:117]
	v_mfma_f32_16x16x32_bf16 v[118:121], v[184:187], v[200:203], v[118:121]
	v_mfma_f32_16x16x32_bf16 v[122:125], v[176:179], v[200:203], v[122:125]
	v_mfma_f32_16x16x32_bf16 v[126:129], v[168:171], v[200:203], v[126:129]
	v_mfma_f32_16x16x32_bf16 v[110:113], v[168:171], v[208:211], v[110:113]
	v_mfma_f32_16x16x32_bf16 v[106:109], v[176:179], v[208:211], v[106:109]
	v_mfma_f32_16x16x32_bf16 v[102:105], v[184:187], v[208:211], v[102:105]
	v_mfma_f32_16x16x32_bf16 v[98:101], v[192:195], v[208:211], v[98:101]
	v_mfma_f32_16x16x32_bf16 v[98:101], v[188:191], v[204:207], v[98:101]
	v_mfma_f32_16x16x32_bf16 v[102:105], v[180:183], v[204:207], v[102:105]
	v_mfma_f32_16x16x32_bf16 v[106:109], v[172:175], v[204:207], v[106:109]
	v_mfma_f32_16x16x32_bf16 v[110:113], v[142:145], v[204:207], v[110:113]
	v_mfma_f32_16x16x32_bf16 v[94:97], v[142:145], v[212:215], v[94:97]
	v_mfma_f32_16x16x32_bf16 v[90:93], v[172:175], v[212:215], v[90:93]
	v_mfma_f32_16x16x32_bf16 v[86:89], v[180:183], v[212:215], v[86:89]
	v_mfma_f32_16x16x32_bf16 v[82:85], v[188:191], v[212:215], v[82:85]
	v_mfma_f32_16x16x32_bf16 v[82:85], v[192:195], v[216:219], v[82:85]
	v_mfma_f32_16x16x32_bf16 v[86:89], v[184:187], v[216:219], v[86:89]
	v_mfma_f32_16x16x32_bf16 v[90:93], v[176:179], v[216:219], v[90:93]
	v_mfma_f32_16x16x32_bf16 v[94:97], v[168:171], v[216:219], v[94:97]
	v_mfma_f32_16x16x32_bf16 v[78:81], v[168:171], v[224:227], v[78:81]
	v_mfma_f32_16x16x32_bf16 v[74:77], v[176:179], v[224:227], v[74:77]
	v_mfma_f32_16x16x32_bf16 v[70:73], v[184:187], v[224:227], v[70:73]
	v_mfma_f32_16x16x32_bf16 v[66:69], v[192:195], v[224:227], v[66:69]
	v_mfma_f32_16x16x32_bf16 v[66:69], v[188:191], v[220:223], v[66:69]
	v_mfma_f32_16x16x32_bf16 v[70:73], v[180:183], v[220:223], v[70:73]
	v_mfma_f32_16x16x32_bf16 v[74:77], v[172:175], v[220:223], v[74:77]
	v_mfma_f32_16x16x32_bf16 v[78:81], v[142:145], v[220:223], v[78:81]
	s_setprio 0
	s_barrier
	s_mov_b32 m0, s52
	s_add_u32 s30, s30, 0x80
	s_addc_u32 s31, s31, 0
	global_load_lds_dwordx4 v132, s[30:31]
	s_mov_b32 m0, s53
	ds_read_b128 v[196:199], v158 offset:49152
	global_load_lds_dwordx4 v136, s[30:31]
	s_mov_b32 m0, s54
	s_add_u32 s30, s30, 0x2b0000
	s_addc_u32 s31, s31, 0
	global_load_lds_dwordx4 v132, s[30:31]
	s_mov_b32 m0, s55
	ds_read_b128 v[200:203], v158 offset:50176
	global_load_lds_dwordx4 v136, s[30:31]
	ds_read_b128 v[204:207], v158 offset:51200
	ds_read_b128 v[208:211], v158 offset:52224
	ds_read_b128 v[212:215], v158 offset:53248
	ds_read_b128 v[216:219], v158 offset:54272
	ds_read_b128 v[220:223], v158 offset:55296
	ds_read_b128 v[224:227], v158 offset:56320
	s_waitcnt vmcnt(6)
	s_waitcnt lgkmcnt(0)
	s_barrier
	s_setprio 1
	s_waitcnt lgkmcnt(0)
	v_mfma_f32_16x16x32_bf16 v[62:65], v[142:145], v[196:199], v[62:65]
	v_mfma_f32_16x16x32_bf16 v[58:61], v[172:175], v[196:199], v[58:61]
	v_mfma_f32_16x16x32_bf16 v[54:57], v[180:183], v[196:199], v[54:57]
	v_mfma_f32_16x16x32_bf16 v[50:53], v[188:191], v[196:199], v[50:53]
	v_mfma_f32_16x16x32_bf16 v[50:53], v[192:195], v[200:203], v[50:53]
	v_mfma_f32_16x16x32_bf16 v[54:57], v[184:187], v[200:203], v[54:57]
	v_mfma_f32_16x16x32_bf16 v[58:61], v[176:179], v[200:203], v[58:61]
	v_mfma_f32_16x16x32_bf16 v[62:65], v[168:171], v[200:203], v[62:65]
	v_mfma_f32_16x16x32_bf16 v[46:49], v[168:171], v[208:211], v[46:49]
	v_mfma_f32_16x16x32_bf16 v[42:45], v[176:179], v[208:211], v[42:45]
	v_mfma_f32_16x16x32_bf16 v[38:41], v[184:187], v[208:211], v[38:41]
	v_mfma_f32_16x16x32_bf16 v[34:37], v[192:195], v[208:211], v[34:37]
	v_mfma_f32_16x16x32_bf16 v[34:37], v[188:191], v[204:207], v[34:37]
	v_mfma_f32_16x16x32_bf16 v[38:41], v[180:183], v[204:207], v[38:41]
	v_mfma_f32_16x16x32_bf16 v[42:45], v[172:175], v[204:207], v[42:45]
	v_mfma_f32_16x16x32_bf16 v[46:49], v[142:145], v[204:207], v[46:49]
	v_mfma_f32_16x16x32_bf16 v[30:33], v[142:145], v[212:215], v[30:33]
	v_mfma_f32_16x16x32_bf16 v[26:29], v[172:175], v[212:215], v[26:29]
	v_mfma_f32_16x16x32_bf16 v[22:25], v[180:183], v[212:215], v[22:25]
	v_mfma_f32_16x16x32_bf16 v[18:21], v[188:191], v[212:215], v[18:21]
	v_mfma_f32_16x16x32_bf16 v[18:21], v[192:195], v[216:219], v[18:21]
	v_mfma_f32_16x16x32_bf16 v[22:25], v[184:187], v[216:219], v[22:25]
	v_mfma_f32_16x16x32_bf16 v[26:29], v[176:179], v[216:219], v[26:29]
	v_mfma_f32_16x16x32_bf16 v[30:33], v[168:171], v[216:219], v[30:33]
	v_mfma_f32_16x16x32_bf16 v[14:17], v[168:171], v[224:227], v[14:17]
	v_mfma_f32_16x16x32_bf16 v[10:13], v[176:179], v[224:227], v[10:13]
	v_mfma_f32_16x16x32_bf16 v[6:9], v[184:187], v[224:227], v[6:9]
	v_mfma_f32_16x16x32_bf16 v[2:5], v[192:195], v[224:227], v[2:5]
	v_mfma_f32_16x16x32_bf16 v[2:5], v[188:191], v[220:223], v[2:5]
	v_mfma_f32_16x16x32_bf16 v[6:9], v[180:183], v[220:223], v[6:9]
	v_mfma_f32_16x16x32_bf16 v[10:13], v[172:175], v[220:223], v[10:13]
	v_mfma_f32_16x16x32_bf16 v[14:17], v[142:145], v[220:223], v[14:17]
	s_setprio 0
	s_barrier
	s_add_i32 s62, s62, 2
	s_add_u32 s28, s28, 0x100
	s_addc_u32 s29, s29, 0
	s_add_u32 s60, s60, 0x100
	s_addc_u32 s61, s61, 0
	s_cmpk_gt_u32 s62, 0xa9
	s_cbranch_scc0 .LBB0_2618
	s_and_b64 vcc, exec, s[12:13]
	s_cbranch_vccz .LBB0_2621
	s_barrier

.LBB0_2632:
	ds_read_b128 v[150:153], v1
	ds_read_b128 v[154:157], v1 offset:1024
	ds_read_b128 v[158:161], v1 offset:2048
	ds_read_b128 v[166:169], v1 offset:3072
	ds_read_b128 v[170:173], v139
	ds_read_b128 v[174:177], v139 offset:1024
	ds_read_b128 v[178:181], v139 offset:2048
	ds_read_b128 v[182:185], v139 offset:3072
	s_add_i32 s38, s13, 2
	s_add_u32 s12, s10, 0xc2050080
	s_addc_u32 s14, s11, -1
	s_cmp_lg_u32 s26, s13
	s_cselect_b32 s12, s12, 0
	s_cselect_b32 s13, s14, 0
	s_add_u32 s14, s4, s12
	s_addc_u32 s15, s5, s13
	s_add_u32 s12, s6, s12
	s_addc_u32 s13, s7, s13
	s_mov_b32 m0, s27
	v_lshl_add_u64 v[162:163], v[140:141], 0, s[10:11]
	ds_read_b128 v[186:189], v144
	ds_read_b128 v[190:193], v144 offset:1024
	ds_read_b128 v[194:197], v144 offset:2048
	ds_read_b128 v[198:201], v144 offset:3072
	ds_read_b128 v[202:205], v144 offset:4096
	ds_read_b128 v[206:209], v144 offset:5120
	ds_read_b128 v[210:213], v144 offset:6144
	ds_read_b128 v[214:217], v144 offset:7168
	global_load_lds_dwordx4 v[162:163], off
	v_lshl_add_u64 v[162:163], v[142:143], 0, s[10:11]
	s_mov_b32 m0, s28
	s_nop 0
	global_load_lds_dwordx4 v[162:163], off
	s_waitcnt vmcnt(8)
	s_waitcnt lgkmcnt(0)
	s_barrier
	s_setprio 1
	s_waitcnt lgkmcnt(0)
	v_mfma_f32_16x16x32_bf16 v[126:129], v[150:153], v[186:189], v[126:129]
	v_mfma_f32_16x16x32_bf16 v[122:125], v[158:161], v[186:189], v[122:125]
	v_mfma_f32_16x16x32_bf16 v[110:113], v[170:173], v[186:189], v[110:113]
	v_mfma_f32_16x16x32_bf16 v[106:109], v[178:181], v[186:189], v[106:109]
	v_mfma_f32_16x16x32_bf16 v[106:109], v[182:185], v[190:193], v[106:109]
	v_mfma_f32_16x16x32_bf16 v[110:113], v[174:177], v[190:193], v[110:113]
	v_mfma_f32_16x16x32_bf16 v[122:125], v[166:169], v[190:193], v[122:125]
	v_mfma_f32_16x16x32_bf16 v[126:129], v[154:157], v[190:193], v[126:129]
	v_mfma_f32_16x16x32_bf16 v[118:121], v[154:157], v[198:201], v[118:121]
	v_mfma_f32_16x16x32_bf16 v[114:117], v[166:169], v[198:201], v[114:117]
	v_mfma_f32_16x16x32_bf16 v[94:97], v[174:177], v[198:201], v[94:97]
	v_mfma_f32_16x16x32_bf16 v[90:93], v[182:185], v[198:201], v[90:93]
	v_mfma_f32_16x16x32_bf16 v[90:93], v[178:181], v[194:197], v[90:93]
	v_mfma_f32_16x16x32_bf16 v[94:97], v[170:173], v[194:197], v[94:97]
	v_mfma_f32_16x16x32_bf16 v[114:117], v[158:161], v[194:197], v[114:117]
	v_mfma_f32_16x16x32_bf16 v[118:121], v[150:153], v[194:197], v[118:121]
	v_mfma_f32_16x16x32_bf16 v[102:105], v[150:153], v[202:205], v[102:105]
	v_mfma_f32_16x16x32_bf16 v[98:101], v[158:161], v[202:205], v[98:101]
	v_mfma_f32_16x16x32_bf16 v[78:81], v[170:173], v[202:205], v[78:81]
	v_mfma_f32_16x16x32_bf16 v[74:77], v[178:181], v[202:205], v[74:77]
	v_mfma_f32_16x16x32_bf16 v[74:77], v[182:185], v[206:209], v[74:77]
	v_mfma_f32_16x16x32_bf16 v[78:81], v[174:177], v[206:209], v[78:81]
	v_mfma_f32_16x16x32_bf16 v[98:101], v[166:169], v[206:209], v[98:101]
	v_mfma_f32_16x16x32_bf16 v[102:105], v[154:157], v[206:209], v[102:105]
	v_mfma_f32_16x16x32_bf16 v[86:89], v[154:157], v[214:217], v[86:89]
	v_mfma_f32_16x16x32_bf16 v[82:85], v[166:169], v[214:217], v[82:85]
	v_mfma_f32_16x16x32_bf16 v[70:73], v[174:177], v[214:217], v[70:73]
	v_mfma_f32_16x16x32_bf16 v[66:69], v[182:185], v[214:217], v[66:69]
	v_mfma_f32_16x16x32_bf16 v[66:69], v[178:181], v[210:213], v[66:69]
	v_mfma_f32_16x16x32_bf16 v[70:73], v[170:173], v[210:213], v[70:73]
	v_mfma_f32_16x16x32_bf16 v[82:85], v[158:161], v[210:213], v[82:85]
	v_mfma_f32_16x16x32_bf16 v[86:89], v[150:153], v[210:213], v[86:89]
	s_setprio 0
	s_barrier
	s_mov_b32 m0, s29
	v_lshl_add_u64 v[162:163], s[12:13], 0, v[132:133]
	s_add_u32 s40, s12, 0x2b0000
	ds_read_b128 v[186:189], v144 offset:16384
	ds_read_b128 v[190:193], v144 offset:17408
	ds_read_b128 v[194:197], v144 offset:18432
	ds_read_b128 v[198:201], v144 offset:19456
	ds_read_b128 v[202:205], v144 offset:20480
	ds_read_b128 v[206:209], v144 offset:21504
	ds_read_b128 v[210:213], v144 offset:22528
	ds_read_b128 v[214:217], v144 offset:23552
	global_load_lds_dwordx4 v[162:163], off
	v_lshl_add_u64 v[218:219], s[12:13], 0, v[136:137]
	s_mov_b32 m0, s30
	s_addc_u32 s41, s13, 0
	global_load_lds_dwordx4 v[218:219], off
	v_lshl_add_u64 v[220:221], s[40:41], 0, v[132:133]
	s_mov_b32 m0, s31
	v_lshl_add_u64 v[222:223], s[14:15], 0, v[134:135]
	global_load_lds_dwordx4 v[220:221], off
	v_lshl_add_u64 v[220:221], s[40:41], 0, v[136:137]
	s_mov_b32 m0, s33
	s_nop 0
	global_load_lds_dwordx4 v[220:221], off
	v_lshl_add_u64 v[220:221], s[14:15], 0, v[130:131]
	s_mov_b32 m0, s19
	s_nop 0
	global_load_lds_dwordx4 v[220:221], off
	s_mov_b32 m0, s20
	s_nop 0
	global_load_lds_dwordx4 v[222:223], off
	s_waitcnt vmcnt(8)
	s_waitcnt lgkmcnt(0)
	s_barrier
	s_setprio 1
	s_waitcnt lgkmcnt(0)
	v_mfma_f32_16x16x32_bf16 v[62:65], v[150:153], v[186:189], v[62:65]
	v_mfma_f32_16x16x32_bf16 v[58:61], v[158:161], v[186:189], v[58:61]
	v_mfma_f32_16x16x32_bf16 v[46:49], v[170:173], v[186:189], v[46:49]
	v_mfma_f32_16x16x32_bf16 v[42:45], v[178:181], v[186:189], v[42:45]
	v_mfma_f32_16x16x32_bf16 v[42:45], v[182:185], v[190:193], v[42:45]
	v_mfma_f32_16x16x32_bf16 v[46:49], v[174:177], v[190:193], v[46:49]
	v_mfma_f32_16x16x32_bf16 v[58:61], v[166:169], v[190:193], v[58:61]
	v_mfma_f32_16x16x32_bf16 v[62:65], v[154:157], v[190:193], v[62:65]
	v_mfma_f32_16x16x32_bf16 v[54:57], v[154:157], v[198:201], v[54:57]
	v_mfma_f32_16x16x32_bf16 v[50:53], v[166:169], v[198:201], v[50:53]
	v_mfma_f32_16x16x32_bf16 v[30:33], v[174:177], v[198:201], v[30:33]
	v_mfma_f32_16x16x32_bf16 v[26:29], v[182:185], v[198:201], v[26:29]
	v_mfma_f32_16x16x32_bf16 v[26:29], v[178:181], v[194:197], v[26:29]
	v_mfma_f32_16x16x32_bf16 v[30:33], v[170:173], v[194:197], v[30:33]
	v_mfma_f32_16x16x32_bf16 v[50:53], v[158:161], v[194:197], v[50:53]
	v_mfma_f32_16x16x32_bf16 v[54:57], v[150:153], v[194:197], v[54:57]
	v_mfma_f32_16x16x32_bf16 v[38:41], v[150:153], v[202:205], v[38:41]
	v_mfma_f32_16x16x32_bf16 v[34:37], v[158:161], v[202:205], v[34:37]
	v_mfma_f32_16x16x32_bf16 v[14:17], v[170:173], v[202:205], v[14:17]
	v_mfma_f32_16x16x32_bf16 v[10:13], v[178:181], v[202:205], v[10:13]
	v_mfma_f32_16x16x32_bf16 v[10:13], v[182:185], v[206:209], v[10:13]
	v_mfma_f32_16x16x32_bf16 v[14:17], v[174:177], v[206:209], v[14:17]
	v_mfma_f32_16x16x32_bf16 v[34:37], v[166:169], v[206:209], v[34:37]
	v_mfma_f32_16x16x32_bf16 v[38:41], v[154:157], v[206:209], v[38:41]
	v_mfma_f32_16x16x32_bf16 v[22:25], v[154:157], v[214:217], v[22:25]
	v_mfma_f32_16x16x32_bf16 v[18:21], v[166:169], v[214:217], v[18:21]
	v_mfma_f32_16x16x32_bf16 v[6:9], v[174:177], v[214:217], v[6:9]
	v_mfma_f32_16x16x32_bf16 v[2:5], v[182:185], v[214:217], v[2:5]
	v_mfma_f32_16x16x32_bf16 v[2:5], v[178:181], v[210:213], v[2:5]
	v_mfma_f32_16x16x32_bf16 v[6:9], v[170:173], v[210:213], v[6:9]
	v_mfma_f32_16x16x32_bf16 v[18:21], v[158:161], v[210:213], v[18:21]
	v_mfma_f32_16x16x32_bf16 v[22:25], v[150:153], v[210:213], v[22:25]
	s_setprio 0
	s_barrier
	ds_read_b128 v[150:153], v145
	ds_read_b128 v[154:157], v145 offset:1024
	ds_read_b128 v[158:161], v145 offset:2048
	ds_read_b128 v[166:169], v145 offset:3072
	ds_read_b128 v[170:173], v146
	ds_read_b128 v[174:177], v146 offset:1024
	ds_read_b128 v[178:181], v146 offset:2048
	ds_read_b128 v[182:185], v146 offset:3072
	s_add_u32 s14, s14, 0x2b0000
	s_addc_u32 s15, s15, 0
	s_mov_b32 m0, s21
	v_lshl_add_u64 v[224:225], s[14:15], 0, v[130:131]
	ds_read_b128 v[186:189], v144 offset:32768
	ds_read_b128 v[190:193], v144 offset:33792
	ds_read_b128 v[194:197], v144 offset:34816
	ds_read_b128 v[198:201], v144 offset:35840
	ds_read_b128 v[202:205], v144 offset:36864
	ds_read_b128 v[206:209], v144 offset:37888
	ds_read_b128 v[210:213], v144 offset:38912
	ds_read_b128 v[214:217], v144 offset:39936
	global_load_lds_dwordx4 v[224:225], off
	v_lshl_add_u64 v[224:225], s[14:15], 0, v[134:135]
	s_mov_b32 m0, s22
	s_nop 0
	global_load_lds_dwordx4 v[224:225], off
	s_waitcnt vmcnt(8)
	s_waitcnt lgkmcnt(0)
	s_barrier
	s_setprio 1
	s_waitcnt lgkmcnt(0)
	v_mfma_f32_16x16x32_bf16 v[126:129], v[150:153], v[186:189], v[126:129]
	v_mfma_f32_16x16x32_bf16 v[122:125], v[158:161], v[186:189], v[122:125]
	v_mfma_f32_16x16x32_bf16 v[110:113], v[170:173], v[186:189], v[110:113]
	v_mfma_f32_16x16x32_bf16 v[106:109], v[178:181], v[186:189], v[106:109]
	v_mfma_f32_16x16x32_bf16 v[106:109], v[182:185], v[190:193], v[106:109]
	v_mfma_f32_16x16x32_bf16 v[110:113], v[174:177], v[190:193], v[110:113]
	v_mfma_f32_16x16x32_bf16 v[122:125], v[166:169], v[190:193], v[122:125]
	v_mfma_f32_16x16x32_bf16 v[126:129], v[154:157], v[190:193], v[126:129]
	v_mfma_f32_16x16x32_bf16 v[118:121], v[154:157], v[198:201], v[118:121]
	v_mfma_f32_16x16x32_bf16 v[114:117], v[166:169], v[198:201], v[114:117]
	v_mfma_f32_16x16x32_bf16 v[94:97], v[174:177], v[198:201], v[94:97]
	v_mfma_f32_16x16x32_bf16 v[90:93], v[182:185], v[198:201], v[90:93]
	v_mfma_f32_16x16x32_bf16 v[90:93], v[178:181], v[194:197], v[90:93]
	v_mfma_f32_16x16x32_bf16 v[94:97], v[170:173], v[194:197], v[94:97]
	v_mfma_f32_16x16x32_bf16 v[114:117], v[158:161], v[194:197], v[114:117]
	v_mfma_f32_16x16x32_bf16 v[118:121], v[150:153], v[194:197], v[118:121]
	v_mfma_f32_16x16x32_bf16 v[102:105], v[150:153], v[202:205], v[102:105]
	v_mfma_f32_16x16x32_bf16 v[98:101], v[158:161], v[202:205], v[98:101]
	v_mfma_f32_16x16x32_bf16 v[78:81], v[170:173], v[202:205], v[78:81]
	v_mfma_f32_16x16x32_bf16 v[74:77], v[178:181], v[202:205], v[74:77]
	v_mfma_f32_16x16x32_bf16 v[74:77], v[182:185], v[206:209], v[74:77]
	v_mfma_f32_16x16x32_bf16 v[78:81], v[174:177], v[206:209], v[78:81]
	v_mfma_f32_16x16x32_bf16 v[98:101], v[166:169], v[206:209], v[98:101]
	v_mfma_f32_16x16x32_bf16 v[102:105], v[154:157], v[206:209], v[102:105]
	v_mfma_f32_16x16x32_bf16 v[86:89], v[154:157], v[214:217], v[86:89]
	v_mfma_f32_16x16x32_bf16 v[82:85], v[166:169], v[214:217], v[82:85]
	v_mfma_f32_16x16x32_bf16 v[70:73], v[174:177], v[214:217], v[70:73]
	v_mfma_f32_16x16x32_bf16 v[66:69], v[182:185], v[214:217], v[66:69]
	v_mfma_f32_16x16x32_bf16 v[66:69], v[178:181], v[210:213], v[66:69]
	v_mfma_f32_16x16x32_bf16 v[70:73], v[170:173], v[210:213], v[70:73]
	v_mfma_f32_16x16x32_bf16 v[82:85], v[158:161], v[210:213], v[82:85]
	v_mfma_f32_16x16x32_bf16 v[86:89], v[150:153], v[210:213], v[86:89]
	s_setprio 0
	s_barrier
	s_mov_b32 m0, s34
	v_lshl_add_u64 v[162:163], v[162:163], 0, s[8:9]
	s_add_u32 s12, s12, 0x2b0080
	ds_read_b128 v[186:189], v144 offset:49152
	ds_read_b128 v[190:193], v144 offset:50176
	ds_read_b128 v[194:197], v144 offset:51200
	ds_read_b128 v[198:201], v144 offset:52224
	ds_read_b128 v[202:205], v144 offset:53248
	ds_read_b128 v[206:209], v144 offset:54272
	ds_read_b128 v[210:213], v144 offset:55296
	ds_read_b128 v[214:217], v144 offset:56320
	global_load_lds_dwordx4 v[162:163], off
	v_lshl_add_u64 v[162:163], v[218:219], 0, s[8:9]
	s_mov_b32 m0, s35
	s_addc_u32 s13, s13, 0
	global_load_lds_dwordx4 v[162:163], off
	v_lshl_add_u64 v[162:163], s[12:13], 0, v[132:133]
	s_mov_b32 m0, s36
	s_nop 0
	global_load_lds_dwordx4 v[162:163], off
	v_lshl_add_u64 v[162:163], s[12:13], 0, v[136:137]
	s_mov_b32 m0, s37
	s_nop 0
	global_load_lds_dwordx4 v[162:163], off
	v_lshl_add_u64 v[162:163], v[220:221], 0, s[8:9]
	s_mov_b32 m0, s24
	s_nop 0
	global_load_lds_dwordx4 v[162:163], off
	v_lshl_add_u64 v[162:163], v[222:223], 0, s[8:9]
	s_mov_b32 m0, s25
	s_nop 0
	global_load_lds_dwordx4 v[162:163], off
	s_waitcnt vmcnt(8)
	s_waitcnt lgkmcnt(0)
	s_barrier
	s_setprio 1
	s_waitcnt lgkmcnt(0)
	v_mfma_f32_16x16x32_bf16 v[62:65], v[150:153], v[186:189], v[62:65]
	v_mfma_f32_16x16x32_bf16 v[58:61], v[158:161], v[186:189], v[58:61]
	v_mfma_f32_16x16x32_bf16 v[46:49], v[170:173], v[186:189], v[46:49]
	v_mfma_f32_16x16x32_bf16 v[42:45], v[178:181], v[186:189], v[42:45]
	v_mfma_f32_16x16x32_bf16 v[42:45], v[182:185], v[190:193], v[42:45]
	v_mfma_f32_16x16x32_bf16 v[46:49], v[174:177], v[190:193], v[46:49]
	v_mfma_f32_16x16x32_bf16 v[58:61], v[166:169], v[190:193], v[58:61]
	v_mfma_f32_16x16x32_bf16 v[62:65], v[154:157], v[190:193], v[62:65]
	v_mfma_f32_16x16x32_bf16 v[54:57], v[154:157], v[198:201], v[54:57]
	v_mfma_f32_16x16x32_bf16 v[50:53], v[166:169], v[198:201], v[50:53]
	v_mfma_f32_16x16x32_bf16 v[30:33], v[174:177], v[198:201], v[30:33]
	v_mfma_f32_16x16x32_bf16 v[26:29], v[182:185], v[198:201], v[26:29]
	v_mfma_f32_16x16x32_bf16 v[26:29], v[178:181], v[194:197], v[26:29]
	v_mfma_f32_16x16x32_bf16 v[30:33], v[170:173], v[194:197], v[30:33]
	v_mfma_f32_16x16x32_bf16 v[50:53], v[158:161], v[194:197], v[50:53]
	v_mfma_f32_16x16x32_bf16 v[54:57], v[150:153], v[194:197], v[54:57]
	v_mfma_f32_16x16x32_bf16 v[38:41], v[150:153], v[202:205], v[38:41]
	v_mfma_f32_16x16x32_bf16 v[34:37], v[158:161], v[202:205], v[34:37]
	v_mfma_f32_16x16x32_bf16 v[14:17], v[170:173], v[202:205], v[14:17]
	v_mfma_f32_16x16x32_bf16 v[10:13], v[178:181], v[202:205], v[10:13]
	v_mfma_f32_16x16x32_bf16 v[10:13], v[182:185], v[206:209], v[10:13]
	v_mfma_f32_16x16x32_bf16 v[14:17], v[174:177], v[206:209], v[14:17]
	v_mfma_f32_16x16x32_bf16 v[34:37], v[166:169], v[206:209], v[34:37]
	v_mfma_f32_16x16x32_bf16 v[38:41], v[154:157], v[206:209], v[38:41]
	v_mfma_f32_16x16x32_bf16 v[22:25], v[154:157], v[214:217], v[22:25]
	v_mfma_f32_16x16x32_bf16 v[18:21], v[166:169], v[214:217], v[18:21]
	v_mfma_f32_16x16x32_bf16 v[6:9], v[174:177], v[214:217], v[6:9]
	v_mfma_f32_16x16x32_bf16 v[2:5], v[182:185], v[214:217], v[2:5]
	v_mfma_f32_16x16x32_bf16 v[2:5], v[178:181], v[210:213], v[2:5]
	v_mfma_f32_16x16x32_bf16 v[6:9], v[170:173], v[210:213], v[6:9]
	v_mfma_f32_16x16x32_bf16 v[18:21], v[158:161], v[210:213], v[18:21]
	v_mfma_f32_16x16x32_bf16 v[22:25], v[150:153], v[210:213], v[22:25]
	s_setprio 0
	s_barrier
	s_add_u32 s10, s10, 0x100
	s_addc_u32 s11, s11, 0
	s_cmp_ge_u32 s38, s17
	s_mov_b32 s13, s38
	s_cbranch_scc0 .LBB0_2632
	s_lshl_b32 s4, s16, 21
	v_readlane_b32 s2, v249, 29
	v_lshl_or_b32 v1, s18, 8, v148
	v_mov_b32_e32 v139, 0
	s_add_u32 s4, s2, s4
	v_readlane_b32 s2, v249, 31
	v_or_b32_e32 v130, s23, v1
	v_cvt_pk_bf16_f32 v70, v70, v71
	v_cvt_pk_bf16_f32 v71, v72, v73
	v_cvt_pk_bf16_f32 v72, v66, v67
	v_add_u32_e32 v66, 0x80, v138
	v_mov_b32_e32 v67, v139
	s_addc_u32 s5, s2, 0
	v_ashrrev_i32_e32 v131, 31, v130
	v_lshlrev_b64 v[132:133], 13, v[138:139]
	v_cvt_pk_bf16_f32 v110, v110, v111
	v_cvt_pk_bf16_f32 v111, v112, v113
	v_cvt_pk_bf16_f32 v112, v106, v107
	v_or_b32_e32 v106, 16, v138
	v_mov_b32_e32 v107, v139
	v_lshlrev_b64 v[66:67], 13, v[66:67]
	v_cvt_pk_bf16_f32 v46, v46, v47
	v_cvt_pk_bf16_f32 v47, v48, v49
	v_cvt_pk_bf16_f32 v48, v42, v43
	v_add_u32_e32 v42, 0x90, v138
	v_mov_b32_e32 v43, v139
	v_lshl_add_u64 v[132:133], s[4:5], 0, v[132:133]
	v_lshlrev_b64 v[130:131], 1, v[130:131]
	v_lshlrev_b64 v[106:107], 13, v[106:107]
	v_cvt_pk_bf16_f32 v94, v94, v95
	v_cvt_pk_bf16_f32 v95, v96, v97
	v_cvt_pk_bf16_f32 v96, v90, v91
	v_or_b32_e32 v90, 32, v138
	v_mov_b32_e32 v91, v139
	v_lshl_add_u64 v[66:67], s[4:5], 0, v[66:67]
	v_lshlrev_b64 v[42:43], 13, v[42:43]
	v_cvt_pk_bf16_f32 v30, v30, v31
	v_cvt_pk_bf16_f32 v31, v32, v33
	v_cvt_pk_bf16_f32 v32, v26, v27
	v_add_u32_e32 v26, 0xa0, v138
	v_mov_b32_e32 v27, v139
	v_lshl_add_u64 v[132:133], v[132:133], 0, v[130:131]
	v_cvt_pk_bf16_f32 v113, v108, v109
	v_lshl_add_u64 v[106:107], s[4:5], 0, v[106:107]
	v_lshlrev_b64 v[90:91], 13, v[90:91]
	v_cvt_pk_bf16_f32 v78, v78, v79
	v_cvt_pk_bf16_f32 v79, v80, v81
	v_cvt_pk_bf16_f32 v80, v74, v75
	v_or_b32_e32 v74, 48, v138
	v_mov_b32_e32 v75, v139
	v_lshl_add_u64 v[66:67], v[66:67], 0, v[130:131]
	v_cvt_pk_bf16_f32 v49, v44, v45
	v_lshl_add_u64 v[42:43], s[4:5], 0, v[42:43]
	v_lshlrev_b64 v[26:27], 13, v[26:27]
	v_add_u32_e32 v138, 0xb0, v138
	global_store_dwordx4 v[132:133], v[110:113], off offset:256
	v_cvt_pk_bf16_f32 v97, v92, v93
	v_lshl_add_u64 v[90:91], s[4:5], 0, v[90:91]
	v_lshl_add_u64 v[110:111], v[106:107], 0, v[130:131]
	v_lshlrev_b64 v[74:75], 13, v[74:75]
	global_store_dwordx4 v[66:67], v[46:49], off offset:256
	v_cvt_pk_bf16_f32 v33, v28, v29
	v_lshl_add_u64 v[26:27], s[4:5], 0, v[26:27]
	v_lshl_add_u64 v[46:47], v[42:43], 0, v[130:131]
	v_cvt_pk_bf16_f32 v14, v14, v15
	v_cvt_pk_bf16_f32 v15, v16, v17
	v_cvt_pk_bf16_f32 v16, v10, v11
	v_lshlrev_b64 v[10:11], 13, v[138:139]
	global_store_dwordx4 v[110:111], v[94:97], off offset:256
	v_cvt_pk_bf16_f32 v81, v76, v77
	v_lshl_add_u64 v[74:75], s[4:5], 0, v[74:75]
	v_lshl_add_u64 v[94:95], v[90:91], 0, v[130:131]
	global_store_dwordx4 v[46:47], v[30:33], off offset:256
	v_cvt_pk_bf16_f32 v17, v12, v13
	v_lshl_add_u64 v[10:11], s[4:5], 0, v[10:11]
	v_lshl_add_u64 v[30:31], v[26:27], 0, v[130:131]
	v_cvt_pk_bf16_f32 v126, v126, v127
	v_cvt_pk_bf16_f32 v127, v128, v129
	v_cvt_pk_bf16_f32 v128, v122, v123
	v_cvt_pk_bf16_f32 v129, v124, v125
	v_cvt_pk_bf16_f32 v106, v118, v119
	v_cvt_pk_bf16_f32 v107, v120, v121
	v_cvt_pk_bf16_f32 v108, v114, v115
	v_cvt_pk_bf16_f32 v109, v116, v117
	v_cvt_pk_bf16_f32 v90, v102, v103
	v_cvt_pk_bf16_f32 v91, v104, v105
	v_cvt_pk_bf16_f32 v92, v98, v99
	v_cvt_pk_bf16_f32 v93, v100, v101
	global_store_dwordx4 v[94:95], v[78:81], off offset:256
	v_cvt_pk_bf16_f32 v76, v82, v83
	v_cvt_pk_bf16_f32 v77, v84, v85
	v_lshl_add_u64 v[78:79], v[74:75], 0, v[130:131]
	v_cvt_pk_bf16_f32 v74, v86, v87
	v_cvt_pk_bf16_f32 v75, v88, v89
	v_cvt_pk_bf16_f32 v73, v68, v69
	v_cvt_pk_bf16_f32 v62, v62, v63
	v_cvt_pk_bf16_f32 v63, v64, v65
	v_cvt_pk_bf16_f32 v64, v58, v59
	v_cvt_pk_bf16_f32 v65, v60, v61
	v_cvt_pk_bf16_f32 v42, v54, v55
	v_cvt_pk_bf16_f32 v43, v56, v57
	v_cvt_pk_bf16_f32 v44, v50, v51
	v_cvt_pk_bf16_f32 v45, v52, v53
	v_cvt_pk_bf16_f32 v26, v38, v39
	v_cvt_pk_bf16_f32 v27, v40, v41
	v_cvt_pk_bf16_f32 v28, v34, v35
	v_cvt_pk_bf16_f32 v29, v36, v37
	global_store_dwordx4 v[30:31], v[14:17], off offset:256
	v_cvt_pk_bf16_f32 v12, v18, v19
	v_cvt_pk_bf16_f32 v13, v20, v21
	v_lshl_add_u64 v[14:15], v[10:11], 0, v[130:131]
	v_cvt_pk_bf16_f32 v10, v22, v23
	v_cvt_pk_bf16_f32 v11, v24, v25
	v_cvt_pk_bf16_f32 v6, v6, v7
	v_cvt_pk_bf16_f32 v7, v8, v9
	v_cvt_pk_bf16_f32 v8, v2, v3
	v_cvt_pk_bf16_f32 v9, v4, v5
	global_store_dwordx4 v[132:133], v[126:129], off
	global_store_dwordx4 v[110:111], v[106:109], off
	global_store_dwordx4 v[94:95], v[90:93], off
	global_store_dwordx4 v[78:79], v[74:77], off
	global_store_dwordx4 v[78:79], v[70:73], off offset:256
	global_store_dwordx4 v[66:67], v[62:65], off
	global_store_dwordx4 v[46:47], v[42:45], off
	global_store_dwordx4 v[30:31], v[26:29], off
	global_store_dwordx4 v[14:15], v[10:13], off
	global_store_dwordx4 v[14:15], v[6:9], off offset:256
	s_waitcnt vmcnt(0)
	s_cmpk_lt_u32 s3, 0x100
	s_cbranch_scc0 .LBB0_2635
	s_barrier
